# GEMM k-loops: B staging registers reloaded right after their ds_write (2 k-steps ahead instead of 1.5), single vmcnt(6) wait per k-step
# baseline (speedup 1.0000x reference)
.LBB0_215:
	s_mul_hi_i32 s0, s8, 0x2aaaaaab
	s_lshr_b32 s1, s0, 31
	s_ashr_i32 s0, s0, 5
	s_add_i32 s0, s0, s1
	s_lshl_b32 s1, s0, 3
	s_sub_i32 s2, 17, s1
	s_min_u32 s2, s2, 8
	v_cvt_f32_ubyte0_e32 v0, s2
	v_rcp_iflag_f32_e32 v0, v0
	s_sub_i32 s5, 0, s2
	s_mulk_i32 s0, 0xff40
	s_add_i32 s3, s0, s8
	v_mul_f32_e32 v0, 0x4f7ffffe, v0
	v_cvt_u32_f32_e32 v0, v0
	s_abs_i32 s4, s3
	s_ashr_i32 s0, s3, 31
	v_mov_b32_e32 v181, v179
	v_readfirstlane_b32 s6, v0
	s_mul_i32 s5, s5, s6
	s_mul_hi_u32 s5, s6, s5
	s_add_i32 s6, s6, s5
	s_mul_hi_u32 s5, s4, s6
	s_mul_i32 s6, s5, s2
	s_sub_i32 s4, s4, s6
	s_add_i32 s6, s5, 1
	s_sub_i32 s7, s4, s2
	s_cmp_ge_u32 s4, s2
	s_cselect_b32 s5, s6, s5
	s_cselect_b32 s4, s7, s4
	s_add_i32 s6, s5, 1
	s_cmp_ge_u32 s4, s2
	s_cselect_b32 s4, s6, s5
	s_xor_b32 s4, s4, s0
	s_sub_i32 s0, s4, s0
	s_mul_i32 s2, s2, s0
	s_sub_i32 s2, s3, s2
	s_add_i32 s1, s1, s11
	s_add_i32 s2, s1, s2
	v_ashrrev_i32_e32 v233, 6, v181
	v_lshlrev_b32_e32 v0, 1, v233
	v_lshl_add_u32 v0, s2, 3, v0
	v_ashrrev_i32_e32 v1, 31, v0
	v_bfe_u32 v183, v181, 5, 1
	v_lshlrev_b64 v[0:1], 16, v[0:1]
	v_and_b32_e32 v231, 31, v181
	v_lshl_add_u64 v[0:1], s[64:65], 0, v[0:1]
	v_lshlrev_b32_e32 v176, 9, v183
	s_ashr_i32 s1, s0, 31
	v_lshl_add_u64 v[0:1], v[0:1], 0, v[176:177]
	v_lshlrev_b32_e32 v176, 4, v231
	v_ashrrev_i32_e32 v12, 2, v181
	s_lshl_b64 s[4:5], s[0:1], 18
	v_lshl_add_u64 v[184:185], v[0:1], 0, v[176:177]
	s_add_u32 s4, s9, s4
	v_lshlrev_b32_e32 v0, 5, v12
	s_addc_u32 s5, s10, s5
	v_ashrrev_i32_e32 v1, 31, v0
	v_lshlrev_b32_e32 v2, 4, v181
	v_lshl_add_u64 v[0:1], v[0:1], 1, s[4:5]
	v_and_b32_e32 v176, 48, v2
	v_lshl_add_u64 v[186:187], v[0:1], 0, v[176:177]
	s_movk_i32 s1, 0x2000
	v_add_co_u32_e32 v8, vcc, s1, v186
	v_mul_u32_u24_e32 v10, 40, v231
	s_nop 0
	v_addc_co_u32_e32 v9, vcc, 0, v187, vcc
	v_lshlrev_b32_e32 v11, 4, v183
	v_lshl_add_u32 v235, v10, 1, v11
	v_add_co_u32_e32 v10, vcc, s41, v184
	s_movk_i32 s3, 0x50
	s_nop 0
	v_addc_co_u32_e32 v11, vcc, 0, v185, vcc
	v_and_b32_e32 v232, 63, v181
	v_lshlrev_b32_e32 v234, 3, v181
	v_mov_b32_e32 v176, 0x800
	v_lshl_add_u64 v[188:189], v[186:187], 0, v[176:177]
	v_bfe_u32 v197, v181, 4, 1
	v_lshlrev_b32_e32 v176, 9, v183
	v_lshl_add_u32 v176, v197, 8, v176
	v_lshl_add_u64 v[184:185], v[184:185], 0, v[176:177]
	v_mov_b32_e32 v176, s41
	v_lshl_add_u64 v[186:187], v[184:185], 0, v[176:177]
	v_lshrrev_b32_e32 v235, 2, v181
	v_bfe_u32 v197, v181, 4, 2
	v_lshlrev_b32_e32 v197, 1, v197
	v_mov_b32_e32 v176, 0x78
	v_lshrrev_b32_e32 v197, v197, v176
	v_and_b32_e32 v197, 3, v197
	v_and_b32_e32 v196, 3, v181
	v_xor_b32_e32 v197, v197, v196
	v_lshlrev_b32_e32 v197, 4, v197
	v_lshl_add_u32 v235, v235, 6, v197
	v_bfe_u32 v197, v181, 2, 2
	v_lshlrev_b32_e32 v197, 1, v197
	v_lshrrev_b32_e32 v197, v197, v176
	v_and_b32_e32 v197, 3, v197
	v_bfe_u32 v196, v181, 4, 2
	v_xor_b32_e32 v197, v197, v196
	v_lshlrev_b32_e32 v197, 4, v197
	v_and_b32_e32 v196, 15, v181
	v_lshl_add_u32 v196, v196, 6, v197
	s_mov_b32 s96, 0
	v_lshl_add_u64 v[166:167], v[188:189], 0, s[96:97]
	global_load_dwordx4 v[160:163], v[166:167], off offset:-2048
	global_load_dwordx4 v[164:167], v[166:167], off offset:2048
	s_movk_i32 s96, 0x2000
	v_lshl_add_u64 v[174:175], v[188:189], 0, s[96:97]
	global_load_dwordx4 v[168:171], v[174:175], off offset:-2048
	global_load_dwordx4 v[172:175], v[174:175], off offset:2048
	s_mov_b32 s96, 0
	v_lshl_add_u64 v[198:199], v[184:185], 0, s[96:97]
	v_lshl_add_u64 v[200:201], v[186:187], 0, s[96:97]
	global_load_dwordx4 v[128:131], v[198:199], off
	global_load_dwordx4 v[132:135], v[198:199], off offset:256
	global_load_dwordx4 v[136:139], v[200:201], off
	global_load_dwordx4 v[140:143], v[200:201], off offset:256
	s_movk_i32 s96, 0x800
	v_lshl_add_u64 v[198:199], v[184:185], 0, s[96:97]
	v_lshl_add_u64 v[200:201], v[186:187], 0, s[96:97]
	global_load_dwordx4 v[144:147], v[198:199], off
	global_load_dwordx4 v[148:151], v[198:199], off offset:256
	global_load_dwordx4 v[152:155], v[200:201], off
	global_load_dwordx4 v[156:159], v[200:201], off offset:256
	v_mov_b32_e32 v0, 0
	v_mov_b32_e32 v1, 0
	v_mov_b32_e32 v2, 0
	v_mov_b32_e32 v3, 0
	v_mov_b32_e32 v4, 0
	v_mov_b32_e32 v5, 0
	v_mov_b32_e32 v6, 0
	v_mov_b32_e32 v7, 0
	v_mov_b32_e32 v8, 0
	v_mov_b32_e32 v9, 0
	v_mov_b32_e32 v10, 0
	v_mov_b32_e32 v11, 0
	v_mov_b32_e32 v12, 0
	v_mov_b32_e32 v13, 0
	v_mov_b32_e32 v14, 0
	v_mov_b32_e32 v15, 0
	v_mov_b32_e32 v16, 0
	v_mov_b32_e32 v17, 0
	v_mov_b32_e32 v18, 0
	v_mov_b32_e32 v19, 0
	v_mov_b32_e32 v20, 0
	v_mov_b32_e32 v21, 0
	v_mov_b32_e32 v22, 0
	v_mov_b32_e32 v23, 0
	v_mov_b32_e32 v24, 0
	v_mov_b32_e32 v25, 0
	v_mov_b32_e32 v26, 0
	v_mov_b32_e32 v27, 0
	v_mov_b32_e32 v28, 0
	v_mov_b32_e32 v29, 0
	v_mov_b32_e32 v30, 0
	v_mov_b32_e32 v31, 0
	v_mov_b32_e32 v32, 0
	v_mov_b32_e32 v33, 0
	v_mov_b32_e32 v34, 0
	v_mov_b32_e32 v35, 0
	v_mov_b32_e32 v36, 0
	v_mov_b32_e32 v37, 0
	v_mov_b32_e32 v38, 0
	v_mov_b32_e32 v39, 0
	v_mov_b32_e32 v40, 0
	v_mov_b32_e32 v41, 0
	v_mov_b32_e32 v42, 0
	v_mov_b32_e32 v43, 0
	v_mov_b32_e32 v44, 0
	v_mov_b32_e32 v45, 0
	v_mov_b32_e32 v46, 0
	v_mov_b32_e32 v47, 0
	v_mov_b32_e32 v48, 0
	v_mov_b32_e32 v49, 0
	v_mov_b32_e32 v50, 0
	v_mov_b32_e32 v51, 0
	v_mov_b32_e32 v52, 0
	v_mov_b32_e32 v53, 0
	v_mov_b32_e32 v54, 0
	v_mov_b32_e32 v55, 0
	v_mov_b32_e32 v56, 0
	v_mov_b32_e32 v57, 0
	v_mov_b32_e32 v58, 0
	v_mov_b32_e32 v59, 0
	v_mov_b32_e32 v60, 0
	v_mov_b32_e32 v61, 0
	v_mov_b32_e32 v62, 0
	v_mov_b32_e32 v63, 0
	v_mov_b32_e32 v64, 0
	v_mov_b32_e32 v65, 0
	v_mov_b32_e32 v66, 0
	v_mov_b32_e32 v67, 0
	v_mov_b32_e32 v68, 0
	v_mov_b32_e32 v69, 0
	v_mov_b32_e32 v70, 0
	v_mov_b32_e32 v71, 0
	v_mov_b32_e32 v72, 0
	v_mov_b32_e32 v73, 0
	v_mov_b32_e32 v74, 0
	v_mov_b32_e32 v75, 0
	v_mov_b32_e32 v76, 0
	v_mov_b32_e32 v77, 0
	v_mov_b32_e32 v78, 0
	v_mov_b32_e32 v79, 0
	v_mov_b32_e32 v80, 0
	v_mov_b32_e32 v81, 0
	v_mov_b32_e32 v82, 0
	v_mov_b32_e32 v83, 0
	v_mov_b32_e32 v84, 0
	v_mov_b32_e32 v85, 0
	v_mov_b32_e32 v86, 0
	v_mov_b32_e32 v87, 0
	v_mov_b32_e32 v88, 0
	v_mov_b32_e32 v89, 0
	v_mov_b32_e32 v90, 0
	v_mov_b32_e32 v91, 0
	v_mov_b32_e32 v92, 0
	v_mov_b32_e32 v93, 0
	v_mov_b32_e32 v94, 0
	v_mov_b32_e32 v95, 0
	v_mov_b32_e32 v96, 0
	v_mov_b32_e32 v97, 0
	v_mov_b32_e32 v98, 0
	v_mov_b32_e32 v99, 0
	v_mov_b32_e32 v100, 0
	v_mov_b32_e32 v101, 0
	v_mov_b32_e32 v102, 0
	v_mov_b32_e32 v103, 0
	v_mov_b32_e32 v104, 0
	v_mov_b32_e32 v105, 0
	v_mov_b32_e32 v106, 0
	v_mov_b32_e32 v107, 0
	v_mov_b32_e32 v108, 0
	v_mov_b32_e32 v109, 0
	v_mov_b32_e32 v110, 0
	v_mov_b32_e32 v111, 0
	v_mov_b32_e32 v112, 0
	v_mov_b32_e32 v113, 0
	v_mov_b32_e32 v114, 0
	v_mov_b32_e32 v115, 0
	v_mov_b32_e32 v116, 0
	v_mov_b32_e32 v117, 0
	v_mov_b32_e32 v118, 0
	v_mov_b32_e32 v119, 0
	v_mov_b32_e32 v120, 0
	v_mov_b32_e32 v121, 0
	v_mov_b32_e32 v122, 0
	v_mov_b32_e32 v123, 0
	v_mov_b32_e32 v124, 0
	v_mov_b32_e32 v125, 0
	v_mov_b32_e32 v126, 0
	v_mov_b32_e32 v127, 0
	s_mov_b32 s1, 0
	s_waitcnt vmcnt(10)
	ds_write_b128 v235, v[160:163]
	ds_write_b128 v235, v[164:167] offset:4096
	s_waitcnt lgkmcnt(0)
	s_movk_i32 s96, 0x4000
	v_lshl_add_u64 v[166:167], v[188:189], 0, s[96:97]
	global_load_dwordx4 v[160:163], v[166:167], off offset:-2048
	global_load_dwordx4 v[164:167], v[166:167], off offset:2048
	s_barrier
.Lg16_proj_k:
	ds_read_b128 v[236:239], v196 offset:0
	ds_read_b128 v[240:243], v196 offset:1024
	ds_read_b128 v[244:247], v196 offset:2048
	ds_read_b128 v[248:251], v196 offset:3072
	s_add_i32 s3, s1, 2
	s_min_u32 s4, s3, 30
	s_lshl_b32 s96, s4, 11
	v_lshl_add_u64 v[198:199], v[184:185], 0, s[96:97]
	v_lshl_add_u64 v[200:201], v[186:187], 0, s[96:97]
	s_waitcnt vmcnt(6) lgkmcnt(3)
	v_mfma_f32_16x16x32_bf16 v[16:19], v[128:131], v[236:239], v[16:19]
	v_mfma_f32_16x16x32_bf16 v[24:27], v[132:135], v[236:239], v[24:27]
	v_mfma_f32_16x16x32_bf16 v[0:3], v[136:139], v[236:239], v[0:3]
	v_mfma_f32_16x16x32_bf16 v[8:11], v[140:143], v[236:239], v[8:11]
	ds_read_b128 v[236:239], v196 offset:4096
	s_waitcnt lgkmcnt(3)
	v_mfma_f32_16x16x32_bf16 v[20:23], v[128:131], v[240:243], v[20:23]
	v_mfma_f32_16x16x32_bf16 v[28:31], v[132:135], v[240:243], v[28:31]
	v_mfma_f32_16x16x32_bf16 v[4:7], v[136:139], v[240:243], v[4:7]
	v_mfma_f32_16x16x32_bf16 v[12:15], v[140:143], v[240:243], v[12:15]
	ds_read_b128 v[240:243], v196 offset:5120
	s_waitcnt lgkmcnt(3)
	v_mfma_f32_16x16x32_bf16 v[112:115], v[128:131], v[244:247], v[112:115]
	v_mfma_f32_16x16x32_bf16 v[120:123], v[132:135], v[244:247], v[120:123]
	v_mfma_f32_16x16x32_bf16 v[96:99], v[136:139], v[244:247], v[96:99]
	v_mfma_f32_16x16x32_bf16 v[104:107], v[140:143], v[244:247], v[104:107]
	ds_read_b128 v[244:247], v196 offset:6144
	s_waitcnt lgkmcnt(3)
	v_mfma_f32_16x16x32_bf16 v[116:119], v[128:131], v[248:251], v[116:119]
	v_mfma_f32_16x16x32_bf16 v[124:127], v[132:135], v[248:251], v[124:127]
	v_mfma_f32_16x16x32_bf16 v[100:103], v[136:139], v[248:251], v[100:103]
	v_mfma_f32_16x16x32_bf16 v[108:111], v[140:143], v[248:251], v[108:111]
	ds_read_b128 v[248:251], v196 offset:7168
	ds_write_b128 v235, v[168:171] offset:8192
	ds_write_b128 v235, v[172:175] offset:12288
	s_add_i32 s3, s1, 3
	s_min_u32 s4, s3, 31
	s_lshl_b32 s96, s4, 13
	v_lshl_add_u64 v[174:175], v[188:189], 0, s[96:97]
	global_load_dwordx4 v[168:171], v[174:175], off offset:-2048
	global_load_dwordx4 v[172:175], v[174:175], off offset:2048
	s_waitcnt lgkmcnt(5)
	v_mfma_f32_16x16x32_bf16 v[80:83], v[128:131], v[236:239], v[80:83]
	v_mfma_f32_16x16x32_bf16 v[88:91], v[132:135], v[236:239], v[88:91]
	v_mfma_f32_16x16x32_bf16 v[48:51], v[136:139], v[236:239], v[48:51]
	v_mfma_f32_16x16x32_bf16 v[56:59], v[140:143], v[236:239], v[56:59]
	s_waitcnt lgkmcnt(4)
	v_mfma_f32_16x16x32_bf16 v[84:87], v[128:131], v[240:243], v[84:87]
	v_mfma_f32_16x16x32_bf16 v[92:95], v[132:135], v[240:243], v[92:95]
	v_mfma_f32_16x16x32_bf16 v[52:55], v[136:139], v[240:243], v[52:55]
	v_mfma_f32_16x16x32_bf16 v[60:63], v[140:143], v[240:243], v[60:63]
	s_waitcnt lgkmcnt(3)
	v_mfma_f32_16x16x32_bf16 v[64:67], v[128:131], v[244:247], v[64:67]
	v_mfma_f32_16x16x32_bf16 v[72:75], v[132:135], v[244:247], v[72:75]
	v_mfma_f32_16x16x32_bf16 v[32:35], v[136:139], v[244:247], v[32:35]
	v_mfma_f32_16x16x32_bf16 v[40:43], v[140:143], v[244:247], v[40:43]
	s_waitcnt lgkmcnt(2)
	v_mfma_f32_16x16x32_bf16 v[68:71], v[128:131], v[248:251], v[68:71]
	v_mfma_f32_16x16x32_bf16 v[76:79], v[132:135], v[248:251], v[76:79]
	v_mfma_f32_16x16x32_bf16 v[36:39], v[136:139], v[248:251], v[36:39]
	v_mfma_f32_16x16x32_bf16 v[44:47], v[140:143], v[248:251], v[44:47]
	global_load_dwordx4 v[128:131], v[198:199], off
	global_load_dwordx4 v[132:135], v[198:199], off offset:256
	global_load_dwordx4 v[136:139], v[200:201], off
	global_load_dwordx4 v[140:143], v[200:201], off offset:256
	s_waitcnt lgkmcnt(0)
	s_barrier
	ds_read_b128 v[236:239], v196 offset:8192
	ds_read_b128 v[240:243], v196 offset:9216
	ds_read_b128 v[244:247], v196 offset:10240
	ds_read_b128 v[248:251], v196 offset:11264
	s_add_i32 s3, s1, 3
	s_min_u32 s4, s3, 31
	s_lshl_b32 s96, s4, 11
	v_lshl_add_u64 v[198:199], v[184:185], 0, s[96:97]
	v_lshl_add_u64 v[200:201], v[186:187], 0, s[96:97]
	s_waitcnt vmcnt(6) lgkmcnt(3)
	v_mfma_f32_16x16x32_bf16 v[16:19], v[144:147], v[236:239], v[16:19]
	v_mfma_f32_16x16x32_bf16 v[24:27], v[148:151], v[236:239], v[24:27]
	v_mfma_f32_16x16x32_bf16 v[0:3], v[152:155], v[236:239], v[0:3]
	v_mfma_f32_16x16x32_bf16 v[8:11], v[156:159], v[236:239], v[8:11]
	ds_read_b128 v[236:239], v196 offset:12288
	s_waitcnt lgkmcnt(3)
	v_mfma_f32_16x16x32_bf16 v[20:23], v[144:147], v[240:243], v[20:23]
	v_mfma_f32_16x16x32_bf16 v[28:31], v[148:151], v[240:243], v[28:31]
	v_mfma_f32_16x16x32_bf16 v[4:7], v[152:155], v[240:243], v[4:7]
	v_mfma_f32_16x16x32_bf16 v[12:15], v[156:159], v[240:243], v[12:15]
	ds_read_b128 v[240:243], v196 offset:13312
	s_waitcnt lgkmcnt(3)
	v_mfma_f32_16x16x32_bf16 v[112:115], v[144:147], v[244:247], v[112:115]
	v_mfma_f32_16x16x32_bf16 v[120:123], v[148:151], v[244:247], v[120:123]
	v_mfma_f32_16x16x32_bf16 v[96:99], v[152:155], v[244:247], v[96:99]
	v_mfma_f32_16x16x32_bf16 v[104:107], v[156:159], v[244:247], v[104:107]
	ds_read_b128 v[244:247], v196 offset:14336
	s_waitcnt lgkmcnt(3)
	v_mfma_f32_16x16x32_bf16 v[116:119], v[144:147], v[248:251], v[116:119]
	v_mfma_f32_16x16x32_bf16 v[124:127], v[148:151], v[248:251], v[124:127]
	v_mfma_f32_16x16x32_bf16 v[100:103], v[152:155], v[248:251], v[100:103]
	v_mfma_f32_16x16x32_bf16 v[108:111], v[156:159], v[248:251], v[108:111]
	ds_read_b128 v[248:251], v196 offset:15360
	ds_write_b128 v235, v[160:163] offset:0
	ds_write_b128 v235, v[164:167] offset:4096
	s_add_i32 s3, s1, 4
	s_min_u32 s4, s3, 30
	s_lshl_b32 s96, s4, 13
	v_lshl_add_u64 v[166:167], v[188:189], 0, s[96:97]
	global_load_dwordx4 v[160:163], v[166:167], off offset:-2048
	global_load_dwordx4 v[164:167], v[166:167], off offset:2048
	s_waitcnt lgkmcnt(5)
	v_mfma_f32_16x16x32_bf16 v[80:83], v[144:147], v[236:239], v[80:83]
	v_mfma_f32_16x16x32_bf16 v[88:91], v[148:151], v[236:239], v[88:91]
	v_mfma_f32_16x16x32_bf16 v[48:51], v[152:155], v[236:239], v[48:51]
	v_mfma_f32_16x16x32_bf16 v[56:59], v[156:159], v[236:239], v[56:59]
	s_waitcnt lgkmcnt(4)
	v_mfma_f32_16x16x32_bf16 v[84:87], v[144:147], v[240:243], v[84:87]
	v_mfma_f32_16x16x32_bf16 v[92:95], v[148:151], v[240:243], v[92:95]
	v_mfma_f32_16x16x32_bf16 v[52:55], v[152:155], v[240:243], v[52:55]
	v_mfma_f32_16x16x32_bf16 v[60:63], v[156:159], v[240:243], v[60:63]
	s_waitcnt lgkmcnt(3)
	v_mfma_f32_16x16x32_bf16 v[64:67], v[144:147], v[244:247], v[64:67]
	v_mfma_f32_16x16x32_bf16 v[72:75], v[148:151], v[244:247], v[72:75]
	v_mfma_f32_16x16x32_bf16 v[32:35], v[152:155], v[244:247], v[32:35]
	v_mfma_f32_16x16x32_bf16 v[40:43], v[156:159], v[244:247], v[40:43]
	s_waitcnt lgkmcnt(2)
	v_mfma_f32_16x16x32_bf16 v[68:71], v[144:147], v[248:251], v[68:71]
	v_mfma_f32_16x16x32_bf16 v[76:79], v[148:151], v[248:251], v[76:79]
	v_mfma_f32_16x16x32_bf16 v[36:39], v[152:155], v[248:251], v[36:39]
	v_mfma_f32_16x16x32_bf16 v[44:47], v[156:159], v[248:251], v[44:47]
	global_load_dwordx4 v[144:147], v[198:199], off
	global_load_dwordx4 v[148:151], v[198:199], off offset:256
	global_load_dwordx4 v[152:155], v[200:201], off
	global_load_dwordx4 v[156:159], v[200:201], off offset:256
	s_add_i32 s1, s1, 2
	s_cmp_lt_u32 s1, 32
	s_waitcnt lgkmcnt(0)
	s_barrier
	s_cbranch_scc1 .Lg16_proj_k
	s_nop 7
	v_permlane16_swap_b32_e32 v16, v20
	v_permlane16_swap_b32_e32 v17, v21
	v_permlane16_swap_b32_e32 v18, v22
	v_permlane16_swap_b32_e32 v19, v23
	v_permlane16_swap_b32_e32 v24, v28
	v_permlane16_swap_b32_e32 v25, v29
	v_permlane16_swap_b32_e32 v26, v30
	v_permlane16_swap_b32_e32 v27, v31
	v_permlane16_swap_b32_e32 v112, v116
	v_permlane16_swap_b32_e32 v113, v117
	v_permlane16_swap_b32_e32 v114, v118
	v_permlane16_swap_b32_e32 v115, v119
	v_permlane16_swap_b32_e32 v120, v124
	v_permlane16_swap_b32_e32 v121, v125
	v_permlane16_swap_b32_e32 v122, v126
	v_permlane16_swap_b32_e32 v123, v127
	v_permlane16_swap_b32_e32 v80, v84
	v_permlane16_swap_b32_e32 v81, v85
	v_permlane16_swap_b32_e32 v82, v86
	v_permlane16_swap_b32_e32 v83, v87
	v_permlane16_swap_b32_e32 v88, v92
	v_permlane16_swap_b32_e32 v89, v93
	v_permlane16_swap_b32_e32 v90, v94
	v_permlane16_swap_b32_e32 v91, v95
	v_permlane16_swap_b32_e32 v64, v68
	v_permlane16_swap_b32_e32 v65, v69
	v_permlane16_swap_b32_e32 v66, v70
	v_permlane16_swap_b32_e32 v67, v71
	v_permlane16_swap_b32_e32 v72, v76
	v_permlane16_swap_b32_e32 v73, v77
	v_permlane16_swap_b32_e32 v74, v78
	v_permlane16_swap_b32_e32 v75, v79
	v_permlane16_swap_b32_e32 v0, v4
	v_permlane16_swap_b32_e32 v1, v5
	v_permlane16_swap_b32_e32 v2, v6
	v_permlane16_swap_b32_e32 v3, v7
	v_permlane16_swap_b32_e32 v8, v12
	v_permlane16_swap_b32_e32 v9, v13
	v_permlane16_swap_b32_e32 v10, v14
	v_permlane16_swap_b32_e32 v11, v15
	v_permlane16_swap_b32_e32 v96, v100
	v_permlane16_swap_b32_e32 v97, v101
	v_permlane16_swap_b32_e32 v98, v102
	v_permlane16_swap_b32_e32 v99, v103
	v_permlane16_swap_b32_e32 v104, v108
	v_permlane16_swap_b32_e32 v105, v109
	v_permlane16_swap_b32_e32 v106, v110
	v_permlane16_swap_b32_e32 v107, v111
	v_permlane16_swap_b32_e32 v48, v52
	v_permlane16_swap_b32_e32 v49, v53
	v_permlane16_swap_b32_e32 v50, v54
	v_permlane16_swap_b32_e32 v51, v55
	v_permlane16_swap_b32_e32 v56, v60
	v_permlane16_swap_b32_e32 v57, v61
	v_permlane16_swap_b32_e32 v58, v62
	v_permlane16_swap_b32_e32 v59, v63
	v_permlane16_swap_b32_e32 v32, v36
	v_permlane16_swap_b32_e32 v33, v37
	v_permlane16_swap_b32_e32 v34, v38
	v_permlane16_swap_b32_e32 v35, v39
	v_permlane16_swap_b32_e32 v40, v44
	v_permlane16_swap_b32_e32 v41, v45
	v_permlane16_swap_b32_e32 v42, v46
	v_permlane16_swap_b32_e32 v43, v47
	v_permlane32_swap_b32_e32 v16, v20
	v_permlane32_swap_b32_e32 v17, v21
	v_permlane32_swap_b32_e32 v18, v22
	v_permlane32_swap_b32_e32 v19, v23
	v_permlane32_swap_b32_e32 v24, v28
	v_permlane32_swap_b32_e32 v25, v29
	v_permlane32_swap_b32_e32 v26, v30
	v_permlane32_swap_b32_e32 v27, v31
	v_permlane32_swap_b32_e32 v112, v116
	v_permlane32_swap_b32_e32 v113, v117
	v_permlane32_swap_b32_e32 v114, v118
	v_permlane32_swap_b32_e32 v115, v119
	v_permlane32_swap_b32_e32 v120, v124
	v_permlane32_swap_b32_e32 v121, v125
	v_permlane32_swap_b32_e32 v122, v126
	v_permlane32_swap_b32_e32 v123, v127
	v_permlane32_swap_b32_e32 v80, v84
	v_permlane32_swap_b32_e32 v81, v85
	v_permlane32_swap_b32_e32 v82, v86
	v_permlane32_swap_b32_e32 v83, v87
	v_permlane32_swap_b32_e32 v88, v92
	v_permlane32_swap_b32_e32 v89, v93
	v_permlane32_swap_b32_e32 v90, v94
	v_permlane32_swap_b32_e32 v91, v95
	v_permlane32_swap_b32_e32 v64, v68
	v_permlane32_swap_b32_e32 v65, v69
	v_permlane32_swap_b32_e32 v66, v70
	v_permlane32_swap_b32_e32 v67, v71
	v_permlane32_swap_b32_e32 v72, v76
	v_permlane32_swap_b32_e32 v73, v77
	v_permlane32_swap_b32_e32 v74, v78
	v_permlane32_swap_b32_e32 v75, v79
	v_permlane32_swap_b32_e32 v0, v4
	v_permlane32_swap_b32_e32 v1, v5
	v_permlane32_swap_b32_e32 v2, v6
	v_permlane32_swap_b32_e32 v3, v7
	v_permlane32_swap_b32_e32 v8, v12
	v_permlane32_swap_b32_e32 v9, v13
	v_permlane32_swap_b32_e32 v10, v14
	v_permlane32_swap_b32_e32 v11, v15
	v_permlane32_swap_b32_e32 v96, v100
	v_permlane32_swap_b32_e32 v97, v101
	v_permlane32_swap_b32_e32 v98, v102
	v_permlane32_swap_b32_e32 v99, v103
	v_permlane32_swap_b32_e32 v104, v108
	v_permlane32_swap_b32_e32 v105, v109
	v_permlane32_swap_b32_e32 v106, v110
	v_permlane32_swap_b32_e32 v107, v111
	v_permlane32_swap_b32_e32 v48, v52
	v_permlane32_swap_b32_e32 v49, v53
	v_permlane32_swap_b32_e32 v50, v54
	v_permlane32_swap_b32_e32 v51, v55
	v_permlane32_swap_b32_e32 v56, v60
	v_permlane32_swap_b32_e32 v57, v61
	v_permlane32_swap_b32_e32 v58, v62
	v_permlane32_swap_b32_e32 v59, v63
	v_permlane32_swap_b32_e32 v32, v36
	v_permlane32_swap_b32_e32 v33, v37
	v_permlane32_swap_b32_e32 v34, v38
	v_permlane32_swap_b32_e32 v35, v39
	v_permlane32_swap_b32_e32 v40, v44
	v_permlane32_swap_b32_e32 v41, v45
	v_permlane32_swap_b32_e32 v42, v46
	v_permlane32_swap_b32_e32 v43, v47
	s_waitcnt vmcnt(0)
	s_lshl_b32 s12, s2, 8
	s_cmp_eq_u32 s0, 23
	s_mov_b64 s[2:3], -1
	s_cbranch_scc1 .LBB0_347
	s_movk_i32 s1, 0x2400
	s_waitcnt vmcnt(6)
	v_and_b32_e32 v130, 0xffffffc0, v181
	s_cmp_gt_i32 s0, 10
	v_mul_lo_u32 v129, v233, s1
	v_and_b32_e32 v128, 56, v234
	v_add_u32_e32 v131, s12, v130
	s_cselect_b64 s[2:3], -1, 0
	s_cmp_gt_u32 s0, 19
	v_mul_u32_u24_e32 v130, 0x120, v183
	s_waitcnt vmcnt(0)
	v_lshl_or_b32 v132, v128, 1, v129
	v_lshl_or_b32 v128, s0, 7, v128
	s_cselect_b64 s[0:1], -1, 0
	v_lshl_add_u32 v129, v130, 1, v129
	v_lshl_or_b32 v130, v231, 1, v129
	v_cvt_pk_bf16_f32 v112, v112, s0
	ds_write_b16 v130, v112 offset:64
	v_cvt_pk_bf16_f32 v112, v17, s0
	v_cvt_pk_bf16_f32 v96, v96, s0
	ds_write_b16 v130, v112 offset:144
	v_cvt_pk_bf16_f32 v112, v113, s0
	ds_write_b16 v130, v96 offset:4672
	v_cvt_pk_bf16_f32 v96, v1, s0
	ds_write_b16 v130, v112 offset:208
	v_cvt_pk_bf16_f32 v112, v18, s0
	ds_write_b16 v130, v96 offset:4752
	v_cvt_pk_bf16_f32 v96, v97, s0
	ds_write_b16 v130, v112 offset:288
	v_cvt_pk_bf16_f32 v112, v114, s0
	ds_write_b16 v130, v96 offset:4816
	v_cvt_pk_bf16_f32 v96, v2, s0
	ds_write_b16 v130, v112 offset:352
	v_cvt_pk_bf16_f32 v112, v19, s0
	ds_write_b16 v130, v96 offset:4896
	v_cvt_pk_bf16_f32 v96, v98, s0
	ds_write_b16 v130, v112 offset:432
	v_cvt_pk_bf16_f32 v112, v115, s0
	ds_write_b16 v130, v96 offset:4960
	v_cvt_pk_bf16_f32 v96, v3, s0
	ds_write_b16 v130, v112 offset:496
	v_cvt_pk_bf16_f32 v112, v20, s0
	ds_write_b16 v130, v96 offset:5040
	v_cvt_pk_bf16_f32 v96, v99, s0
	ds_write_b16 v130, v112 offset:1152
	v_cvt_pk_bf16_f32 v112, v116, s0
	ds_write_b16 v130, v96 offset:5104
	v_cvt_pk_bf16_f32 v96, v4, s0
	ds_write_b16 v130, v112 offset:1216
	v_cvt_pk_bf16_f32 v112, v21, s0
	ds_write_b16 v130, v96 offset:5760
	v_cvt_pk_bf16_f32 v96, v100, s0
	ds_write_b16 v130, v112 offset:1296
	v_cvt_pk_bf16_f32 v112, v117, s0
	ds_write_b16 v130, v96 offset:5824
	v_cvt_pk_bf16_f32 v96, v5, s0
	ds_write_b16 v130, v112 offset:1360
	v_cvt_pk_bf16_f32 v112, v22, s0
	ds_write_b16 v130, v96 offset:5904
	v_cvt_pk_bf16_f32 v96, v101, s0
	ds_write_b16 v130, v112 offset:1440
	v_cvt_pk_bf16_f32 v112, v118, s0
	ds_write_b16 v130, v96 offset:5968
	v_cvt_pk_bf16_f32 v96, v6, s0
	ds_write_b16 v130, v112 offset:1504
	v_cvt_pk_bf16_f32 v112, v23, s0
	ds_write_b16 v130, v96 offset:6048
	v_cvt_pk_bf16_f32 v96, v102, s0
	ds_write_b16 v130, v112 offset:1584
	v_cvt_pk_bf16_f32 v112, v119, s0
	ds_write_b16 v130, v96 offset:6112
	v_cvt_pk_bf16_f32 v96, v7, s0
	ds_write_b16 v130, v112 offset:1648
	v_cvt_pk_bf16_f32 v112, v24, s0
	ds_write_b16 v130, v96 offset:6192
	v_cvt_pk_bf16_f32 v96, v103, s0
	ds_write_b16 v130, v112 offset:2304
	v_cvt_pk_bf16_f32 v112, v120, s0
	ds_write_b16 v130, v96 offset:6256
	v_cvt_pk_bf16_f32 v96, v8, s0
	ds_write_b16 v130, v112 offset:2368
	v_cvt_pk_bf16_f32 v112, v25, s0
	ds_write_b16 v130, v96 offset:6912
	v_cvt_pk_bf16_f32 v96, v104, s0
	ds_write_b16 v130, v112 offset:2448
	v_cvt_pk_bf16_f32 v112, v121, s0
	ds_write_b16 v130, v96 offset:6976
	v_cvt_pk_bf16_f32 v96, v9, s0
	ds_write_b16 v130, v112 offset:2512
	v_cvt_pk_bf16_f32 v112, v26, s0
	ds_write_b16 v130, v96 offset:7056
	v_cvt_pk_bf16_f32 v96, v105, s0
	ds_write_b16 v130, v112 offset:2592
	v_cvt_pk_bf16_f32 v112, v122, s0
	ds_write_b16 v130, v96 offset:7120
	v_cvt_pk_bf16_f32 v96, v10, s0
	ds_write_b16 v130, v112 offset:2656
	v_cvt_pk_bf16_f32 v112, v27, s0
	ds_write_b16 v130, v96 offset:7200
	v_cvt_pk_bf16_f32 v96, v106, s0
	ds_write_b16 v130, v112 offset:2736
	v_cvt_pk_bf16_f32 v112, v123, s0
	ds_write_b16 v130, v96 offset:7264
	v_cvt_pk_bf16_f32 v96, v11, s0
	ds_write_b16 v130, v112 offset:2800
	v_cvt_pk_bf16_f32 v112, v28, s0
	ds_write_b16 v130, v96 offset:7344
	v_cvt_pk_bf16_f32 v96, v107, s0
	ds_write_b16 v130, v112 offset:3456
	v_cvt_pk_bf16_f32 v112, v124, s0
	ds_write_b16 v130, v96 offset:7408
	v_cvt_pk_bf16_f32 v96, v12, s0
	ds_write_b16 v130, v112 offset:3520
	v_cvt_pk_bf16_f32 v112, v29, s0
	ds_write_b16 v130, v96 offset:8064
	v_cvt_pk_bf16_f32 v96, v108, s0
	ds_write_b16 v130, v112 offset:3600
	v_cvt_pk_bf16_f32 v112, v125, s0
	ds_write_b16 v130, v96 offset:8128
	v_cvt_pk_bf16_f32 v96, v13, s0
	ds_write_b16 v130, v112 offset:3664
	v_cvt_pk_bf16_f32 v112, v30, s0
	ds_write_b16 v130, v96 offset:8208
	v_cvt_pk_bf16_f32 v96, v109, s0
	ds_write_b16 v130, v112 offset:3744
	v_cvt_pk_bf16_f32 v112, v126, s0
	ds_write_b16 v130, v96 offset:8272
	v_cvt_pk_bf16_f32 v96, v14, s0
	ds_write_b16 v130, v112 offset:3808
	v_cvt_pk_bf16_f32 v112, v31, s0
	ds_write_b16 v130, v96 offset:8352
	v_cvt_pk_bf16_f32 v96, v110, s0
	ds_write_b16 v130, v112 offset:3888
	v_cvt_pk_bf16_f32 v112, v127, s0
	ds_write_b16 v130, v96 offset:8416
	v_cvt_pk_bf16_f32 v96, v15, s0
	v_cvt_pk_bf16_f32 v133, v16, s0
	ds_write_b16 v130, v112 offset:3952
	v_cvt_pk_bf16_f32 v112, v0, s0
	ds_write_b16 v130, v96 offset:8496
	v_cvt_pk_bf16_f32 v96, v111, s0
	ds_write_b16 v130, v133
	ds_write_b16 v130, v112 offset:4608
	ds_write_b16 v130, v96 offset:8560
	v_lshrrev_b32_e32 v109, 3, v232
	s_waitcnt lgkmcnt(0)
	v_mad_u32_u24 v96, v109, s42, v132
	ds_read_b128 v[96:99], v96
	v_mov_b32_e32 v176, v128
	v_or_b32_e32 v110, v131, v109
	s_mov_b64 s[4:5], -1
	s_and_b64 vcc, exec, s[2:3]
	s_cbranch_vccz .LBB0_224
	s_and_b64 vcc, exec, s[0:1]
	s_cbranch_vccz .LBB0_221
	v_readlane_b32 s16, v254, 15
	v_readlane_b32 s18, v254, 17
	v_readlane_b32 s19, v254, 18
	v_readlane_b32 s17, v254, 16
	v_readlane_b32 s20, v254, 19
	v_mov_b64_e32 v[100:101], s[18:19]
	v_mad_i64_i32 v[100:101], s[4:5], v110, s89, v[100:101]
	s_movk_i32 s4, 0xec00
	v_lshl_add_u64 v[100:101], v[176:177], 1, v[100:101]
	s_mov_b32 s5, -1
	v_readlane_b32 s21, v254, 20
	v_readlane_b32 s22, v254, 21
	v_readlane_b32 s23, v254, 22
	v_readlane_b32 s24, v254, 23
	v_readlane_b32 s25, v254, 24
	v_readlane_b32 s26, v254, 25
	v_readlane_b32 s27, v254, 26
	v_readlane_b32 s28, v254, 27
	v_readlane_b32 s29, v254, 28
	v_readlane_b32 s30, v254, 29
	v_readlane_b32 s31, v254, 30
	v_lshl_add_u64 v[100:101], v[100:101], 0, s[4:5]
	s_mov_b64 s[4:5], 0

.LBB0_923:
	s_ashr_i32 s2, s4, 31
	s_lshr_b32 s2, s2, 26
	s_add_i32 s2, s4, s2
	s_ashr_i32 s3, s2, 6
	s_lshl_b32 s3, s3, 3
	s_sub_i32 s8, s25, s3
	s_min_i32 s8, s8, 8
	s_abs_i32 s9, s8
	v_cvt_f32_u32_e32 v0, s9
	s_sub_i32 s12, 0, s9
	s_andn2_b32 s2, s2, 63
	s_sub_i32 s10, s4, s2
	v_rcp_iflag_f32_e32 v0, v0
	s_abs_i32 s2, s10
	s_xor_b32 s11, s10, s8
	s_ashr_i32 s11, s11, 31
	v_mul_f32_e32 v0, 0x4f7ffffe, v0
	v_cvt_u32_f32_e32 v0, v0
	v_mov_b32_e32 v181, v179
	v_readfirstlane_b32 s13, v0
	s_mul_i32 s12, s12, s13
	s_mul_hi_u32 s12, s13, s12
	s_add_i32 s13, s13, s12
	s_mul_hi_u32 s12, s2, s13
	s_mul_i32 s13, s12, s9
	s_sub_i32 s2, s2, s13
	s_add_i32 s14, s12, 1
	s_sub_i32 s13, s2, s9
	s_cmp_ge_u32 s2, s9
	s_cselect_b32 s12, s14, s12
	s_cselect_b32 s2, s13, s2
	s_add_i32 s13, s12, 1
	s_cmp_ge_u32 s2, s9
	s_cselect_b32 s2, s13, s12
	s_xor_b32 s2, s2, s11
	s_sub_i32 s2, s2, s11
	s_mul_i32 s8, s8, s2
	s_add_i32 s3, s3, s7
	s_sub_i32 s8, s10, s8
	v_ashrrev_i32_e32 v237, 6, v181
	s_add_i32 s8, s3, s8
	v_lshlrev_b32_e32 v0, 1, v237
	v_lshl_add_u32 v0, s8, 3, v0
	v_ashrrev_i32_e32 v1, 31, v0
	v_bfe_u32 v183, v181, 5, 1
	v_lshlrev_b64 v[0:1], 16, v[0:1]
	v_and_b32_e32 v238, 31, v181
	v_lshl_add_u64 v[0:1], s[64:65], 0, v[0:1]
	v_lshlrev_b32_e32 v176, 9, v183
	s_ashr_i32 s3, s2, 31
	v_lshl_add_u64 v[0:1], v[0:1], 0, v[176:177]
	v_lshlrev_b32_e32 v176, 4, v238
	v_ashrrev_i32_e32 v40, 2, v181
	s_lshl_b64 s[10:11], s[2:3], 18
	v_lshl_add_u64 v[184:185], v[0:1], 0, v[176:177]
	s_add_u32 s10, s5, s10
	v_lshlrev_b32_e32 v0, 5, v40
	s_addc_u32 s11, s6, s11
	v_ashrrev_i32_e32 v1, 31, v0
	v_lshlrev_b32_e32 v2, 4, v181
	v_lshl_add_u64 v[0:1], v[0:1], 1, s[10:11]
	v_and_b32_e32 v176, 48, v2
	v_lshl_add_u64 v[186:187], v[0:1], 0, v[176:177]
	s_movk_i32 s3, 0x2000
	v_add_co_u32_e32 v36, vcc, s3, v186
	v_mul_u32_u24_e32 v38, 40, v238
	s_nop 0
	v_addc_co_u32_e32 v37, vcc, 0, v187, vcc
	v_lshlrev_b32_e32 v39, 4, v183
	v_lshl_add_u32 v240, v38, 1, v39
	v_add_co_u32_e32 v38, vcc, s41, v184
	s_movk_i32 s9, 0x50
	s_nop 0
	v_addc_co_u32_e32 v39, vcc, 0, v185, vcc
	v_and_b32_e32 v239, 63, v181
	v_mov_b32_e32 v176, 0x800
	v_lshl_add_u64 v[188:189], v[186:187], 0, v[176:177]
	v_bfe_u32 v247, v181, 4, 1
	v_lshlrev_b32_e32 v176, 9, v183
	v_lshl_add_u32 v176, v247, 8, v176
	v_lshl_add_u64 v[184:185], v[184:185], 0, v[176:177]
	v_mov_b32_e32 v176, s41
	v_lshl_add_u64 v[186:187], v[184:185], 0, v[176:177]
	v_lshrrev_b32_e32 v241, 2, v181
	v_bfe_u32 v247, v181, 4, 2
	v_lshlrev_b32_e32 v247, 1, v247
	v_mov_b32_e32 v176, 0x78
	v_lshrrev_b32_e32 v247, v247, v176
	v_and_b32_e32 v247, 3, v247
	v_and_b32_e32 v246, 3, v181
	v_xor_b32_e32 v247, v247, v246
	v_lshlrev_b32_e32 v247, 4, v247
	v_lshl_add_u32 v241, v241, 6, v247
	v_bfe_u32 v247, v181, 2, 2
	v_lshlrev_b32_e32 v247, 1, v247
	v_lshrrev_b32_e32 v247, v247, v176
	v_and_b32_e32 v247, 3, v247
	v_bfe_u32 v246, v181, 4, 2
	v_xor_b32_e32 v247, v247, v246
	v_lshlrev_b32_e32 v247, 4, v247
	v_and_b32_e32 v246, 15, v181
	v_lshl_add_u32 v246, v246, 6, v247
	s_mov_b32 s96, 0
	v_lshl_add_u64 v[166:167], v[188:189], 0, s[96:97]
	global_load_dwordx4 v[160:163], v[166:167], off offset:-2048
	global_load_dwordx4 v[164:167], v[166:167], off offset:2048
	s_movk_i32 s96, 0x2000
	v_lshl_add_u64 v[174:175], v[188:189], 0, s[96:97]
	global_load_dwordx4 v[168:171], v[174:175], off offset:-2048
	global_load_dwordx4 v[172:175], v[174:175], off offset:2048
	s_mov_b32 s96, 0
	v_lshl_add_u64 v[248:249], v[184:185], 0, s[96:97]
	v_lshl_add_u64 v[250:251], v[186:187], 0, s[96:97]
	global_load_dwordx4 v[128:131], v[248:249], off
	global_load_dwordx4 v[132:135], v[248:249], off offset:256
	global_load_dwordx4 v[136:139], v[250:251], off
	global_load_dwordx4 v[140:143], v[250:251], off offset:256
	s_movk_i32 s96, 0x800
	v_lshl_add_u64 v[248:249], v[184:185], 0, s[96:97]
	v_lshl_add_u64 v[250:251], v[186:187], 0, s[96:97]
	global_load_dwordx4 v[144:147], v[248:249], off
	global_load_dwordx4 v[148:151], v[248:249], off offset:256
	global_load_dwordx4 v[152:155], v[250:251], off
	global_load_dwordx4 v[156:159], v[250:251], off offset:256
	v_mov_b32_e32 v0, 0
	v_mov_b32_e32 v1, 0
	v_mov_b32_e32 v2, 0
	v_mov_b32_e32 v3, 0
	v_mov_b32_e32 v4, 0
	v_mov_b32_e32 v5, 0
	v_mov_b32_e32 v6, 0
	v_mov_b32_e32 v7, 0
	v_mov_b32_e32 v8, 0
	v_mov_b32_e32 v9, 0
	v_mov_b32_e32 v10, 0
	v_mov_b32_e32 v11, 0
	v_mov_b32_e32 v12, 0
	v_mov_b32_e32 v13, 0
	v_mov_b32_e32 v14, 0
	v_mov_b32_e32 v15, 0
	v_mov_b32_e32 v16, 0
	v_mov_b32_e32 v17, 0
	v_mov_b32_e32 v18, 0
	v_mov_b32_e32 v19, 0
	v_mov_b32_e32 v20, 0
	v_mov_b32_e32 v21, 0
	v_mov_b32_e32 v22, 0
	v_mov_b32_e32 v23, 0
	v_mov_b32_e32 v24, 0
	v_mov_b32_e32 v25, 0
	v_mov_b32_e32 v26, 0
	v_mov_b32_e32 v27, 0
	v_mov_b32_e32 v28, 0
	v_mov_b32_e32 v29, 0
	v_mov_b32_e32 v30, 0
	v_mov_b32_e32 v31, 0
	v_mov_b32_e32 v32, 0
	v_mov_b32_e32 v33, 0
	v_mov_b32_e32 v34, 0
	v_mov_b32_e32 v35, 0
	v_mov_b32_e32 v36, 0
	v_mov_b32_e32 v37, 0
	v_mov_b32_e32 v38, 0
	v_mov_b32_e32 v39, 0
	v_mov_b32_e32 v40, 0
	v_mov_b32_e32 v41, 0
	v_mov_b32_e32 v42, 0
	v_mov_b32_e32 v43, 0
	v_mov_b32_e32 v44, 0
	v_mov_b32_e32 v45, 0
	v_mov_b32_e32 v46, 0
	v_mov_b32_e32 v47, 0
	v_mov_b32_e32 v48, 0
	v_mov_b32_e32 v49, 0
	v_mov_b32_e32 v50, 0
	v_mov_b32_e32 v51, 0
	v_mov_b32_e32 v52, 0
	v_mov_b32_e32 v53, 0
	v_mov_b32_e32 v54, 0
	v_mov_b32_e32 v55, 0
	v_mov_b32_e32 v56, 0
	v_mov_b32_e32 v57, 0
	v_mov_b32_e32 v58, 0
	v_mov_b32_e32 v59, 0
	v_mov_b32_e32 v60, 0
	v_mov_b32_e32 v61, 0
	v_mov_b32_e32 v62, 0
	v_mov_b32_e32 v63, 0
	v_mov_b32_e32 v64, 0
	v_mov_b32_e32 v65, 0
	v_mov_b32_e32 v66, 0
	v_mov_b32_e32 v67, 0
	v_mov_b32_e32 v68, 0
	v_mov_b32_e32 v69, 0
	v_mov_b32_e32 v70, 0
	v_mov_b32_e32 v71, 0
	v_mov_b32_e32 v72, 0
	v_mov_b32_e32 v73, 0
	v_mov_b32_e32 v74, 0
	v_mov_b32_e32 v75, 0
	v_mov_b32_e32 v76, 0
	v_mov_b32_e32 v77, 0
	v_mov_b32_e32 v78, 0
	v_mov_b32_e32 v79, 0
	v_mov_b32_e32 v80, 0
	v_mov_b32_e32 v81, 0
	v_mov_b32_e32 v82, 0
	v_mov_b32_e32 v83, 0
	v_mov_b32_e32 v84, 0
	v_mov_b32_e32 v85, 0
	v_mov_b32_e32 v86, 0
	v_mov_b32_e32 v87, 0
	v_mov_b32_e32 v88, 0
	v_mov_b32_e32 v89, 0
	v_mov_b32_e32 v90, 0
	v_mov_b32_e32 v91, 0
	v_mov_b32_e32 v92, 0
	v_mov_b32_e32 v93, 0
	v_mov_b32_e32 v94, 0
	v_mov_b32_e32 v95, 0
	v_mov_b32_e32 v96, 0
	v_mov_b32_e32 v97, 0
	v_mov_b32_e32 v98, 0
	v_mov_b32_e32 v99, 0
	v_mov_b32_e32 v100, 0
	v_mov_b32_e32 v101, 0
	v_mov_b32_e32 v102, 0
	v_mov_b32_e32 v103, 0
	v_mov_b32_e32 v104, 0
	v_mov_b32_e32 v105, 0
	v_mov_b32_e32 v106, 0
	v_mov_b32_e32 v107, 0
	v_mov_b32_e32 v108, 0
	v_mov_b32_e32 v109, 0
	v_mov_b32_e32 v110, 0
	v_mov_b32_e32 v111, 0
	v_mov_b32_e32 v112, 0
	v_mov_b32_e32 v113, 0
	v_mov_b32_e32 v114, 0
	v_mov_b32_e32 v115, 0
	v_mov_b32_e32 v116, 0
	v_mov_b32_e32 v117, 0
	v_mov_b32_e32 v118, 0
	v_mov_b32_e32 v119, 0
	v_mov_b32_e32 v120, 0
	v_mov_b32_e32 v121, 0
	v_mov_b32_e32 v122, 0
	v_mov_b32_e32 v123, 0
	v_mov_b32_e32 v124, 0
	v_mov_b32_e32 v125, 0
	v_mov_b32_e32 v126, 0
	v_mov_b32_e32 v127, 0
	s_mov_b32 s3, 0
	s_waitcnt vmcnt(10)
	ds_write_b128 v241, v[160:163]
	ds_write_b128 v241, v[164:167] offset:4096
	s_waitcnt lgkmcnt(0)
	s_movk_i32 s96, 0x4000
	v_lshl_add_u64 v[166:167], v[188:189], 0, s[96:97]
	global_load_dwordx4 v[160:163], v[166:167], off offset:-2048
	global_load_dwordx4 v[164:167], v[166:167], off offset:2048
	s_barrier
.Lg16_out_k:
	ds_read_b128 v[196:199], v246 offset:0
	ds_read_b128 v[200:203], v246 offset:1024
	ds_read_b128 v[204:207], v246 offset:2048
	ds_read_b128 v[242:245], v246 offset:3072
	s_add_i32 s9, s3, 2
	s_min_u32 s10, s9, 30
	s_lshl_b32 s96, s10, 11
	v_lshl_add_u64 v[248:249], v[184:185], 0, s[96:97]
	v_lshl_add_u64 v[250:251], v[186:187], 0, s[96:97]
	s_waitcnt vmcnt(6) lgkmcnt(3)
	v_mfma_f32_16x16x32_bf16 v[112:115], v[128:131], v[196:199], v[112:115]
	v_mfma_f32_16x16x32_bf16 v[120:123], v[132:135], v[196:199], v[120:123]
	v_mfma_f32_16x16x32_bf16 v[48:51], v[136:139], v[196:199], v[48:51]
	v_mfma_f32_16x16x32_bf16 v[56:59], v[140:143], v[196:199], v[56:59]
	ds_read_b128 v[196:199], v246 offset:4096
	s_waitcnt lgkmcnt(3)
	v_mfma_f32_16x16x32_bf16 v[116:119], v[128:131], v[200:203], v[116:119]
	v_mfma_f32_16x16x32_bf16 v[124:127], v[132:135], v[200:203], v[124:127]
	v_mfma_f32_16x16x32_bf16 v[52:55], v[136:139], v[200:203], v[52:55]
	v_mfma_f32_16x16x32_bf16 v[60:63], v[140:143], v[200:203], v[60:63]
	ds_read_b128 v[200:203], v246 offset:5120
	s_waitcnt lgkmcnt(3)
	v_mfma_f32_16x16x32_bf16 v[96:99], v[128:131], v[204:207], v[96:99]
	v_mfma_f32_16x16x32_bf16 v[104:107], v[132:135], v[204:207], v[104:107]
	v_mfma_f32_16x16x32_bf16 v[32:35], v[136:139], v[204:207], v[32:35]
	v_mfma_f32_16x16x32_bf16 v[40:43], v[140:143], v[204:207], v[40:43]
	ds_read_b128 v[204:207], v246 offset:6144
	s_waitcnt lgkmcnt(3)
	v_mfma_f32_16x16x32_bf16 v[100:103], v[128:131], v[242:245], v[100:103]
	v_mfma_f32_16x16x32_bf16 v[108:111], v[132:135], v[242:245], v[108:111]
	v_mfma_f32_16x16x32_bf16 v[36:39], v[136:139], v[242:245], v[36:39]
	v_mfma_f32_16x16x32_bf16 v[44:47], v[140:143], v[242:245], v[44:47]
	ds_read_b128 v[242:245], v246 offset:7168
	ds_write_b128 v241, v[168:171] offset:8192
	ds_write_b128 v241, v[172:175] offset:12288
	s_add_i32 s9, s3, 3
	s_min_u32 s10, s9, 31
	s_lshl_b32 s96, s10, 13
	v_lshl_add_u64 v[174:175], v[188:189], 0, s[96:97]
	global_load_dwordx4 v[168:171], v[174:175], off offset:-2048
	global_load_dwordx4 v[172:175], v[174:175], off offset:2048
	s_waitcnt lgkmcnt(5)
	v_mfma_f32_16x16x32_bf16 v[80:83], v[128:131], v[196:199], v[80:83]
	v_mfma_f32_16x16x32_bf16 v[88:91], v[132:135], v[196:199], v[88:91]
	v_mfma_f32_16x16x32_bf16 v[16:19], v[136:139], v[196:199], v[16:19]
	v_mfma_f32_16x16x32_bf16 v[24:27], v[140:143], v[196:199], v[24:27]
	s_waitcnt lgkmcnt(4)
	v_mfma_f32_16x16x32_bf16 v[84:87], v[128:131], v[200:203], v[84:87]
	v_mfma_f32_16x16x32_bf16 v[92:95], v[132:135], v[200:203], v[92:95]
	v_mfma_f32_16x16x32_bf16 v[20:23], v[136:139], v[200:203], v[20:23]
	v_mfma_f32_16x16x32_bf16 v[28:31], v[140:143], v[200:203], v[28:31]
	s_waitcnt lgkmcnt(3)
	v_mfma_f32_16x16x32_bf16 v[64:67], v[128:131], v[204:207], v[64:67]
	v_mfma_f32_16x16x32_bf16 v[72:75], v[132:135], v[204:207], v[72:75]
	v_mfma_f32_16x16x32_bf16 v[0:3], v[136:139], v[204:207], v[0:3]
	v_mfma_f32_16x16x32_bf16 v[8:11], v[140:143], v[204:207], v[8:11]
	s_waitcnt lgkmcnt(2)
	v_mfma_f32_16x16x32_bf16 v[68:71], v[128:131], v[242:245], v[68:71]
	v_mfma_f32_16x16x32_bf16 v[76:79], v[132:135], v[242:245], v[76:79]
	v_mfma_f32_16x16x32_bf16 v[4:7], v[136:139], v[242:245], v[4:7]
	v_mfma_f32_16x16x32_bf16 v[12:15], v[140:143], v[242:245], v[12:15]
	global_load_dwordx4 v[128:131], v[248:249], off
	global_load_dwordx4 v[132:135], v[248:249], off offset:256
	global_load_dwordx4 v[136:139], v[250:251], off
	global_load_dwordx4 v[140:143], v[250:251], off offset:256
	s_waitcnt lgkmcnt(0)
	s_barrier
	ds_read_b128 v[196:199], v246 offset:8192
	ds_read_b128 v[200:203], v246 offset:9216
	ds_read_b128 v[204:207], v246 offset:10240
	ds_read_b128 v[242:245], v246 offset:11264
	s_add_i32 s9, s3, 3
	s_min_u32 s10, s9, 31
	s_lshl_b32 s96, s10, 11
	v_lshl_add_u64 v[248:249], v[184:185], 0, s[96:97]
	v_lshl_add_u64 v[250:251], v[186:187], 0, s[96:97]
	s_waitcnt vmcnt(6) lgkmcnt(3)
	v_mfma_f32_16x16x32_bf16 v[112:115], v[144:147], v[196:199], v[112:115]
	v_mfma_f32_16x16x32_bf16 v[120:123], v[148:151], v[196:199], v[120:123]
	v_mfma_f32_16x16x32_bf16 v[48:51], v[152:155], v[196:199], v[48:51]
	v_mfma_f32_16x16x32_bf16 v[56:59], v[156:159], v[196:199], v[56:59]
	ds_read_b128 v[196:199], v246 offset:12288
	s_waitcnt lgkmcnt(3)
	v_mfma_f32_16x16x32_bf16 v[116:119], v[144:147], v[200:203], v[116:119]
	v_mfma_f32_16x16x32_bf16 v[124:127], v[148:151], v[200:203], v[124:127]
	v_mfma_f32_16x16x32_bf16 v[52:55], v[152:155], v[200:203], v[52:55]
	v_mfma_f32_16x16x32_bf16 v[60:63], v[156:159], v[200:203], v[60:63]
	ds_read_b128 v[200:203], v246 offset:13312
	s_waitcnt lgkmcnt(3)
	v_mfma_f32_16x16x32_bf16 v[96:99], v[144:147], v[204:207], v[96:99]
	v_mfma_f32_16x16x32_bf16 v[104:107], v[148:151], v[204:207], v[104:107]
	v_mfma_f32_16x16x32_bf16 v[32:35], v[152:155], v[204:207], v[32:35]
	v_mfma_f32_16x16x32_bf16 v[40:43], v[156:159], v[204:207], v[40:43]
	ds_read_b128 v[204:207], v246 offset:14336
	s_waitcnt lgkmcnt(3)
	v_mfma_f32_16x16x32_bf16 v[100:103], v[144:147], v[242:245], v[100:103]
	v_mfma_f32_16x16x32_bf16 v[108:111], v[148:151], v[242:245], v[108:111]
	v_mfma_f32_16x16x32_bf16 v[36:39], v[152:155], v[242:245], v[36:39]
	v_mfma_f32_16x16x32_bf16 v[44:47], v[156:159], v[242:245], v[44:47]
	ds_read_b128 v[242:245], v246 offset:15360
	ds_write_b128 v241, v[160:163] offset:0
	ds_write_b128 v241, v[164:167] offset:4096
	s_add_i32 s9, s3, 4
	s_min_u32 s10, s9, 30
	s_lshl_b32 s96, s10, 13
	v_lshl_add_u64 v[166:167], v[188:189], 0, s[96:97]
	global_load_dwordx4 v[160:163], v[166:167], off offset:-2048
	global_load_dwordx4 v[164:167], v[166:167], off offset:2048
	s_waitcnt lgkmcnt(5)
	v_mfma_f32_16x16x32_bf16 v[80:83], v[144:147], v[196:199], v[80:83]
	v_mfma_f32_16x16x32_bf16 v[88:91], v[148:151], v[196:199], v[88:91]
	v_mfma_f32_16x16x32_bf16 v[16:19], v[152:155], v[196:199], v[16:19]
	v_mfma_f32_16x16x32_bf16 v[24:27], v[156:159], v[196:199], v[24:27]
	s_waitcnt lgkmcnt(4)
	v_mfma_f32_16x16x32_bf16 v[84:87], v[144:147], v[200:203], v[84:87]
	v_mfma_f32_16x16x32_bf16 v[92:95], v[148:151], v[200:203], v[92:95]
	v_mfma_f32_16x16x32_bf16 v[20:23], v[152:155], v[200:203], v[20:23]
	v_mfma_f32_16x16x32_bf16 v[28:31], v[156:159], v[200:203], v[28:31]
	s_waitcnt lgkmcnt(3)
	v_mfma_f32_16x16x32_bf16 v[64:67], v[144:147], v[204:207], v[64:67]
	v_mfma_f32_16x16x32_bf16 v[72:75], v[148:151], v[204:207], v[72:75]
	v_mfma_f32_16x16x32_bf16 v[0:3], v[152:155], v[204:207], v[0:3]
	v_mfma_f32_16x16x32_bf16 v[8:11], v[156:159], v[204:207], v[8:11]
	s_waitcnt lgkmcnt(2)
	v_mfma_f32_16x16x32_bf16 v[68:71], v[144:147], v[242:245], v[68:71]
	v_mfma_f32_16x16x32_bf16 v[76:79], v[148:151], v[242:245], v[76:79]
	v_mfma_f32_16x16x32_bf16 v[4:7], v[152:155], v[242:245], v[4:7]
	v_mfma_f32_16x16x32_bf16 v[12:15], v[156:159], v[242:245], v[12:15]
	global_load_dwordx4 v[144:147], v[248:249], off
	global_load_dwordx4 v[148:151], v[248:249], off offset:256
	global_load_dwordx4 v[152:155], v[250:251], off
	global_load_dwordx4 v[156:159], v[250:251], off offset:256
	s_add_i32 s3, s3, 2
	s_cmp_lt_u32 s3, 32
	s_waitcnt lgkmcnt(0)
	s_barrier
	s_cbranch_scc1 .Lg16_out_k
	s_nop 7
	v_permlane16_swap_b32_e32 v112, v116
	v_permlane16_swap_b32_e32 v113, v117
	v_permlane16_swap_b32_e32 v114, v118
	v_permlane16_swap_b32_e32 v115, v119
	v_permlane16_swap_b32_e32 v120, v124
	v_permlane16_swap_b32_e32 v121, v125
	v_permlane16_swap_b32_e32 v122, v126
	v_permlane16_swap_b32_e32 v123, v127
	v_permlane16_swap_b32_e32 v96, v100
	v_permlane16_swap_b32_e32 v97, v101
	v_permlane16_swap_b32_e32 v98, v102
	v_permlane16_swap_b32_e32 v99, v103
	v_permlane16_swap_b32_e32 v104, v108
	v_permlane16_swap_b32_e32 v105, v109
	v_permlane16_swap_b32_e32 v106, v110
	v_permlane16_swap_b32_e32 v107, v111
	v_permlane16_swap_b32_e32 v80, v84
	v_permlane16_swap_b32_e32 v81, v85
	v_permlane16_swap_b32_e32 v82, v86
	v_permlane16_swap_b32_e32 v83, v87
	v_permlane16_swap_b32_e32 v88, v92
	v_permlane16_swap_b32_e32 v89, v93
	v_permlane16_swap_b32_e32 v90, v94
	v_permlane16_swap_b32_e32 v91, v95
	v_permlane16_swap_b32_e32 v64, v68
	v_permlane16_swap_b32_e32 v65, v69
	v_permlane16_swap_b32_e32 v66, v70
	v_permlane16_swap_b32_e32 v67, v71
	v_permlane16_swap_b32_e32 v72, v76
	v_permlane16_swap_b32_e32 v73, v77
	v_permlane16_swap_b32_e32 v74, v78
	v_permlane16_swap_b32_e32 v75, v79
	v_permlane16_swap_b32_e32 v48, v52
	v_permlane16_swap_b32_e32 v49, v53
	v_permlane16_swap_b32_e32 v50, v54
	v_permlane16_swap_b32_e32 v51, v55
	v_permlane16_swap_b32_e32 v56, v60
	v_permlane16_swap_b32_e32 v57, v61
	v_permlane16_swap_b32_e32 v58, v62
	v_permlane16_swap_b32_e32 v59, v63
	v_permlane16_swap_b32_e32 v32, v36
	v_permlane16_swap_b32_e32 v33, v37
	v_permlane16_swap_b32_e32 v34, v38
	v_permlane16_swap_b32_e32 v35, v39
	v_permlane16_swap_b32_e32 v40, v44
	v_permlane16_swap_b32_e32 v41, v45
	v_permlane16_swap_b32_e32 v42, v46
	v_permlane16_swap_b32_e32 v43, v47
	v_permlane16_swap_b32_e32 v16, v20
	v_permlane16_swap_b32_e32 v17, v21
	v_permlane16_swap_b32_e32 v18, v22
	v_permlane16_swap_b32_e32 v19, v23
	v_permlane16_swap_b32_e32 v24, v28
	v_permlane16_swap_b32_e32 v25, v29
	v_permlane16_swap_b32_e32 v26, v30
	v_permlane16_swap_b32_e32 v27, v31
	v_permlane16_swap_b32_e32 v0, v4
	v_permlane16_swap_b32_e32 v1, v5
	v_permlane16_swap_b32_e32 v2, v6
	v_permlane16_swap_b32_e32 v3, v7
	v_permlane16_swap_b32_e32 v8, v12
	v_permlane16_swap_b32_e32 v9, v13
	v_permlane16_swap_b32_e32 v10, v14
	v_permlane16_swap_b32_e32 v11, v15
	v_permlane32_swap_b32_e32 v112, v116
	v_permlane32_swap_b32_e32 v113, v117
	v_permlane32_swap_b32_e32 v114, v118
	v_permlane32_swap_b32_e32 v115, v119
	v_permlane32_swap_b32_e32 v120, v124
	v_permlane32_swap_b32_e32 v121, v125
	v_permlane32_swap_b32_e32 v122, v126
	v_permlane32_swap_b32_e32 v123, v127
	v_permlane32_swap_b32_e32 v96, v100
	v_permlane32_swap_b32_e32 v97, v101
	v_permlane32_swap_b32_e32 v98, v102
	v_permlane32_swap_b32_e32 v99, v103
	v_permlane32_swap_b32_e32 v104, v108
	v_permlane32_swap_b32_e32 v105, v109
	v_permlane32_swap_b32_e32 v106, v110
	v_permlane32_swap_b32_e32 v107, v111
	v_permlane32_swap_b32_e32 v80, v84
	v_permlane32_swap_b32_e32 v81, v85
	v_permlane32_swap_b32_e32 v82, v86
	v_permlane32_swap_b32_e32 v83, v87
	v_permlane32_swap_b32_e32 v88, v92
	v_permlane32_swap_b32_e32 v89, v93
	v_permlane32_swap_b32_e32 v90, v94
	v_permlane32_swap_b32_e32 v91, v95
	v_permlane32_swap_b32_e32 v64, v68
	v_permlane32_swap_b32_e32 v65, v69
	v_permlane32_swap_b32_e32 v66, v70
	v_permlane32_swap_b32_e32 v67, v71
	v_permlane32_swap_b32_e32 v72, v76
	v_permlane32_swap_b32_e32 v73, v77
	v_permlane32_swap_b32_e32 v74, v78
	v_permlane32_swap_b32_e32 v75, v79
	v_permlane32_swap_b32_e32 v48, v52
	v_permlane32_swap_b32_e32 v49, v53
	v_permlane32_swap_b32_e32 v50, v54
	v_permlane32_swap_b32_e32 v51, v55
	v_permlane32_swap_b32_e32 v56, v60
	v_permlane32_swap_b32_e32 v57, v61
	v_permlane32_swap_b32_e32 v58, v62
	v_permlane32_swap_b32_e32 v59, v63
	v_permlane32_swap_b32_e32 v32, v36
	v_permlane32_swap_b32_e32 v33, v37
	v_permlane32_swap_b32_e32 v34, v38
	v_permlane32_swap_b32_e32 v35, v39
	v_permlane32_swap_b32_e32 v40, v44
	v_permlane32_swap_b32_e32 v41, v45
	v_permlane32_swap_b32_e32 v42, v46
	v_permlane32_swap_b32_e32 v43, v47
	v_permlane32_swap_b32_e32 v16, v20
	v_permlane32_swap_b32_e32 v17, v21
	v_permlane32_swap_b32_e32 v18, v22
	v_permlane32_swap_b32_e32 v19, v23
	v_permlane32_swap_b32_e32 v24, v28
	v_permlane32_swap_b32_e32 v25, v29
	v_permlane32_swap_b32_e32 v26, v30
	v_permlane32_swap_b32_e32 v27, v31
	v_permlane32_swap_b32_e32 v0, v4
	v_permlane32_swap_b32_e32 v1, v5
	v_permlane32_swap_b32_e32 v2, v6
	v_permlane32_swap_b32_e32 v3, v7
	v_permlane32_swap_b32_e32 v8, v12
	v_permlane32_swap_b32_e32 v9, v13
	v_permlane32_swap_b32_e32 v10, v14
	v_permlane32_swap_b32_e32 v11, v15
	s_waitcnt vmcnt(0)
	s_movk_i32 s3, 0x2400
	s_waitcnt vmcnt(6)
	v_lshlrev_b32_e32 v128, 2, v181
	s_waitcnt vmcnt(0)
	v_and_b32_e32 v133, 0xffffffc0, v181
	v_mul_lo_u32 v129, v237, s3
	v_lshlrev_b32_e32 v130, 2, v238
	v_and_b32_e32 v128, 60, v128
	v_lshl_add_u32 v176, s8, 8, v133
	v_mul_u32_u24_e32 v133, 0x110, v183
	v_or_b32_e32 v131, v129, v130
	v_lshl_or_b32 v132, v128, 2, v129
	v_lshl_or_b32 v128, s2, 7, v128
	v_lshlrev_b32_e32 v133, 2, v133
	v_lshrrev_b32_e32 v175, 4, v239
	s_movk_i32 s2, 0x110
	v_add_u32_e32 v147, v131, v133
	v_add3_u32 v148, v129, v133, v130
	v_mad_u32_u24 v146, v175, s2, v132
	v_readlane_b32 s2, v254, 39
	v_readlane_b32 s8, v253, 36
	v_add_u32_e32 v149, 0x800, v147
	v_add_u32_e32 v150, 0x800, v148
	v_add_u32_e32 v151, 0xa00, v148
	v_mov_b32_e32 v160, s2
	v_readlane_b32 s2, v254, 37
	v_readlane_b32 s9, v253, 37
	v_readlane_b32 s10, v253, 38
	v_readlane_b32 s11, v253, 39
	v_readlane_b32 s12, v253, 40
	v_readlane_b32 s13, v253, 41
	v_readlane_b32 s14, v253, 42
	v_readlane_b32 s15, v253, 43
	v_readlane_b32 s16, v253, 44
	v_readlane_b32 s17, v253, 45
	ds_write2_b32 v147, v112, v113 offset1:68
	ds_write2_b32 v148, v96, v97 offset0:32 offset1:100
	ds_write2_b32 v147, v114, v115 offset0:136 offset1:204
	ds_write2_b32 v148, v98, v99 offset0:168 offset1:236
	ds_write2_b32 v149, v116, v117 offset0:32 offset1:100
	ds_write2_b32 v150, v100, v101 offset0:64 offset1:132
	ds_write2_b32 v149, v118, v119 offset0:168 offset1:236
	ds_write2_b32 v151, v102, v103 offset0:72 offset1:140
	v_or_b32_e32 v102, v176, v175
	v_mov_b32_e32 v161, s2
	v_readlane_b32 s2, v254, 40
	v_readlane_b32 s18, v253, 46
	v_readlane_b32 s19, v253, 47
	v_readlane_b32 s20, v253, 48
	v_readlane_b32 s21, v253, 49
	v_readlane_b32 s22, v253, 50
	v_readlane_b32 s23, v253, 51
	s_mov_b64 s[8:9], s[16:17]
	v_cmp_gt_i32_e32 vcc, s39, v102
	v_add_u32_e32 v96, 0xffff8000, v102
	v_ashrrev_i32_e32 v97, 31, v102
	v_mov_b32_e32 v162, s2
	v_readlane_b32 s2, v254, 38
	s_mov_b64 s[10:11], s[18:19]
	v_cndmask_b32_e32 v97, 0, v97, vcc
	v_cndmask_b32_e32 v96, v96, v102, vcc
	v_mov_b32_e32 v163, s2
	v_mov_b32_e32 v164, s63
	v_mov_b32_e32 v165, s11
	v_mov_b32_e32 v166, s62
	v_mov_b32_e32 v167, s10
	v_min_i32_e32 v102, 0x8000, v102
	v_add_u32_e32 v152, 0x1000, v147
	v_add_u32_e32 v153, 0x1000, v148
	v_add_u32_e32 v154, 0x1200, v147
	v_add_u32_e32 v155, 0x1200, v148
	v_add_u32_e32 v156, 0x1800, v147
	v_add_u32_e32 v157, 0x1800, v148
	v_add_u32_e32 v158, 0x1a00, v147
	v_add_u32_e32 v159, 0x1c00, v148
	v_ashrrev_i32_e32 v129, 31, v128
	v_cndmask_b32_e32 v99, v160, v161, vcc
	v_cndmask_b32_e32 v98, v162, v163, vcc
	v_lshlrev_b64 v[96:97], 12, v[96:97]
	v_cndmask_b32_e32 v101, v164, v165, vcc
	v_cndmask_b32_e32 v100, v166, v167, vcc
	v_ashrrev_i32_e32 v102, 12, v102
	ds_write2_b32 v152, v120, v121 offset0:64 offset1:132
	ds_write2_b32 v153, v104, v105 offset0:96 offset1:164
	ds_write2_b32 v154, v122, v123 offset0:72 offset1:140
	ds_write2_b32 v155, v106, v107 offset0:104 offset1:172
	ds_write2_b32 v156, v124, v125 offset0:96 offset1:164
	ds_write2_b32 v157, v108, v109 offset0:128 offset1:196
	ds_write2_b32 v158, v126, v127 offset0:104 offset1:172
	ds_write2_b32 v159, v110, v111 offset0:8 offset1:76
	v_lshl_add_u64 v[98:99], v[98:99], 0, v[96:97]
	v_lshl_add_u64 v[100:101], v[100:101], 0, v[96:97]
	v_lshlrev_b64 v[96:97], 2, v[128:129]
	v_mul_hi_i32_i24_e32 v103, 0x6000, v102
	v_mul_i32_i24_e32 v102, 0x6000, v102
	s_waitcnt lgkmcnt(0)
	v_lshl_add_u64 v[98:99], v[98:99], 0, v[96:97]
	v_lshl_add_u64 v[102:103], s[0:1], 0, v[102:103]
	v_lshl_add_u64 v[102:103], v[102:103], 0, v[96:97]
	ds_read_b128 v[104:107], v146
	global_load_dwordx4 v[108:111], v[98:99], off
	global_load_dwordx4 v[112:115], v[102:103], off
	v_or_b32_e32 v168, 4, v175
	v_lshl_add_u64 v[100:101], v[100:101], 0, v[96:97]
	v_or_b32_e32 v169, 8, v175
	v_or_b32_e32 v170, 12, v175
	v_or_b32_e32 v171, 16, v175
	v_or_b32_e32 v172, 20, v175
	v_or_b32_e32 v173, 24, v175
	v_or_b32_e32 v174, 28, v175
	v_or_b32_e32 v181, v176, v174
	v_readlane_b32 s2, v254, 11
	s_add_i32 s4, s4, s2
	s_cmp_lt_i32 s4, s26
	s_mov_b64 s[12:13], s[20:21]
	s_mov_b64 s[14:15], s[22:23]
	s_waitcnt vmcnt(0) lgkmcnt(0)
	v_pk_fma_f32 v[104:105], v[104:105], v[112:113], v[108:109]
	v_pk_fma_f32 v[106:107], v[106:107], v[114:115], v[110:111]
	v_or_b32_e32 v110, v176, v168
	global_store_dwordx4 v[100:101], v[104:107], off
	v_cmp_gt_i32_e32 vcc, s39, v110
	s_nop 0
	v_ashrrev_i32_e32 v104, 31, v110
	v_add_u32_e32 v106, 0xffff8000, v110
	v_cndmask_b32_e32 v105, 0, v104, vcc
	v_cndmask_b32_e32 v104, v106, v110, vcc
	v_cndmask_b32_e32 v107, v160, v161, vcc
	v_cndmask_b32_e32 v106, v162, v163, vcc
	v_lshlrev_b64 v[104:105], 12, v[104:105]
	v_cndmask_b32_e32 v109, v164, v165, vcc
	v_cndmask_b32_e32 v108, v166, v167, vcc
	v_lshl_add_u64 v[106:107], v[106:107], 0, v[104:105]
	v_lshl_add_u64 v[104:105], v[108:109], 0, v[104:105]
	v_min_i32_e32 v108, 0x8000, v110
	v_ashrrev_i32_e32 v108, 12, v108
	v_mul_hi_i32_i24_e32 v109, 0x6000, v108
	v_mul_i32_i24_e32 v108, 0x6000, v108
	v_lshl_add_u64 v[106:107], v[106:107], 0, v[96:97]
	v_lshl_add_u64 v[108:109], s[0:1], 0, v[108:109]
	v_lshl_add_u64 v[108:109], v[108:109], 0, v[96:97]
	ds_read_b128 v[110:113], v146 offset:1088
	global_load_dwordx4 v[114:117], v[106:107], off
	global_load_dwordx4 v[118:121], v[108:109], off
	v_lshl_add_u64 v[104:105], v[104:105], 0, v[96:97]
	s_waitcnt vmcnt(0) lgkmcnt(0)
	v_pk_fma_f32 v[110:111], v[110:111], v[118:119], v[114:115]
	v_pk_fma_f32 v[112:113], v[112:113], v[120:121], v[116:117]
	v_or_b32_e32 v118, v176, v169
	global_store_dwordx4 v[104:105], v[110:113], off
	v_cmp_gt_i32_e32 vcc, s39, v118
	s_nop 0
	v_ashrrev_i32_e32 v110, 31, v118
	v_add_u32_e32 v112, 0xffff8000, v118
	v_cndmask_b32_e32 v111, 0, v110, vcc
	v_cndmask_b32_e32 v110, v112, v118, vcc
	v_cndmask_b32_e32 v113, v160, v161, vcc
	v_cndmask_b32_e32 v112, v162, v163, vcc
	v_lshlrev_b64 v[110:111], 12, v[110:111]
	v_lshl_add_u64 v[112:113], v[112:113], 0, v[110:111]
	v_cndmask_b32_e32 v115, v164, v165, vcc
	v_cndmask_b32_e32 v114, v166, v167, vcc
	v_lshl_add_u64 v[116:117], v[114:115], 0, v[110:111]
	v_lshl_add_u64 v[110:111], v[112:113], 0, v[96:97]
	v_min_i32_e32 v112, 0x8000, v118
	v_ashrrev_i32_e32 v112, 12, v112
	v_mul_hi_i32_i24_e32 v113, 0x6000, v112
	v_mul_i32_i24_e32 v112, 0x6000, v112
	v_lshl_add_u64 v[112:113], s[0:1], 0, v[112:113]
	v_lshl_add_u64 v[114:115], v[112:113], 0, v[96:97]
	v_lshl_add_u64 v[112:113], v[116:117], 0, v[96:97]
	ds_read_b128 v[116:119], v146 offset:2176
	global_load_dwordx4 v[120:123], v[110:111], off
	global_load_dwordx4 v[124:127], v[114:115], off
	s_waitcnt vmcnt(0) lgkmcnt(0)
	v_pk_fma_f32 v[116:117], v[116:117], v[124:125], v[120:121]
	v_pk_fma_f32 v[118:119], v[118:119], v[126:127], v[122:123]
	v_or_b32_e32 v124, v176, v170
	global_store_dwordx4 v[112:113], v[116:119], off
	v_cmp_gt_i32_e32 vcc, s39, v124
	s_nop 0
	v_ashrrev_i32_e32 v116, 31, v124
	v_add_u32_e32 v118, 0xffff8000, v124
	v_cndmask_b32_e32 v117, 0, v116, vcc
	v_cndmask_b32_e32 v116, v118, v124, vcc
	v_cndmask_b32_e32 v119, v160, v161, vcc
	v_cndmask_b32_e32 v118, v162, v163, vcc
	v_lshlrev_b64 v[116:117], 12, v[116:117]
	v_lshl_add_u64 v[118:119], v[118:119], 0, v[116:117]
	v_cndmask_b32_e32 v121, v164, v165, vcc
	v_cndmask_b32_e32 v120, v166, v167, vcc
	v_lshl_add_u64 v[122:123], v[120:121], 0, v[116:117]
	v_lshl_add_u64 v[116:117], v[118:119], 0, v[96:97]
	v_min_i32_e32 v118, 0x8000, v124
	v_ashrrev_i32_e32 v118, 12, v118
	v_mul_hi_i32_i24_e32 v119, 0x6000, v118
	v_mul_i32_i24_e32 v118, 0x6000, v118
	v_lshl_add_u64 v[118:119], s[0:1], 0, v[118:119]
	v_lshl_add_u64 v[120:121], v[118:119], 0, v[96:97]
	v_lshl_add_u64 v[118:119], v[122:123], 0, v[96:97]
	ds_read_b128 v[122:125], v146 offset:3264
	global_load_dwordx4 v[126:129], v[116:117], off
	global_load_dwordx4 v[130:133], v[120:121], off
	s_waitcnt vmcnt(0) lgkmcnt(0)
	v_pk_fma_f32 v[122:123], v[122:123], v[130:131], v[126:127]
	v_pk_fma_f32 v[124:125], v[124:125], v[132:133], v[128:129]
	v_or_b32_e32 v130, v176, v171
	global_store_dwordx4 v[118:119], v[122:125], off
	v_cmp_gt_i32_e32 vcc, s39, v130
	s_nop 0
	v_ashrrev_i32_e32 v122, 31, v130
	v_add_u32_e32 v124, 0xffff8000, v130
	v_cndmask_b32_e32 v123, 0, v122, vcc
	v_cndmask_b32_e32 v122, v124, v130, vcc
	v_cndmask_b32_e32 v125, v160, v161, vcc
	v_cndmask_b32_e32 v124, v162, v163, vcc
	v_lshlrev_b64 v[122:123], 12, v[122:123]
	v_lshl_add_u64 v[124:125], v[124:125], 0, v[122:123]
	v_cndmask_b32_e32 v127, v164, v165, vcc
	v_cndmask_b32_e32 v126, v166, v167, vcc
	v_lshl_add_u64 v[128:129], v[126:127], 0, v[122:123]
	v_lshl_add_u64 v[122:123], v[124:125], 0, v[96:97]
	v_min_i32_e32 v124, 0x8000, v130
	v_ashrrev_i32_e32 v124, 12, v124
	v_mul_hi_i32_i24_e32 v125, 0x6000, v124
	v_mul_i32_i24_e32 v124, 0x6000, v124
	v_lshl_add_u64 v[124:125], s[0:1], 0, v[124:125]
	v_lshl_add_u64 v[126:127], v[124:125], 0, v[96:97]
	v_lshl_add_u64 v[124:125], v[128:129], 0, v[96:97]
	ds_read_b128 v[128:131], v146 offset:4352
	global_load_dwordx4 v[132:135], v[122:123], off
	global_load_dwordx4 v[136:139], v[126:127], off
	s_waitcnt vmcnt(0) lgkmcnt(0)
	v_pk_fma_f32 v[128:129], v[128:129], v[136:137], v[132:133]
	v_pk_fma_f32 v[130:131], v[130:131], v[138:139], v[134:135]
	v_or_b32_e32 v136, v176, v172
	global_store_dwordx4 v[124:125], v[128:131], off
	v_cmp_gt_i32_e32 vcc, s39, v136
	s_nop 0
	v_ashrrev_i32_e32 v128, 31, v136
	v_add_u32_e32 v130, 0xffff8000, v136
	v_cndmask_b32_e32 v129, 0, v128, vcc
	v_cndmask_b32_e32 v128, v130, v136, vcc
	v_cndmask_b32_e32 v131, v160, v161, vcc
	v_cndmask_b32_e32 v130, v162, v163, vcc
	v_lshlrev_b64 v[128:129], 12, v[128:129]
	v_lshl_add_u64 v[130:131], v[130:131], 0, v[128:129]
	v_cndmask_b32_e32 v133, v164, v165, vcc
	v_cndmask_b32_e32 v132, v166, v167, vcc
	v_lshl_add_u64 v[134:135], v[132:133], 0, v[128:129]
	v_lshl_add_u64 v[128:129], v[130:131], 0, v[96:97]
	v_min_i32_e32 v130, 0x8000, v136
	v_ashrrev_i32_e32 v130, 12, v130
	v_mul_hi_i32_i24_e32 v131, 0x6000, v130
	v_mul_i32_i24_e32 v130, 0x6000, v130
	v_lshl_add_u64 v[130:131], s[0:1], 0, v[130:131]
	v_lshl_add_u64 v[132:133], v[130:131], 0, v[96:97]
	v_lshl_add_u64 v[130:131], v[134:135], 0, v[96:97]
	ds_read_b128 v[134:137], v146 offset:5440
	global_load_dwordx4 v[138:141], v[128:129], off
	global_load_dwordx4 v[142:145], v[132:133], off
	s_waitcnt vmcnt(0) lgkmcnt(0)
	v_pk_fma_f32 v[134:135], v[134:135], v[142:143], v[138:139]
	v_pk_fma_f32 v[136:137], v[136:137], v[144:145], v[140:141]
	v_or_b32_e32 v142, v176, v173
	global_store_dwordx4 v[130:131], v[134:137], off
	v_cmp_gt_i32_e32 vcc, s39, v142
	s_nop 0
	v_ashrrev_i32_e32 v134, 31, v142
	v_add_u32_e32 v136, 0xffff8000, v142
	v_cndmask_b32_e32 v135, 0, v134, vcc
	v_cndmask_b32_e32 v134, v136, v142, vcc
	v_cndmask_b32_e32 v137, v160, v161, vcc
	v_cndmask_b32_e32 v136, v162, v163, vcc
	v_lshlrev_b64 v[134:135], 12, v[134:135]
	v_lshl_add_u64 v[136:137], v[136:137], 0, v[134:135]
	v_cndmask_b32_e32 v139, v164, v165, vcc
	v_cndmask_b32_e32 v138, v166, v167, vcc
	v_lshl_add_u64 v[140:141], v[138:139], 0, v[134:135]
	v_lshl_add_u64 v[134:135], v[136:137], 0, v[96:97]
	v_min_i32_e32 v136, 0x8000, v142
	v_ashrrev_i32_e32 v136, 12, v136
	v_mul_hi_i32_i24_e32 v137, 0x6000, v136
	v_mul_i32_i24_e32 v136, 0x6000, v136
	v_lshl_add_u64 v[136:137], s[0:1], 0, v[136:137]
	v_lshl_add_u64 v[138:139], v[136:137], 0, v[96:97]
	v_lshl_add_u64 v[136:137], v[140:141], 0, v[96:97]
	ds_read_b128 v[140:143], v146 offset:6528
	global_load_dwordx4 v[184:187], v[134:135], off
	global_load_dwordx4 v[196:199], v[138:139], off
	v_cmp_gt_i32_e32 vcc, s39, v181
	s_waitcnt vmcnt(0) lgkmcnt(0)
	v_pk_fma_f32 v[140:141], v[140:141], v[196:197], v[184:185]
	v_pk_fma_f32 v[142:143], v[142:143], v[198:199], v[186:187]
	global_store_dwordx4 v[136:137], v[140:143], off
	v_cndmask_b32_e32 v145, v164, v165, vcc
	v_cndmask_b32_e32 v144, v166, v167, vcc
	v_ashrrev_i32_e32 v140, 31, v181
	v_add_u32_e32 v142, 0xffff8000, v181
	v_cndmask_b32_e32 v141, 0, v140, vcc
	v_cndmask_b32_e32 v140, v142, v181, vcc
	v_cndmask_b32_e32 v143, v160, v161, vcc
	v_cndmask_b32_e32 v142, v162, v163, vcc
	v_lshlrev_b64 v[140:141], 12, v[140:141]
	v_lshl_add_u64 v[142:143], v[142:143], 0, v[140:141]
	v_lshl_add_u64 v[184:185], v[144:145], 0, v[140:141]
	v_lshl_add_u64 v[140:141], v[142:143], 0, v[96:97]
	v_min_i32_e32 v142, 0x8000, v181
	v_ashrrev_i32_e32 v142, 12, v142
	v_mul_hi_i32_i24_e32 v143, 0x6000, v142
	v_mul_i32_i24_e32 v142, 0x6000, v142
	v_lshl_add_u64 v[142:143], s[0:1], 0, v[142:143]
	v_lshl_add_u64 v[144:145], v[142:143], 0, v[96:97]
	v_lshl_add_u64 v[142:143], v[184:185], 0, v[96:97]
	ds_read_b128 v[184:187], v146 offset:7616
	global_load_dwordx4 v[196:199], v[140:141], off
	global_load_dwordx4 v[200:203], v[144:145], off
	s_waitcnt vmcnt(0) lgkmcnt(0)
	v_pk_fma_f32 v[184:185], v[184:185], v[200:201], v[196:197]
	v_pk_fma_f32 v[186:187], v[186:187], v[202:203], v[198:199]
	global_store_dwordx4 v[142:143], v[184:187], off
	s_waitcnt lgkmcnt(0)
	ds_write2_b32 v147, v80, v81 offset1:68
	ds_write2_b32 v148, v64, v65 offset0:32 offset1:100
	ds_write2_b32 v147, v82, v83 offset0:136 offset1:204
	ds_write2_b32 v148, v66, v67 offset0:168 offset1:236
	ds_write2_b32 v149, v84, v85 offset0:32 offset1:100
	ds_write2_b32 v150, v68, v69 offset0:64 offset1:132
	ds_write2_b32 v149, v86, v87 offset0:168 offset1:236
	ds_write2_b32 v151, v70, v71 offset0:72 offset1:140
	ds_write2_b32 v152, v88, v89 offset0:64 offset1:132
	ds_write2_b32 v153, v72, v73 offset0:96 offset1:164
	ds_write2_b32 v154, v90, v91 offset0:72 offset1:140
	ds_write2_b32 v155, v74, v75 offset0:104 offset1:172
	ds_write2_b32 v156, v92, v93 offset0:96 offset1:164
	ds_write2_b32 v157, v76, v77 offset0:128 offset1:196
	ds_write2_b32 v158, v94, v95 offset0:104 offset1:172
	ds_write2_b32 v159, v78, v79 offset0:8 offset1:76
	s_waitcnt lgkmcnt(0)
	ds_read_b128 v[64:67], v146
	global_load_dwordx4 v[68:71], v[98:99], off offset:256
	global_load_dwordx4 v[72:75], v[102:103], off offset:256
	s_waitcnt vmcnt(0) lgkmcnt(0)
	v_pk_fma_f32 v[64:65], v[64:65], v[72:73], v[68:69]
	v_pk_fma_f32 v[66:67], v[66:67], v[74:75], v[70:71]
	global_store_dwordx4 v[100:101], v[64:67], off offset:256
	ds_read_b128 v[64:67], v146 offset:1088
	global_load_dwordx4 v[68:71], v[106:107], off offset:256
	global_load_dwordx4 v[72:75], v[108:109], off offset:256
	s_waitcnt vmcnt(0) lgkmcnt(0)
	v_pk_fma_f32 v[64:65], v[64:65], v[72:73], v[68:69]
	v_pk_fma_f32 v[66:67], v[66:67], v[74:75], v[70:71]
	global_store_dwordx4 v[104:105], v[64:67], off offset:256
	ds_read_b128 v[64:67], v146 offset:2176
	global_load_dwordx4 v[68:71], v[110:111], off offset:256
	global_load_dwordx4 v[72:75], v[114:115], off offset:256
	s_waitcnt vmcnt(0) lgkmcnt(0)
	v_pk_fma_f32 v[64:65], v[64:65], v[72:73], v[68:69]
	v_pk_fma_f32 v[66:67], v[66:67], v[74:75], v[70:71]
	global_store_dwordx4 v[112:113], v[64:67], off offset:256
	ds_read_b128 v[64:67], v146 offset:3264
	global_load_dwordx4 v[68:71], v[116:117], off offset:256
	global_load_dwordx4 v[72:75], v[120:121], off offset:256
	s_waitcnt vmcnt(0) lgkmcnt(0)
	v_pk_fma_f32 v[64:65], v[64:65], v[72:73], v[68:69]
	v_pk_fma_f32 v[66:67], v[66:67], v[74:75], v[70:71]
	global_store_dwordx4 v[118:119], v[64:67], off offset:256
	ds_read_b128 v[64:67], v146 offset:4352
	global_load_dwordx4 v[68:71], v[122:123], off offset:256
	global_load_dwordx4 v[72:75], v[126:127], off offset:256
	s_waitcnt vmcnt(0) lgkmcnt(0)
	v_pk_fma_f32 v[64:65], v[64:65], v[72:73], v[68:69]
	v_pk_fma_f32 v[66:67], v[66:67], v[74:75], v[70:71]
	global_store_dwordx4 v[124:125], v[64:67], off offset:256
	ds_read_b128 v[64:67], v146 offset:5440
	global_load_dwordx4 v[68:71], v[128:129], off offset:256
	global_load_dwordx4 v[72:75], v[132:133], off offset:256
	s_waitcnt vmcnt(0) lgkmcnt(0)
	v_pk_fma_f32 v[64:65], v[64:65], v[72:73], v[68:69]
	v_pk_fma_f32 v[66:67], v[66:67], v[74:75], v[70:71]
	global_store_dwordx4 v[130:131], v[64:67], off offset:256
	ds_read_b128 v[64:67], v146 offset:6528
	global_load_dwordx4 v[68:71], v[134:135], off offset:256
	global_load_dwordx4 v[72:75], v[138:139], off offset:256
	s_waitcnt vmcnt(0) lgkmcnt(0)
	v_pk_fma_f32 v[64:65], v[64:65], v[72:73], v[68:69]
	v_pk_fma_f32 v[66:67], v[66:67], v[74:75], v[70:71]
	global_store_dwordx4 v[136:137], v[64:67], off offset:256
	ds_read_b128 v[64:67], v146 offset:7616
	global_load_dwordx4 v[68:71], v[140:141], off offset:256
	global_load_dwordx4 v[72:75], v[144:145], off offset:256
	s_waitcnt vmcnt(0) lgkmcnt(0)
	v_pk_fma_f32 v[64:65], v[64:65], v[72:73], v[68:69]
	v_pk_fma_f32 v[66:67], v[66:67], v[74:75], v[70:71]
	global_store_dwordx4 v[142:143], v[64:67], off offset:256
	v_or_b32_e32 v74, 32, v176
	s_waitcnt lgkmcnt(0)
	ds_write2_b32 v147, v48, v49 offset1:68
	ds_write2_b32 v148, v32, v33 offset0:32 offset1:100
	ds_write2_b32 v147, v50, v51 offset0:136 offset1:204
	ds_write2_b32 v148, v34, v35 offset0:168 offset1:236
	ds_write2_b32 v149, v52, v53 offset0:32 offset1:100
	ds_write2_b32 v150, v36, v37 offset0:64 offset1:132
	ds_write2_b32 v149, v54, v55 offset0:168 offset1:236
	ds_write2_b32 v151, v38, v39 offset0:72 offset1:140
	ds_write2_b32 v152, v56, v57 offset0:64 offset1:132
	ds_write2_b32 v153, v40, v41 offset0:96 offset1:164
	ds_write2_b32 v154, v58, v59 offset0:72 offset1:140
	ds_write2_b32 v155, v42, v43 offset0:104 offset1:172
	ds_write2_b32 v156, v60, v61 offset0:96 offset1:164
	ds_write2_b32 v157, v44, v45 offset0:128 offset1:196
	ds_write2_b32 v158, v62, v63 offset0:104 offset1:172
	ds_write2_b32 v159, v46, v47 offset0:8 offset1:76
	v_or_b32_e32 v40, v74, v175
	v_cmp_gt_i32_e32 vcc, s39, v40
	v_ashrrev_i32_e32 v32, 31, v40
	v_add_u32_e32 v34, 0xffff8000, v40
	v_cndmask_b32_e32 v33, 0, v32, vcc
	v_cndmask_b32_e32 v32, v34, v40, vcc
	v_cndmask_b32_e32 v35, v160, v161, vcc
	v_cndmask_b32_e32 v34, v162, v163, vcc
	v_lshlrev_b64 v[32:33], 12, v[32:33]
	v_lshl_add_u64 v[34:35], v[34:35], 0, v[32:33]
	v_cndmask_b32_e32 v37, v164, v165, vcc
	v_cndmask_b32_e32 v36, v166, v167, vcc
	v_lshl_add_u64 v[38:39], v[36:37], 0, v[32:33]
	v_lshl_add_u64 v[32:33], v[34:35], 0, v[96:97]
	v_min_i32_e32 v34, 0x8000, v40
	v_ashrrev_i32_e32 v34, 12, v34
	v_mul_hi_i32_i24_e32 v35, 0x6000, v34
	v_mul_i32_i24_e32 v34, 0x6000, v34
	s_waitcnt lgkmcnt(0)
	v_lshl_add_u64 v[34:35], s[0:1], 0, v[34:35]
	v_lshl_add_u64 v[36:37], v[34:35], 0, v[96:97]
	v_lshl_add_u64 v[34:35], v[38:39], 0, v[96:97]
	ds_read_b128 v[38:41], v146
	global_load_dwordx4 v[42:45], v[32:33], off
	global_load_dwordx4 v[46:49], v[36:37], off
	v_or_b32_e32 v75, v74, v173
	s_waitcnt vmcnt(0) lgkmcnt(0)
	v_pk_fma_f32 v[38:39], v[38:39], v[46:47], v[42:43]
	v_pk_fma_f32 v[40:41], v[40:41], v[48:49], v[44:45]
	v_or_b32_e32 v46, v74, v168
	global_store_dwordx4 v[34:35], v[38:41], off
	v_cmp_gt_i32_e32 vcc, s39, v46
	s_nop 0
	v_ashrrev_i32_e32 v38, 31, v46
	v_add_u32_e32 v40, 0xffff8000, v46
	v_cndmask_b32_e32 v39, 0, v38, vcc
	v_cndmask_b32_e32 v38, v40, v46, vcc
	v_cndmask_b32_e32 v41, v160, v161, vcc
	v_cndmask_b32_e32 v40, v162, v163, vcc
	v_lshlrev_b64 v[38:39], 12, v[38:39]
	v_lshl_add_u64 v[40:41], v[40:41], 0, v[38:39]
	v_cndmask_b32_e32 v43, v164, v165, vcc
	v_cndmask_b32_e32 v42, v166, v167, vcc
	v_lshl_add_u64 v[44:45], v[42:43], 0, v[38:39]
	v_lshl_add_u64 v[38:39], v[40:41], 0, v[96:97]
	v_min_i32_e32 v40, 0x8000, v46
	v_ashrrev_i32_e32 v40, 12, v40
	v_mul_hi_i32_i24_e32 v41, 0x6000, v40
	v_mul_i32_i24_e32 v40, 0x6000, v40
	v_lshl_add_u64 v[40:41], s[0:1], 0, v[40:41]
	v_lshl_add_u64 v[42:43], v[40:41], 0, v[96:97]
	v_lshl_add_u64 v[40:41], v[44:45], 0, v[96:97]
	ds_read_b128 v[44:47], v146 offset:1088
	global_load_dwordx4 v[48:51], v[38:39], off
	global_load_dwordx4 v[52:55], v[42:43], off
	s_waitcnt vmcnt(0) lgkmcnt(0)
	v_pk_fma_f32 v[44:45], v[44:45], v[52:53], v[48:49]
	v_pk_fma_f32 v[46:47], v[46:47], v[54:55], v[50:51]
	v_or_b32_e32 v52, v74, v169
	global_store_dwordx4 v[40:41], v[44:47], off
	v_cmp_gt_i32_e32 vcc, s39, v52
	s_nop 0
	v_ashrrev_i32_e32 v44, 31, v52
	v_add_u32_e32 v46, 0xffff8000, v52
	v_cndmask_b32_e32 v45, 0, v44, vcc
	v_cndmask_b32_e32 v44, v46, v52, vcc
	v_cndmask_b32_e32 v47, v160, v161, vcc
	v_cndmask_b32_e32 v46, v162, v163, vcc
	v_lshlrev_b64 v[44:45], 12, v[44:45]
	v_lshl_add_u64 v[46:47], v[46:47], 0, v[44:45]
	v_cndmask_b32_e32 v49, v164, v165, vcc
	v_cndmask_b32_e32 v48, v166, v167, vcc
	v_lshl_add_u64 v[50:51], v[48:49], 0, v[44:45]
	v_lshl_add_u64 v[44:45], v[46:47], 0, v[96:97]
	v_min_i32_e32 v46, 0x8000, v52
	v_ashrrev_i32_e32 v46, 12, v46
	v_mul_hi_i32_i24_e32 v47, 0x6000, v46
	v_mul_i32_i24_e32 v46, 0x6000, v46
	v_lshl_add_u64 v[46:47], s[0:1], 0, v[46:47]
	v_lshl_add_u64 v[48:49], v[46:47], 0, v[96:97]
	v_lshl_add_u64 v[46:47], v[50:51], 0, v[96:97]
	ds_read_b128 v[50:53], v146 offset:2176
	global_load_dwordx4 v[54:57], v[44:45], off
	global_load_dwordx4 v[58:61], v[48:49], off
	s_waitcnt vmcnt(0) lgkmcnt(0)
	v_pk_fma_f32 v[50:51], v[50:51], v[58:59], v[54:55]
	v_pk_fma_f32 v[52:53], v[52:53], v[60:61], v[56:57]
	v_or_b32_e32 v58, v74, v170
	global_store_dwordx4 v[46:47], v[50:53], off
	v_cmp_gt_i32_e32 vcc, s39, v58
	s_nop 0
	v_ashrrev_i32_e32 v50, 31, v58
	v_add_u32_e32 v52, 0xffff8000, v58
	v_cndmask_b32_e32 v51, 0, v50, vcc
	v_cndmask_b32_e32 v50, v52, v58, vcc
	v_cndmask_b32_e32 v53, v160, v161, vcc
	v_cndmask_b32_e32 v52, v162, v163, vcc
	v_lshlrev_b64 v[50:51], 12, v[50:51]
	v_lshl_add_u64 v[52:53], v[52:53], 0, v[50:51]
	v_cndmask_b32_e32 v55, v164, v165, vcc
	v_cndmask_b32_e32 v54, v166, v167, vcc
	v_lshl_add_u64 v[56:57], v[54:55], 0, v[50:51]
	v_lshl_add_u64 v[50:51], v[52:53], 0, v[96:97]
	v_min_i32_e32 v52, 0x8000, v58
	v_ashrrev_i32_e32 v52, 12, v52
	v_mul_hi_i32_i24_e32 v53, 0x6000, v52
	v_mul_i32_i24_e32 v52, 0x6000, v52
	v_lshl_add_u64 v[52:53], s[0:1], 0, v[52:53]
	v_lshl_add_u64 v[54:55], v[52:53], 0, v[96:97]
	v_lshl_add_u64 v[52:53], v[56:57], 0, v[96:97]
	ds_read_b128 v[56:59], v146 offset:3264
	global_load_dwordx4 v[60:63], v[50:51], off
	global_load_dwordx4 v[64:67], v[54:55], off
	s_waitcnt vmcnt(0) lgkmcnt(0)
	v_pk_fma_f32 v[56:57], v[56:57], v[64:65], v[60:61]
	v_pk_fma_f32 v[58:59], v[58:59], v[66:67], v[62:63]
	v_or_b32_e32 v64, v74, v171
	global_store_dwordx4 v[52:53], v[56:59], off
	v_cmp_gt_i32_e32 vcc, s39, v64
	s_nop 0
	v_ashrrev_i32_e32 v56, 31, v64
	v_add_u32_e32 v58, 0xffff8000, v64
	v_cndmask_b32_e32 v57, 0, v56, vcc
	v_cndmask_b32_e32 v56, v58, v64, vcc
	v_cndmask_b32_e32 v59, v160, v161, vcc
	v_cndmask_b32_e32 v58, v162, v163, vcc
	v_lshlrev_b64 v[56:57], 12, v[56:57]
	v_lshl_add_u64 v[58:59], v[58:59], 0, v[56:57]
	v_cndmask_b32_e32 v61, v164, v165, vcc
	v_cndmask_b32_e32 v60, v166, v167, vcc
	v_lshl_add_u64 v[62:63], v[60:61], 0, v[56:57]
	v_lshl_add_u64 v[56:57], v[58:59], 0, v[96:97]
	v_min_i32_e32 v58, 0x8000, v64
	v_ashrrev_i32_e32 v58, 12, v58
	v_mul_hi_i32_i24_e32 v59, 0x6000, v58
	v_mul_i32_i24_e32 v58, 0x6000, v58
	v_lshl_add_u64 v[58:59], s[0:1], 0, v[58:59]
	v_lshl_add_u64 v[60:61], v[58:59], 0, v[96:97]
	v_lshl_add_u64 v[58:59], v[62:63], 0, v[96:97]
	ds_read_b128 v[62:65], v146 offset:4352
	global_load_dwordx4 v[66:69], v[56:57], off
	global_load_dwordx4 v[70:73], v[60:61], off
	s_waitcnt vmcnt(0) lgkmcnt(0)
	v_pk_fma_f32 v[62:63], v[62:63], v[70:71], v[66:67]
	v_pk_fma_f32 v[64:65], v[64:65], v[72:73], v[68:69]
	v_or_b32_e32 v70, v74, v172
	global_store_dwordx4 v[58:59], v[62:65], off
	v_cmp_gt_i32_e32 vcc, s39, v70
	s_nop 0
	v_ashrrev_i32_e32 v62, 31, v70
	v_add_u32_e32 v64, 0xffff8000, v70
	v_cndmask_b32_e32 v63, 0, v62, vcc
	v_cndmask_b32_e32 v62, v64, v70, vcc
	v_cndmask_b32_e32 v65, v160, v161, vcc
	v_cndmask_b32_e32 v64, v162, v163, vcc
	v_lshlrev_b64 v[62:63], 12, v[62:63]
	v_lshl_add_u64 v[64:65], v[64:65], 0, v[62:63]
	v_cndmask_b32_e32 v67, v164, v165, vcc
	v_cndmask_b32_e32 v66, v166, v167, vcc
	v_lshl_add_u64 v[68:69], v[66:67], 0, v[62:63]
	v_lshl_add_u64 v[62:63], v[64:65], 0, v[96:97]
	v_min_i32_e32 v64, 0x8000, v70
	v_ashrrev_i32_e32 v64, 12, v64
	v_mul_hi_i32_i24_e32 v65, 0x6000, v64
	v_mul_i32_i24_e32 v64, 0x6000, v64
	v_lshl_add_u64 v[64:65], s[0:1], 0, v[64:65]
	v_lshl_add_u64 v[66:67], v[64:65], 0, v[96:97]
	v_lshl_add_u64 v[64:65], v[68:69], 0, v[96:97]
	ds_read_b128 v[68:71], v146 offset:5440
	global_load_dwordx4 v[76:79], v[62:63], off
	global_load_dwordx4 v[80:83], v[66:67], off
	v_cmp_gt_i32_e32 vcc, s39, v75
	s_waitcnt vmcnt(0) lgkmcnt(0)
	v_pk_fma_f32 v[68:69], v[68:69], v[80:81], v[76:77]
	v_pk_fma_f32 v[70:71], v[70:71], v[82:83], v[78:79]
	global_store_dwordx4 v[64:65], v[68:71], off
	v_cndmask_b32_e32 v73, v164, v165, vcc
	v_cndmask_b32_e32 v72, v166, v167, vcc
	v_ashrrev_i32_e32 v68, 31, v75
	v_add_u32_e32 v70, 0xffff8000, v75
	v_cndmask_b32_e32 v69, 0, v68, vcc
	v_cndmask_b32_e32 v68, v70, v75, vcc
	v_cndmask_b32_e32 v71, v160, v161, vcc
	v_cndmask_b32_e32 v70, v162, v163, vcc
	v_lshlrev_b64 v[68:69], 12, v[68:69]
	v_lshl_add_u64 v[70:71], v[70:71], 0, v[68:69]
	v_lshl_add_u64 v[76:77], v[72:73], 0, v[68:69]
	v_lshl_add_u64 v[68:69], v[70:71], 0, v[96:97]
	v_min_i32_e32 v70, 0x8000, v75
	v_ashrrev_i32_e32 v70, 12, v70
	v_mul_hi_i32_i24_e32 v71, 0x6000, v70
	v_mul_i32_i24_e32 v70, 0x6000, v70
	v_lshl_add_u64 v[70:71], s[0:1], 0, v[70:71]
	v_lshl_add_u64 v[72:73], v[70:71], 0, v[96:97]
	v_lshl_add_u64 v[70:71], v[76:77], 0, v[96:97]
	ds_read_b128 v[76:79], v146 offset:6528
	global_load_dwordx4 v[80:83], v[68:69], off
	global_load_dwordx4 v[84:87], v[72:73], off
	s_waitcnt vmcnt(0) lgkmcnt(0)
	v_pk_fma_f32 v[76:77], v[76:77], v[84:85], v[80:81]
	v_pk_fma_f32 v[78:79], v[78:79], v[86:87], v[82:83]
	v_or_b32_e32 v82, v74, v174
	global_store_dwordx4 v[70:71], v[76:79], off
	v_cmp_gt_i32_e32 vcc, s39, v82
	v_ashrrev_i32_e32 v74, 31, v82
	v_add_u32_e32 v76, 0xffff8000, v82
	v_cndmask_b32_e32 v75, 0, v74, vcc
	v_cndmask_b32_e32 v74, v76, v82, vcc
	v_cndmask_b32_e32 v77, v160, v161, vcc
	v_cndmask_b32_e32 v76, v162, v163, vcc
	v_lshlrev_b64 v[74:75], 12, v[74:75]
	v_lshl_add_u64 v[76:77], v[76:77], 0, v[74:75]
	v_cndmask_b32_e32 v79, v164, v165, vcc
	v_cndmask_b32_e32 v78, v166, v167, vcc
	v_lshl_add_u64 v[80:81], v[78:79], 0, v[74:75]
	v_lshl_add_u64 v[74:75], v[76:77], 0, v[96:97]
	v_min_i32_e32 v76, 0x8000, v82
	v_ashrrev_i32_e32 v76, 12, v76
	v_mul_hi_i32_i24_e32 v77, 0x6000, v76
	v_mul_i32_i24_e32 v76, 0x6000, v76
	v_lshl_add_u64 v[76:77], s[0:1], 0, v[76:77]
	v_lshl_add_u64 v[78:79], v[76:77], 0, v[96:97]
	v_lshl_add_u64 v[76:77], v[80:81], 0, v[96:97]
	ds_read_b128 v[80:83], v146 offset:7616
	global_load_dwordx4 v[84:87], v[74:75], off
	global_load_dwordx4 v[88:91], v[78:79], off
	s_waitcnt vmcnt(0) lgkmcnt(0)
	v_pk_fma_f32 v[80:81], v[80:81], v[88:89], v[84:85]
	v_pk_fma_f32 v[82:83], v[82:83], v[90:91], v[86:87]
	global_store_dwordx4 v[76:77], v[80:83], off
	s_waitcnt lgkmcnt(0)
	ds_write2_b32 v147, v16, v17 offset1:68
	ds_write2_b32 v148, v0, v1 offset0:32 offset1:100
	ds_write2_b32 v147, v18, v19 offset0:136 offset1:204
	ds_write2_b32 v148, v2, v3 offset0:168 offset1:236
	ds_write2_b32 v149, v20, v21 offset0:32 offset1:100
	ds_write2_b32 v150, v4, v5 offset0:64 offset1:132
	ds_write2_b32 v149, v22, v23 offset0:168 offset1:236
	ds_write2_b32 v151, v6, v7 offset0:72 offset1:140
	ds_write2_b32 v152, v24, v25 offset0:64 offset1:132
	ds_write2_b32 v153, v8, v9 offset0:96 offset1:164
	ds_write2_b32 v154, v26, v27 offset0:72 offset1:140
	ds_write2_b32 v155, v10, v11 offset0:104 offset1:172
	ds_write2_b32 v156, v28, v29 offset0:96 offset1:164
	ds_write2_b32 v157, v12, v13 offset0:128 offset1:196
	ds_write2_b32 v158, v30, v31 offset0:104 offset1:172
	ds_write2_b32 v159, v14, v15 offset0:8 offset1:76
	s_waitcnt lgkmcnt(0)
	ds_read_b128 v[0:3], v146
	global_load_dwordx4 v[4:7], v[32:33], off offset:256
	global_load_dwordx4 v[8:11], v[36:37], off offset:256
	s_waitcnt vmcnt(0) lgkmcnt(0)
	v_pk_fma_f32 v[0:1], v[0:1], v[8:9], v[4:5]
	v_pk_fma_f32 v[2:3], v[2:3], v[10:11], v[6:7]
	global_store_dwordx4 v[34:35], v[0:3], off offset:256
	ds_read_b128 v[0:3], v146 offset:1088
	global_load_dwordx4 v[4:7], v[38:39], off offset:256
	global_load_dwordx4 v[8:11], v[42:43], off offset:256
	s_waitcnt vmcnt(0) lgkmcnt(0)
	v_pk_fma_f32 v[0:1], v[0:1], v[8:9], v[4:5]
	v_pk_fma_f32 v[2:3], v[2:3], v[10:11], v[6:7]
	global_store_dwordx4 v[40:41], v[0:3], off offset:256
	ds_read_b128 v[0:3], v146 offset:2176
	global_load_dwordx4 v[4:7], v[44:45], off offset:256
	global_load_dwordx4 v[8:11], v[48:49], off offset:256
	s_waitcnt vmcnt(0) lgkmcnt(0)
	v_pk_fma_f32 v[0:1], v[0:1], v[8:9], v[4:5]
	v_pk_fma_f32 v[2:3], v[2:3], v[10:11], v[6:7]
	global_store_dwordx4 v[46:47], v[0:3], off offset:256
	ds_read_b128 v[0:3], v146 offset:3264
	global_load_dwordx4 v[4:7], v[50:51], off offset:256
	global_load_dwordx4 v[8:11], v[54:55], off offset:256
	s_waitcnt vmcnt(0) lgkmcnt(0)
	v_pk_fma_f32 v[0:1], v[0:1], v[8:9], v[4:5]
	v_pk_fma_f32 v[2:3], v[2:3], v[10:11], v[6:7]
	global_store_dwordx4 v[52:53], v[0:3], off offset:256
	ds_read_b128 v[0:3], v146 offset:4352
	global_load_dwordx4 v[4:7], v[56:57], off offset:256
	global_load_dwordx4 v[8:11], v[60:61], off offset:256
	s_waitcnt vmcnt(0) lgkmcnt(0)
	v_pk_fma_f32 v[0:1], v[0:1], v[8:9], v[4:5]
	v_pk_fma_f32 v[2:3], v[2:3], v[10:11], v[6:7]
	global_store_dwordx4 v[58:59], v[0:3], off offset:256
	ds_read_b128 v[0:3], v146 offset:5440
	global_load_dwordx4 v[4:7], v[62:63], off offset:256
	global_load_dwordx4 v[8:11], v[66:67], off offset:256
	s_waitcnt vmcnt(0) lgkmcnt(0)
	v_pk_fma_f32 v[0:1], v[0:1], v[8:9], v[4:5]
	v_pk_fma_f32 v[2:3], v[2:3], v[10:11], v[6:7]
	global_store_dwordx4 v[64:65], v[0:3], off offset:256
	ds_read_b128 v[0:3], v146 offset:6528
	global_load_dwordx4 v[4:7], v[68:69], off offset:256
	global_load_dwordx4 v[8:11], v[72:73], off offset:256
	s_waitcnt vmcnt(0) lgkmcnt(0)
	v_pk_fma_f32 v[0:1], v[0:1], v[8:9], v[4:5]
	v_pk_fma_f32 v[2:3], v[2:3], v[10:11], v[6:7]
	global_store_dwordx4 v[70:71], v[0:3], off offset:256
	ds_read_b128 v[0:3], v146 offset:7616
	global_load_dwordx4 v[4:7], v[74:75], off offset:256
	global_load_dwordx4 v[8:11], v[78:79], off offset:256
	s_waitcnt vmcnt(0) lgkmcnt(0)
	v_pk_fma_f32 v[0:1], v[0:1], v[8:9], v[4:5]
	v_pk_fma_f32 v[2:3], v[2:3], v[10:11], v[6:7]
	global_store_dwordx4 v[76:77], v[0:3], off offset:256
	s_waitcnt lgkmcnt(0)
	s_barrier
	s_cbranch_scc1 .LBB0_923

.LBB0_1031:
	s_mul_hi_i32 s0, s2, 0x2e8ba2e9
	s_lshr_b32 s1, s0, 31
	s_ashr_i32 s0, s0, 6
	s_add_i32 s0, s0, s1
	s_lshl_b32 s1, s0, 3
	s_sub_i32 s7, s25, s1
	s_min_i32 s7, s7, 8
	s_abs_i32 s8, s7
	v_cvt_f32_u32_e32 v0, s8
	s_sub_i32 s11, 0, s8
	s_mulk_i32 s0, 0xfea0
	s_add_i32 s9, s0, s2
	v_rcp_iflag_f32_e32 v0, v0
	s_abs_i32 s0, s9
	s_xor_b32 s10, s9, s7
	s_ashr_i32 s10, s10, 31
	v_mul_f32_e32 v0, 0x4f7ffffe, v0
	v_cvt_u32_f32_e32 v0, v0
	v_mov_b32_e32 v237, v179
	v_readfirstlane_b32 s12, v0
	s_mul_i32 s11, s11, s12
	s_mul_hi_u32 s11, s12, s11
	s_add_i32 s12, s12, s11
	s_mul_hi_u32 s11, s0, s12
	s_mul_i32 s12, s11, s8
	s_sub_i32 s0, s0, s12
	s_add_i32 s13, s11, 1
	s_sub_i32 s12, s0, s8
	s_cmp_ge_u32 s0, s8
	s_cselect_b32 s11, s13, s11
	s_cselect_b32 s0, s12, s0
	s_add_i32 s12, s11, 1
	s_cmp_ge_u32 s0, s8
	s_cselect_b32 s0, s12, s11
	s_xor_b32 s0, s0, s10
	s_sub_i32 s0, s0, s10
	s_mul_i32 s7, s7, s0
	s_sub_i32 s7, s9, s7
	s_add_i32 s1, s1, s6
	v_ashrrev_i32_e32 v238, 6, v237
	s_add_i32 s7, s1, s7
	v_lshlrev_b32_e32 v0, 1, v238
	v_lshl_add_u32 v0, s7, 3, v0
	v_ashrrev_i32_e32 v1, 31, v0
	v_bfe_u32 v183, v237, 5, 1
	v_lshlrev_b64 v[0:1], 16, v[0:1]
	v_and_b32_e32 v239, 31, v237
	v_lshl_add_u64 v[0:1], s[64:65], 0, v[0:1]
	v_lshlrev_b32_e32 v176, 9, v183
	s_ashr_i32 s1, s0, 31
	v_lshl_add_u64 v[0:1], v[0:1], 0, v[176:177]
	v_lshlrev_b32_e32 v176, 4, v239
	v_ashrrev_i32_e32 v38, 2, v237
	s_lshl_b64 s[8:9], s[0:1], 18
	v_lshl_add_u64 v[184:185], v[0:1], 0, v[176:177]
	s_add_u32 s8, s4, s8
	v_lshlrev_b32_e32 v0, 5, v38
	v_lshlrev_b32_e32 v2, 3, v237
	s_addc_u32 s9, s5, s9
	v_ashrrev_i32_e32 v1, 31, v0
	v_and_b32_e32 v181, 24, v2
	v_lshl_add_u64 v[0:1], v[0:1], 1, s[8:9]
	v_lshlrev_b32_e32 v176, 1, v181
	v_lshl_add_u64 v[186:187], v[0:1], 0, v[176:177]
	s_movk_i32 s1, 0x2000
	v_add_co_u32_e32 v34, vcc, s1, v186
	v_mul_u32_u24_e32 v36, 40, v239
	s_nop 0
	v_addc_co_u32_e32 v35, vcc, 0, v187, vcc
	v_lshlrev_b32_e32 v37, 4, v183
	v_lshl_add_u32 v241, v36, 1, v37
	v_add_co_u32_e32 v36, vcc, s41, v184
	s_movk_i32 s8, 0x50
	s_nop 0
	v_addc_co_u32_e32 v37, vcc, 0, v185, vcc
	v_mad_u64_u32 v[188:189], s[8:9], v38, s8, v[176:177]
	v_and_b32_e32 v240, 63, v237
	v_mov_b32_e32 v176, 0x800
	v_lshl_add_u64 v[188:189], v[186:187], 0, v[176:177]
	v_bfe_u32 v247, v237, 4, 1
	v_lshlrev_b32_e32 v176, 9, v183
	v_lshl_add_u32 v176, v247, 8, v176
	v_lshl_add_u64 v[184:185], v[184:185], 0, v[176:177]
	v_mov_b32_e32 v176, s41
	v_lshl_add_u64 v[186:187], v[184:185], 0, v[176:177]
	v_lshrrev_b32_e32 v241, 2, v237
	v_bfe_u32 v247, v237, 4, 2
	v_lshlrev_b32_e32 v247, 1, v247
	v_mov_b32_e32 v176, 0x78
	v_lshrrev_b32_e32 v247, v247, v176
	v_and_b32_e32 v247, 3, v247
	v_and_b32_e32 v246, 3, v237
	v_xor_b32_e32 v247, v247, v246
	v_lshlrev_b32_e32 v247, 4, v247
	v_lshl_add_u32 v241, v241, 6, v247
	v_bfe_u32 v247, v237, 2, 2
	v_lshlrev_b32_e32 v247, 1, v247
	v_lshrrev_b32_e32 v247, v247, v176
	v_and_b32_e32 v247, 3, v247
	v_bfe_u32 v246, v237, 4, 2
	v_xor_b32_e32 v247, v247, v246
	v_lshlrev_b32_e32 v247, 4, v247
	v_and_b32_e32 v246, 15, v237
	v_lshl_add_u32 v246, v246, 6, v247
	s_mov_b32 s96, 0
	v_lshl_add_u64 v[166:167], v[188:189], 0, s[96:97]
	global_load_dwordx4 v[160:163], v[166:167], off offset:-2048
	global_load_dwordx4 v[164:167], v[166:167], off offset:2048
	s_movk_i32 s96, 0x2000
	v_lshl_add_u64 v[174:175], v[188:189], 0, s[96:97]
	global_load_dwordx4 v[168:171], v[174:175], off offset:-2048
	global_load_dwordx4 v[172:175], v[174:175], off offset:2048
	s_mov_b32 s96, 0
	v_lshl_add_u64 v[248:249], v[184:185], 0, s[96:97]
	v_lshl_add_u64 v[250:251], v[186:187], 0, s[96:97]
	global_load_dwordx4 v[128:131], v[248:249], off
	global_load_dwordx4 v[132:135], v[248:249], off offset:256
	global_load_dwordx4 v[136:139], v[250:251], off
	global_load_dwordx4 v[140:143], v[250:251], off offset:256
	s_movk_i32 s96, 0x800
	v_lshl_add_u64 v[248:249], v[184:185], 0, s[96:97]
	v_lshl_add_u64 v[250:251], v[186:187], 0, s[96:97]
	global_load_dwordx4 v[144:147], v[248:249], off
	global_load_dwordx4 v[148:151], v[248:249], off offset:256
	global_load_dwordx4 v[152:155], v[250:251], off
	global_load_dwordx4 v[156:159], v[250:251], off offset:256
	v_mov_b32_e32 v0, 0
	v_mov_b32_e32 v1, 0
	v_mov_b32_e32 v2, 0
	v_mov_b32_e32 v3, 0
	v_mov_b32_e32 v4, 0
	v_mov_b32_e32 v5, 0
	v_mov_b32_e32 v6, 0
	v_mov_b32_e32 v7, 0
	v_mov_b32_e32 v8, 0
	v_mov_b32_e32 v9, 0
	v_mov_b32_e32 v10, 0
	v_mov_b32_e32 v11, 0
	v_mov_b32_e32 v12, 0
	v_mov_b32_e32 v13, 0
	v_mov_b32_e32 v14, 0
	v_mov_b32_e32 v15, 0
	v_mov_b32_e32 v16, 0
	v_mov_b32_e32 v17, 0
	v_mov_b32_e32 v18, 0
	v_mov_b32_e32 v19, 0
	v_mov_b32_e32 v20, 0
	v_mov_b32_e32 v21, 0
	v_mov_b32_e32 v22, 0
	v_mov_b32_e32 v23, 0
	v_mov_b32_e32 v24, 0
	v_mov_b32_e32 v25, 0
	v_mov_b32_e32 v26, 0
	v_mov_b32_e32 v27, 0
	v_mov_b32_e32 v28, 0
	v_mov_b32_e32 v29, 0
	v_mov_b32_e32 v30, 0
	v_mov_b32_e32 v31, 0
	v_mov_b32_e32 v32, 0
	v_mov_b32_e32 v33, 0
	v_mov_b32_e32 v34, 0
	v_mov_b32_e32 v35, 0
	v_mov_b32_e32 v36, 0
	v_mov_b32_e32 v37, 0
	v_mov_b32_e32 v38, 0
	v_mov_b32_e32 v39, 0
	v_mov_b32_e32 v40, 0
	v_mov_b32_e32 v41, 0
	v_mov_b32_e32 v42, 0
	v_mov_b32_e32 v43, 0
	v_mov_b32_e32 v44, 0
	v_mov_b32_e32 v45, 0
	v_mov_b32_e32 v46, 0
	v_mov_b32_e32 v47, 0
	v_mov_b32_e32 v48, 0
	v_mov_b32_e32 v49, 0
	v_mov_b32_e32 v50, 0
	v_mov_b32_e32 v51, 0
	v_mov_b32_e32 v52, 0
	v_mov_b32_e32 v53, 0
	v_mov_b32_e32 v54, 0
	v_mov_b32_e32 v55, 0
	v_mov_b32_e32 v56, 0
	v_mov_b32_e32 v57, 0
	v_mov_b32_e32 v58, 0
	v_mov_b32_e32 v59, 0
	v_mov_b32_e32 v60, 0
	v_mov_b32_e32 v61, 0
	v_mov_b32_e32 v62, 0
	v_mov_b32_e32 v63, 0
	v_mov_b32_e32 v64, 0
	v_mov_b32_e32 v65, 0
	v_mov_b32_e32 v66, 0
	v_mov_b32_e32 v67, 0
	v_mov_b32_e32 v68, 0
	v_mov_b32_e32 v69, 0
	v_mov_b32_e32 v70, 0
	v_mov_b32_e32 v71, 0
	v_mov_b32_e32 v72, 0
	v_mov_b32_e32 v73, 0
	v_mov_b32_e32 v74, 0
	v_mov_b32_e32 v75, 0
	v_mov_b32_e32 v76, 0
	v_mov_b32_e32 v77, 0
	v_mov_b32_e32 v78, 0
	v_mov_b32_e32 v79, 0
	v_mov_b32_e32 v80, 0
	v_mov_b32_e32 v81, 0
	v_mov_b32_e32 v82, 0
	v_mov_b32_e32 v83, 0
	v_mov_b32_e32 v84, 0
	v_mov_b32_e32 v85, 0
	v_mov_b32_e32 v86, 0
	v_mov_b32_e32 v87, 0
	v_mov_b32_e32 v88, 0
	v_mov_b32_e32 v89, 0
	v_mov_b32_e32 v90, 0
	v_mov_b32_e32 v91, 0
	v_mov_b32_e32 v92, 0
	v_mov_b32_e32 v93, 0
	v_mov_b32_e32 v94, 0
	v_mov_b32_e32 v95, 0
	v_mov_b32_e32 v96, 0
	v_mov_b32_e32 v97, 0
	v_mov_b32_e32 v98, 0
	v_mov_b32_e32 v99, 0
	v_mov_b32_e32 v100, 0
	v_mov_b32_e32 v101, 0
	v_mov_b32_e32 v102, 0
	v_mov_b32_e32 v103, 0
	v_mov_b32_e32 v104, 0
	v_mov_b32_e32 v105, 0
	v_mov_b32_e32 v106, 0
	v_mov_b32_e32 v107, 0
	v_mov_b32_e32 v108, 0
	v_mov_b32_e32 v109, 0
	v_mov_b32_e32 v110, 0
	v_mov_b32_e32 v111, 0
	v_mov_b32_e32 v112, 0
	v_mov_b32_e32 v113, 0
	v_mov_b32_e32 v114, 0
	v_mov_b32_e32 v115, 0
	v_mov_b32_e32 v116, 0
	v_mov_b32_e32 v117, 0
	v_mov_b32_e32 v118, 0
	v_mov_b32_e32 v119, 0
	v_mov_b32_e32 v120, 0
	v_mov_b32_e32 v121, 0
	v_mov_b32_e32 v122, 0
	v_mov_b32_e32 v123, 0
	v_mov_b32_e32 v124, 0
	v_mov_b32_e32 v125, 0
	v_mov_b32_e32 v126, 0
	v_mov_b32_e32 v127, 0
	s_mov_b32 s1, 0
	s_waitcnt vmcnt(10)
	ds_write_b128 v241, v[160:163]
	ds_write_b128 v241, v[164:167] offset:4096
	s_waitcnt lgkmcnt(0)
	s_movk_i32 s96, 0x4000
	v_lshl_add_u64 v[166:167], v[188:189], 0, s[96:97]
	global_load_dwordx4 v[160:163], v[166:167], off offset:-2048
	global_load_dwordx4 v[164:167], v[166:167], off offset:2048
	s_barrier
.Lg16_gu_k:
	ds_read_b128 v[196:199], v246 offset:0
	ds_read_b128 v[200:203], v246 offset:1024
	ds_read_b128 v[204:207], v246 offset:2048
	ds_read_b128 v[242:245], v246 offset:3072
	s_add_i32 s8, s1, 2
	s_min_u32 s9, s8, 30
	s_lshl_b32 s96, s9, 11
	v_lshl_add_u64 v[248:249], v[184:185], 0, s[96:97]
	v_lshl_add_u64 v[250:251], v[186:187], 0, s[96:97]
	s_waitcnt vmcnt(6) lgkmcnt(3)
	v_mfma_f32_16x16x32_bf16 v[112:115], v[128:131], v[196:199], v[112:115]
	v_mfma_f32_16x16x32_bf16 v[120:123], v[132:135], v[196:199], v[120:123]
	v_mfma_f32_16x16x32_bf16 v[80:83], v[136:139], v[196:199], v[80:83]
	v_mfma_f32_16x16x32_bf16 v[88:91], v[140:143], v[196:199], v[88:91]
	ds_read_b128 v[196:199], v246 offset:4096
	s_waitcnt lgkmcnt(3)
	v_mfma_f32_16x16x32_bf16 v[116:119], v[128:131], v[200:203], v[116:119]
	v_mfma_f32_16x16x32_bf16 v[124:127], v[132:135], v[200:203], v[124:127]
	v_mfma_f32_16x16x32_bf16 v[84:87], v[136:139], v[200:203], v[84:87]
	v_mfma_f32_16x16x32_bf16 v[92:95], v[140:143], v[200:203], v[92:95]
	ds_read_b128 v[200:203], v246 offset:5120
	s_waitcnt lgkmcnt(3)
	v_mfma_f32_16x16x32_bf16 v[96:99], v[128:131], v[204:207], v[96:99]
	v_mfma_f32_16x16x32_bf16 v[104:107], v[132:135], v[204:207], v[104:107]
	v_mfma_f32_16x16x32_bf16 v[64:67], v[136:139], v[204:207], v[64:67]
	v_mfma_f32_16x16x32_bf16 v[72:75], v[140:143], v[204:207], v[72:75]
	ds_read_b128 v[204:207], v246 offset:6144
	s_waitcnt lgkmcnt(3)
	v_mfma_f32_16x16x32_bf16 v[100:103], v[128:131], v[242:245], v[100:103]
	v_mfma_f32_16x16x32_bf16 v[108:111], v[132:135], v[242:245], v[108:111]
	v_mfma_f32_16x16x32_bf16 v[68:71], v[136:139], v[242:245], v[68:71]
	v_mfma_f32_16x16x32_bf16 v[76:79], v[140:143], v[242:245], v[76:79]
	ds_read_b128 v[242:245], v246 offset:7168
	ds_write_b128 v241, v[168:171] offset:8192
	ds_write_b128 v241, v[172:175] offset:12288
	s_add_i32 s8, s1, 3
	s_min_u32 s9, s8, 31
	s_lshl_b32 s96, s9, 13
	v_lshl_add_u64 v[174:175], v[188:189], 0, s[96:97]
	global_load_dwordx4 v[168:171], v[174:175], off offset:-2048
	global_load_dwordx4 v[172:175], v[174:175], off offset:2048
	s_waitcnt lgkmcnt(5)
	v_mfma_f32_16x16x32_bf16 v[48:51], v[128:131], v[196:199], v[48:51]
	v_mfma_f32_16x16x32_bf16 v[56:59], v[132:135], v[196:199], v[56:59]
	v_mfma_f32_16x16x32_bf16 v[16:19], v[136:139], v[196:199], v[16:19]
	v_mfma_f32_16x16x32_bf16 v[24:27], v[140:143], v[196:199], v[24:27]
	s_waitcnt lgkmcnt(4)
	v_mfma_f32_16x16x32_bf16 v[52:55], v[128:131], v[200:203], v[52:55]
	v_mfma_f32_16x16x32_bf16 v[60:63], v[132:135], v[200:203], v[60:63]
	v_mfma_f32_16x16x32_bf16 v[20:23], v[136:139], v[200:203], v[20:23]
	v_mfma_f32_16x16x32_bf16 v[28:31], v[140:143], v[200:203], v[28:31]
	s_waitcnt lgkmcnt(3)
	v_mfma_f32_16x16x32_bf16 v[32:35], v[128:131], v[204:207], v[32:35]
	v_mfma_f32_16x16x32_bf16 v[40:43], v[132:135], v[204:207], v[40:43]
	v_mfma_f32_16x16x32_bf16 v[0:3], v[136:139], v[204:207], v[0:3]
	v_mfma_f32_16x16x32_bf16 v[8:11], v[140:143], v[204:207], v[8:11]
	s_waitcnt lgkmcnt(2)
	v_mfma_f32_16x16x32_bf16 v[36:39], v[128:131], v[242:245], v[36:39]
	v_mfma_f32_16x16x32_bf16 v[44:47], v[132:135], v[242:245], v[44:47]
	v_mfma_f32_16x16x32_bf16 v[4:7], v[136:139], v[242:245], v[4:7]
	v_mfma_f32_16x16x32_bf16 v[12:15], v[140:143], v[242:245], v[12:15]
	global_load_dwordx4 v[128:131], v[248:249], off
	global_load_dwordx4 v[132:135], v[248:249], off offset:256
	global_load_dwordx4 v[136:139], v[250:251], off
	global_load_dwordx4 v[140:143], v[250:251], off offset:256
	s_waitcnt lgkmcnt(0)
	s_barrier
	ds_read_b128 v[196:199], v246 offset:8192
	ds_read_b128 v[200:203], v246 offset:9216
	ds_read_b128 v[204:207], v246 offset:10240
	ds_read_b128 v[242:245], v246 offset:11264
	s_add_i32 s8, s1, 3
	s_min_u32 s9, s8, 31
	s_lshl_b32 s96, s9, 11
	v_lshl_add_u64 v[248:249], v[184:185], 0, s[96:97]
	v_lshl_add_u64 v[250:251], v[186:187], 0, s[96:97]
	s_waitcnt vmcnt(6) lgkmcnt(3)
	v_mfma_f32_16x16x32_bf16 v[112:115], v[144:147], v[196:199], v[112:115]
	v_mfma_f32_16x16x32_bf16 v[120:123], v[148:151], v[196:199], v[120:123]
	v_mfma_f32_16x16x32_bf16 v[80:83], v[152:155], v[196:199], v[80:83]
	v_mfma_f32_16x16x32_bf16 v[88:91], v[156:159], v[196:199], v[88:91]
	ds_read_b128 v[196:199], v246 offset:12288
	s_waitcnt lgkmcnt(3)
	v_mfma_f32_16x16x32_bf16 v[116:119], v[144:147], v[200:203], v[116:119]
	v_mfma_f32_16x16x32_bf16 v[124:127], v[148:151], v[200:203], v[124:127]
	v_mfma_f32_16x16x32_bf16 v[84:87], v[152:155], v[200:203], v[84:87]
	v_mfma_f32_16x16x32_bf16 v[92:95], v[156:159], v[200:203], v[92:95]
	ds_read_b128 v[200:203], v246 offset:13312
	s_waitcnt lgkmcnt(3)
	v_mfma_f32_16x16x32_bf16 v[96:99], v[144:147], v[204:207], v[96:99]
	v_mfma_f32_16x16x32_bf16 v[104:107], v[148:151], v[204:207], v[104:107]
	v_mfma_f32_16x16x32_bf16 v[64:67], v[152:155], v[204:207], v[64:67]
	v_mfma_f32_16x16x32_bf16 v[72:75], v[156:159], v[204:207], v[72:75]
	ds_read_b128 v[204:207], v246 offset:14336
	s_waitcnt lgkmcnt(3)
	v_mfma_f32_16x16x32_bf16 v[100:103], v[144:147], v[242:245], v[100:103]
	v_mfma_f32_16x16x32_bf16 v[108:111], v[148:151], v[242:245], v[108:111]
	v_mfma_f32_16x16x32_bf16 v[68:71], v[152:155], v[242:245], v[68:71]
	v_mfma_f32_16x16x32_bf16 v[76:79], v[156:159], v[242:245], v[76:79]
	ds_read_b128 v[242:245], v246 offset:15360
	ds_write_b128 v241, v[160:163] offset:0
	ds_write_b128 v241, v[164:167] offset:4096
	s_add_i32 s8, s1, 4
	s_min_u32 s9, s8, 30
	s_lshl_b32 s96, s9, 13
	v_lshl_add_u64 v[166:167], v[188:189], 0, s[96:97]
	global_load_dwordx4 v[160:163], v[166:167], off offset:-2048
	global_load_dwordx4 v[164:167], v[166:167], off offset:2048
	s_waitcnt lgkmcnt(5)
	v_mfma_f32_16x16x32_bf16 v[48:51], v[144:147], v[196:199], v[48:51]
	v_mfma_f32_16x16x32_bf16 v[56:59], v[148:151], v[196:199], v[56:59]
	v_mfma_f32_16x16x32_bf16 v[16:19], v[152:155], v[196:199], v[16:19]
	v_mfma_f32_16x16x32_bf16 v[24:27], v[156:159], v[196:199], v[24:27]
	s_waitcnt lgkmcnt(4)
	v_mfma_f32_16x16x32_bf16 v[52:55], v[144:147], v[200:203], v[52:55]
	v_mfma_f32_16x16x32_bf16 v[60:63], v[148:151], v[200:203], v[60:63]
	v_mfma_f32_16x16x32_bf16 v[20:23], v[152:155], v[200:203], v[20:23]
	v_mfma_f32_16x16x32_bf16 v[28:31], v[156:159], v[200:203], v[28:31]
	s_waitcnt lgkmcnt(3)
	v_mfma_f32_16x16x32_bf16 v[32:35], v[144:147], v[204:207], v[32:35]
	v_mfma_f32_16x16x32_bf16 v[40:43], v[148:151], v[204:207], v[40:43]
	v_mfma_f32_16x16x32_bf16 v[0:3], v[152:155], v[204:207], v[0:3]
	v_mfma_f32_16x16x32_bf16 v[8:11], v[156:159], v[204:207], v[8:11]
	s_waitcnt lgkmcnt(2)
	v_mfma_f32_16x16x32_bf16 v[36:39], v[144:147], v[242:245], v[36:39]
	v_mfma_f32_16x16x32_bf16 v[44:47], v[148:151], v[242:245], v[44:47]
	v_mfma_f32_16x16x32_bf16 v[4:7], v[152:155], v[242:245], v[4:7]
	v_mfma_f32_16x16x32_bf16 v[12:15], v[156:159], v[242:245], v[12:15]
	global_load_dwordx4 v[144:147], v[248:249], off
	global_load_dwordx4 v[148:151], v[248:249], off offset:256
	global_load_dwordx4 v[152:155], v[250:251], off
	global_load_dwordx4 v[156:159], v[250:251], off offset:256
	s_add_i32 s1, s1, 2
	s_cmp_lt_u32 s1, 32
	s_waitcnt lgkmcnt(0)
	s_barrier
	s_cbranch_scc1 .Lg16_gu_k
	s_nop 7
	v_permlane16_swap_b32_e32 v112, v116
	v_permlane16_swap_b32_e32 v113, v117
	v_permlane16_swap_b32_e32 v114, v118
	v_permlane16_swap_b32_e32 v115, v119
	v_permlane16_swap_b32_e32 v120, v124
	v_permlane16_swap_b32_e32 v121, v125
	v_permlane16_swap_b32_e32 v122, v126
	v_permlane16_swap_b32_e32 v123, v127
	v_permlane16_swap_b32_e32 v96, v100
	v_permlane16_swap_b32_e32 v97, v101
	v_permlane16_swap_b32_e32 v98, v102
	v_permlane16_swap_b32_e32 v99, v103
	v_permlane16_swap_b32_e32 v104, v108
	v_permlane16_swap_b32_e32 v105, v109
	v_permlane16_swap_b32_e32 v106, v110
	v_permlane16_swap_b32_e32 v107, v111
	v_permlane16_swap_b32_e32 v48, v52
	v_permlane16_swap_b32_e32 v49, v53
	v_permlane16_swap_b32_e32 v50, v54
	v_permlane16_swap_b32_e32 v51, v55
	v_permlane16_swap_b32_e32 v56, v60
	v_permlane16_swap_b32_e32 v57, v61
	v_permlane16_swap_b32_e32 v58, v62
	v_permlane16_swap_b32_e32 v59, v63
	v_permlane16_swap_b32_e32 v32, v36
	v_permlane16_swap_b32_e32 v33, v37
	v_permlane16_swap_b32_e32 v34, v38
	v_permlane16_swap_b32_e32 v35, v39
	v_permlane16_swap_b32_e32 v40, v44
	v_permlane16_swap_b32_e32 v41, v45
	v_permlane16_swap_b32_e32 v42, v46
	v_permlane16_swap_b32_e32 v43, v47
	v_permlane16_swap_b32_e32 v80, v84
	v_permlane16_swap_b32_e32 v81, v85
	v_permlane16_swap_b32_e32 v82, v86
	v_permlane16_swap_b32_e32 v83, v87
	v_permlane16_swap_b32_e32 v88, v92
	v_permlane16_swap_b32_e32 v89, v93
	v_permlane16_swap_b32_e32 v90, v94
	v_permlane16_swap_b32_e32 v91, v95
	v_permlane16_swap_b32_e32 v64, v68
	v_permlane16_swap_b32_e32 v65, v69
	v_permlane16_swap_b32_e32 v66, v70
	v_permlane16_swap_b32_e32 v67, v71
	v_permlane16_swap_b32_e32 v72, v76
	v_permlane16_swap_b32_e32 v73, v77
	v_permlane16_swap_b32_e32 v74, v78
	v_permlane16_swap_b32_e32 v75, v79
	v_permlane16_swap_b32_e32 v16, v20
	v_permlane16_swap_b32_e32 v17, v21
	v_permlane16_swap_b32_e32 v18, v22
	v_permlane16_swap_b32_e32 v19, v23
	v_permlane16_swap_b32_e32 v24, v28
	v_permlane16_swap_b32_e32 v25, v29
	v_permlane16_swap_b32_e32 v26, v30
	v_permlane16_swap_b32_e32 v27, v31
	v_permlane16_swap_b32_e32 v0, v4
	v_permlane16_swap_b32_e32 v1, v5
	v_permlane16_swap_b32_e32 v2, v6
	v_permlane16_swap_b32_e32 v3, v7
	v_permlane16_swap_b32_e32 v8, v12
	v_permlane16_swap_b32_e32 v9, v13
	v_permlane16_swap_b32_e32 v10, v14
	v_permlane16_swap_b32_e32 v11, v15
	v_permlane32_swap_b32_e32 v112, v116
	v_permlane32_swap_b32_e32 v113, v117
	v_permlane32_swap_b32_e32 v114, v118
	v_permlane32_swap_b32_e32 v115, v119
	v_permlane32_swap_b32_e32 v120, v124
	v_permlane32_swap_b32_e32 v121, v125
	v_permlane32_swap_b32_e32 v122, v126
	v_permlane32_swap_b32_e32 v123, v127
	v_permlane32_swap_b32_e32 v96, v100
	v_permlane32_swap_b32_e32 v97, v101
	v_permlane32_swap_b32_e32 v98, v102
	v_permlane32_swap_b32_e32 v99, v103
	v_permlane32_swap_b32_e32 v104, v108
	v_permlane32_swap_b32_e32 v105, v109
	v_permlane32_swap_b32_e32 v106, v110
	v_permlane32_swap_b32_e32 v107, v111
	v_permlane32_swap_b32_e32 v48, v52
	v_permlane32_swap_b32_e32 v49, v53
	v_permlane32_swap_b32_e32 v50, v54
	v_permlane32_swap_b32_e32 v51, v55
	v_permlane32_swap_b32_e32 v56, v60
	v_permlane32_swap_b32_e32 v57, v61
	v_permlane32_swap_b32_e32 v58, v62
	v_permlane32_swap_b32_e32 v59, v63
	v_permlane32_swap_b32_e32 v32, v36
	v_permlane32_swap_b32_e32 v33, v37
	v_permlane32_swap_b32_e32 v34, v38
	v_permlane32_swap_b32_e32 v35, v39
	v_permlane32_swap_b32_e32 v40, v44
	v_permlane32_swap_b32_e32 v41, v45
	v_permlane32_swap_b32_e32 v42, v46
	v_permlane32_swap_b32_e32 v43, v47
	v_permlane32_swap_b32_e32 v80, v84
	v_permlane32_swap_b32_e32 v81, v85
	v_permlane32_swap_b32_e32 v82, v86
	v_permlane32_swap_b32_e32 v83, v87
	v_permlane32_swap_b32_e32 v88, v92
	v_permlane32_swap_b32_e32 v89, v93
	v_permlane32_swap_b32_e32 v90, v94
	v_permlane32_swap_b32_e32 v91, v95
	v_permlane32_swap_b32_e32 v64, v68
	v_permlane32_swap_b32_e32 v65, v69
	v_permlane32_swap_b32_e32 v66, v70
	v_permlane32_swap_b32_e32 v67, v71
	v_permlane32_swap_b32_e32 v72, v76
	v_permlane32_swap_b32_e32 v73, v77
	v_permlane32_swap_b32_e32 v74, v78
	v_permlane32_swap_b32_e32 v75, v79
	v_permlane32_swap_b32_e32 v16, v20
	v_permlane32_swap_b32_e32 v17, v21
	v_permlane32_swap_b32_e32 v18, v22
	v_permlane32_swap_b32_e32 v19, v23
	v_permlane32_swap_b32_e32 v24, v28
	v_permlane32_swap_b32_e32 v25, v29
	v_permlane32_swap_b32_e32 v26, v30
	v_permlane32_swap_b32_e32 v27, v31
	v_permlane32_swap_b32_e32 v0, v4
	v_permlane32_swap_b32_e32 v1, v5
	v_permlane32_swap_b32_e32 v2, v6
	v_permlane32_swap_b32_e32 v3, v7
	v_permlane32_swap_b32_e32 v8, v12
	v_permlane32_swap_b32_e32 v9, v13
	v_permlane32_swap_b32_e32 v10, v14
	v_permlane32_swap_b32_e32 v11, v15
	s_waitcnt vmcnt(0)
	s_waitcnt vmcnt(0)
	v_mul_f32_e32 v133, 0xbfb8aa3b, v112
	v_exp_f32_e32 v133, v133
	s_movk_i32 s1, 0x2400
	v_mul_lo_u32 v128, v238, s1
	v_lshl_or_b32 v131, s0, 6, v181
	v_add_f32_e32 v133, 1.0, v133
	v_lshl_or_b32 v132, v239, 1, v128
	v_and_b32_e32 v129, 0xffffffc0, v237
	v_lshl_or_b32 v128, v181, 1, v128
	v_rcp_f32_e32 v135, v133
	s_nop 0
	v_mul_f32_e32 v112, v112, v135
	v_mul_f32_e32 v96, v96, v112
	v_cvt_pk_bf16_f32 v112, v96, s0
	s_movk_i32 s0, 0x240
	v_mad_u32_u24 v96, v183, s0, v132
	ds_write_b16 v96, v112
	v_mul_f32_e32 v112, 0xbfb8aa3b, v113
	v_exp_f32_e32 v112, v112
	v_lshl_add_u32 v130, s7, 8, v129
	v_lshrrev_b32_e32 v129, 2, v240
	v_mad_u32_u24 v128, v129, s42, v128
	v_add_f32_e32 v112, 1.0, v112
	v_rcp_f32_e32 v133, v112
	s_nop 0
	v_mul_f32_e32 v112, v113, v133
	v_mul_f32_e32 v97, v97, v112
	v_cvt_pk_bf16_f32 v97, v97, s0
	ds_write_b16 v96, v97 offset:144
	v_mul_f32_e32 v97, 0xbfb8aa3b, v114
	v_exp_f32_e32 v97, v97
	s_nop 0
	v_add_f32_e32 v97, 1.0, v97
	v_rcp_f32_e32 v113, v97
	s_nop 0
	v_mul_f32_e32 v97, v114, v113
	v_mul_f32_e32 v97, v98, v97
	v_cvt_pk_bf16_f32 v97, v97, s0
	ds_write_b16 v96, v97 offset:288
	v_mul_f32_e32 v97, 0xbfb8aa3b, v115
	v_exp_f32_e32 v97, v97
	s_nop 0
	v_add_f32_e32 v97, 1.0, v97
	v_rcp_f32_e32 v112, v97
	s_nop 0
	v_mul_f32_e32 v97, v115, v112
	v_mul_f32_e32 v97, v99, v97
	v_cvt_pk_bf16_f32 v97, v97, s0
	ds_write_b16 v96, v97 offset:432
	v_mul_f32_e32 v97, 0xbfb8aa3b, v116
	v_exp_f32_e32 v97, v97
	s_nop 0
	v_add_f32_e32 v97, 1.0, v97
	v_rcp_f32_e32 v99, v97
	s_nop 0
	v_mul_f32_e32 v97, v116, v99
	v_mul_f32_e32 v97, v100, v97
	v_cvt_pk_bf16_f32 v97, v97, s0
	ds_write_b16 v96, v97 offset:1152
	v_mul_f32_e32 v97, 0xbfb8aa3b, v117
	v_exp_f32_e32 v97, v97
	s_nop 0
	v_add_f32_e32 v97, 1.0, v97
	v_rcp_f32_e32 v99, v97
	s_nop 0
	v_mul_f32_e32 v97, v117, v99
	v_mul_f32_e32 v97, v101, v97
	v_cvt_pk_bf16_f32 v97, v97, s0
	ds_write_b16 v96, v97 offset:1296
	v_mul_f32_e32 v97, 0xbfb8aa3b, v118
	v_exp_f32_e32 v97, v97
	s_nop 0
	v_add_f32_e32 v97, 1.0, v97
	v_rcp_f32_e32 v99, v97
	s_nop 0
	v_mul_f32_e32 v97, v118, v99
	v_mul_f32_e32 v97, v102, v97
	v_cvt_pk_bf16_f32 v97, v97, s0
	ds_write_b16 v96, v97 offset:1440
	v_mul_f32_e32 v97, 0xbfb8aa3b, v119
	v_exp_f32_e32 v97, v97
	s_nop 0
	v_add_f32_e32 v97, 1.0, v97
	v_rcp_f32_e32 v99, v97
	s_nop 0
	v_mul_f32_e32 v97, v119, v99
	v_mul_f32_e32 v97, v103, v97
	v_cvt_pk_bf16_f32 v97, v97, s0
	ds_write_b16 v96, v97 offset:1584
	v_mul_f32_e32 v97, 0xbfb8aa3b, v120
	v_exp_f32_e32 v97, v97
	s_nop 0
	v_add_f32_e32 v97, 1.0, v97
	v_rcp_f32_e32 v99, v97
	s_nop 0
	v_mul_f32_e32 v97, v120, v99
	v_mul_f32_e32 v97, v104, v97
	v_cvt_pk_bf16_f32 v97, v97, s0
	ds_write_b16 v96, v97 offset:2304
	v_mul_f32_e32 v97, 0xbfb8aa3b, v121
	v_exp_f32_e32 v97, v97
	s_nop 0
	v_add_f32_e32 v97, 1.0, v97
	v_rcp_f32_e32 v99, v97
	s_nop 0
	v_mul_f32_e32 v97, v121, v99
	v_mul_f32_e32 v97, v105, v97
	v_cvt_pk_bf16_f32 v97, v97, s0
	ds_write_b16 v96, v97 offset:2448
	v_mul_f32_e32 v97, 0xbfb8aa3b, v122
	v_exp_f32_e32 v97, v97
	s_nop 0
	v_add_f32_e32 v97, 1.0, v97
	v_rcp_f32_e32 v99, v97
	s_nop 0
	v_mul_f32_e32 v97, v122, v99
	v_mul_f32_e32 v97, v106, v97
	v_cvt_pk_bf16_f32 v97, v97, s0
	ds_write_b16 v96, v97 offset:2592
	v_mul_f32_e32 v97, 0xbfb8aa3b, v123
	v_exp_f32_e32 v97, v97
	s_nop 0
	v_add_f32_e32 v97, 1.0, v97
	v_rcp_f32_e32 v99, v97
	s_nop 0
	v_mul_f32_e32 v97, v123, v99
	v_mul_f32_e32 v97, v107, v97
	v_cvt_pk_bf16_f32 v97, v97, s0
	ds_write_b16 v96, v97 offset:2736
	v_mul_f32_e32 v97, 0xbfb8aa3b, v124
	v_exp_f32_e32 v97, v97
	s_nop 0
	v_add_f32_e32 v97, 1.0, v97
	v_rcp_f32_e32 v99, v97
	s_nop 0
	v_mul_f32_e32 v97, v124, v99
	v_mul_f32_e32 v97, v108, v97
	v_cvt_pk_bf16_f32 v97, v97, s0
	ds_write_b16 v96, v97 offset:3456
	v_mul_f32_e32 v97, 0xbfb8aa3b, v125
	v_exp_f32_e32 v97, v97
	s_nop 0
	v_add_f32_e32 v97, 1.0, v97
	v_rcp_f32_e32 v99, v97
	s_nop 0
	v_mul_f32_e32 v97, v125, v99
	v_mul_f32_e32 v97, v109, v97
	v_cvt_pk_bf16_f32 v97, v97, s0
	ds_write_b16 v96, v97 offset:3600
	v_mul_f32_e32 v97, 0xbfb8aa3b, v126
	v_exp_f32_e32 v97, v97
	s_nop 0
	v_add_f32_e32 v97, 1.0, v97
	v_rcp_f32_e32 v99, v97
	s_nop 0
	v_mul_f32_e32 v97, v126, v99
	v_mul_f32_e32 v97, v110, v97
	v_cvt_pk_bf16_f32 v97, v97, s0
	ds_write_b16 v96, v97 offset:3744
	v_mul_f32_e32 v97, 0xbfb8aa3b, v127
	v_exp_f32_e32 v97, v97
	s_nop 0
	v_add_f32_e32 v97, 1.0, v97
	v_rcp_f32_e32 v99, v97
	s_nop 0
	v_mul_f32_e32 v97, v127, v99
	v_mul_f32_e32 v97, v111, v97
	v_cvt_pk_bf16_f32 v97, v97, s0
	ds_write_b16 v96, v97 offset:3888
	v_mul_f32_e32 v97, 0xbfb8aa3b, v80
	v_exp_f32_e32 v97, v97
	s_nop 0
	v_add_f32_e32 v97, 1.0, v97
	v_rcp_f32_e32 v99, v97
	s_nop 0
	v_mul_f32_e32 v80, v80, v99
	v_mul_f32_e32 v64, v64, v80
	v_cvt_pk_bf16_f32 v64, v64, s0
	ds_write_b16 v96, v64 offset:4608
	v_mul_f32_e32 v64, 0xbfb8aa3b, v81
	v_exp_f32_e32 v64, v64
	s_nop 0
	v_add_f32_e32 v64, 1.0, v64
	v_rcp_f32_e32 v97, v64
	s_nop 0
	v_mul_f32_e32 v64, v81, v97
	v_mul_f32_e32 v64, v65, v64
	v_cvt_pk_bf16_f32 v64, v64, s0
	ds_write_b16 v96, v64 offset:4752
	v_mul_f32_e32 v64, 0xbfb8aa3b, v82
	v_exp_f32_e32 v64, v64
	s_nop 0
	v_add_f32_e32 v64, 1.0, v64
	v_rcp_f32_e32 v80, v64
	s_nop 0
	v_mul_f32_e32 v64, v82, v80
	v_mul_f32_e32 v64, v66, v64
	v_cvt_pk_bf16_f32 v64, v64, s0
	ds_write_b16 v96, v64 offset:4896
	v_mul_f32_e32 v64, 0xbfb8aa3b, v83
	v_exp_f32_e32 v64, v64
	s_nop 0
	v_add_f32_e32 v64, 1.0, v64
	v_rcp_f32_e32 v66, v64
	s_nop 0
	v_mul_f32_e32 v64, v83, v66
	v_mul_f32_e32 v64, v67, v64
	v_cvt_pk_bf16_f32 v64, v64, s0
	ds_write_b16 v96, v64 offset:5040
	v_mul_f32_e32 v64, 0xbfb8aa3b, v84
	v_exp_f32_e32 v64, v64
	s_nop 0
	v_add_f32_e32 v64, 1.0, v64
	v_rcp_f32_e32 v66, v64
	s_nop 0
	v_mul_f32_e32 v64, v84, v66
	v_mul_f32_e32 v64, v68, v64
	v_cvt_pk_bf16_f32 v64, v64, s0
	ds_write_b16 v96, v64 offset:5760
	v_mul_f32_e32 v64, 0xbfb8aa3b, v85
	v_exp_f32_e32 v64, v64
	s_nop 0
	v_add_f32_e32 v64, 1.0, v64
	v_rcp_f32_e32 v66, v64
	s_nop 0
	v_mul_f32_e32 v64, v85, v66
	v_mul_f32_e32 v64, v69, v64
	v_cvt_pk_bf16_f32 v64, v64, s0
	ds_write_b16 v96, v64 offset:5904
	v_mul_f32_e32 v64, 0xbfb8aa3b, v86
	v_exp_f32_e32 v64, v64
	s_nop 0
	v_add_f32_e32 v64, 1.0, v64
	v_rcp_f32_e32 v66, v64
	s_nop 0
	v_mul_f32_e32 v64, v86, v66
	v_mul_f32_e32 v64, v70, v64
	v_cvt_pk_bf16_f32 v64, v64, s0
	ds_write_b16 v96, v64 offset:6048
	v_mul_f32_e32 v64, 0xbfb8aa3b, v87
	v_exp_f32_e32 v64, v64
	s_nop 0
	v_add_f32_e32 v64, 1.0, v64
	v_rcp_f32_e32 v66, v64
	s_nop 0
	v_mul_f32_e32 v64, v87, v66
	v_mul_f32_e32 v64, v71, v64
	v_cvt_pk_bf16_f32 v64, v64, s0
	ds_write_b16 v96, v64 offset:6192
	v_mul_f32_e32 v64, 0xbfb8aa3b, v88
	v_exp_f32_e32 v64, v64
	v_ashrrev_i32_e32 v71, 5, v130
	v_or_b32_e32 v70, 1, v71
	v_add_f32_e32 v64, 1.0, v64
	v_rcp_f32_e32 v66, v64
	s_nop 0
	v_mul_f32_e32 v64, v88, v66
	v_mul_f32_e32 v64, v72, v64
	v_cvt_pk_bf16_f32 v64, v64, s0
	ds_write_b16 v96, v64 offset:6912
	v_mul_f32_e32 v64, 0xbfb8aa3b, v89
	v_exp_f32_e32 v64, v64
	s_nop 0
	v_add_f32_e32 v64, 1.0, v64
	v_rcp_f32_e32 v66, v64
	s_nop 0
	v_mul_f32_e32 v64, v89, v66
	v_mul_f32_e32 v64, v73, v64
	v_cvt_pk_bf16_f32 v64, v64, s0
	ds_write_b16 v96, v64 offset:7056
	v_mul_f32_e32 v64, 0xbfb8aa3b, v90
	v_exp_f32_e32 v64, v64
	s_nop 0
	v_add_f32_e32 v64, 1.0, v64
	v_rcp_f32_e32 v66, v64
	s_nop 0
	v_mul_f32_e32 v64, v90, v66
	v_mul_f32_e32 v64, v74, v64
	v_cvt_pk_bf16_f32 v64, v64, s0
	ds_write_b16 v96, v64 offset:7200
	v_mul_f32_e32 v64, 0xbfb8aa3b, v91
	v_exp_f32_e32 v64, v64
	s_nop 0
	v_add_f32_e32 v64, 1.0, v64
	v_rcp_f32_e32 v66, v64
	s_nop 0
	v_mul_f32_e32 v64, v91, v66
	v_mul_f32_e32 v64, v75, v64
	v_cvt_pk_bf16_f32 v64, v64, s0
	ds_write_b16 v96, v64 offset:7344
	v_mul_f32_e32 v64, 0xbfb8aa3b, v92
	v_exp_f32_e32 v64, v64
	s_nop 0
	v_add_f32_e32 v64, 1.0, v64
	v_rcp_f32_e32 v66, v64
	s_nop 0
	v_mul_f32_e32 v64, v92, v66
	v_mul_f32_e32 v64, v76, v64
	v_cvt_pk_bf16_f32 v64, v64, s0
	ds_write_b16 v96, v64 offset:8064
	v_mul_f32_e32 v64, 0xbfb8aa3b, v93
	v_exp_f32_e32 v64, v64
	s_nop 0
	v_add_f32_e32 v64, 1.0, v64
	v_rcp_f32_e32 v66, v64
	s_nop 0
	v_mul_f32_e32 v64, v93, v66
	v_mul_f32_e32 v64, v77, v64
	v_cvt_pk_bf16_f32 v64, v64, s0
	ds_write_b16 v96, v64 offset:8208
	v_mul_f32_e32 v64, 0xbfb8aa3b, v94
	v_exp_f32_e32 v64, v64
	s_nop 0
	v_add_f32_e32 v64, 1.0, v64
	v_rcp_f32_e32 v66, v64
	s_nop 0
	v_mul_f32_e32 v64, v94, v66
	v_mul_f32_e32 v64, v78, v64
	v_cvt_pk_bf16_f32 v64, v64, s0
	ds_write_b16 v96, v64 offset:8352
	v_mul_f32_e32 v64, 0xbfb8aa3b, v95
	v_exp_f32_e32 v64, v64
	s_nop 0
	v_add_f32_e32 v64, 1.0, v64
	v_rcp_f32_e32 v66, v64
	s_nop 0
	v_mul_f32_e32 v64, v95, v66
	v_mul_f32_e32 v64, v79, v64
	v_cvt_pk_bf16_f32 v64, v64, s0
	ds_write_b16 v96, v64 offset:8496
	v_ashrrev_i32_e32 v68, 4, v131
	s_waitcnt lgkmcnt(0)
	v_ashrrev_i32_e32 v69, 31, v68
	ds_read_b128 v[72:75], v128
	v_mad_i64_i32 v[64:65], s[0:1], v71, s23, v[68:69]
	v_lshlrev_b64 v[64:65], 10, v[64:65]
	v_lshlrev_b32_e32 v66, 6, v181
	v_lshl_add_u64 v[64:65], s[66:67], 0, v[64:65]
	v_and_b32_e32 v176, 0x200, v66
	v_lshl_add_u64 v[76:77], v[64:65], 0, v[176:177]
	v_lshlrev_b32_e32 v66, 4, v129
	v_mov_b32_e32 v67, v177
	v_lshl_add_u64 v[64:65], v[76:77], 0, v[66:67]
	s_waitcnt lgkmcnt(0)
	global_store_dwordx4 v[64:65], v[72:75], off
	ds_read_b128 v[72:75], v128 offset:2304
	v_or_b32_e32 v64, 0x100, v66
	v_mov_b32_e32 v65, v177
	v_lshl_add_u64 v[76:77], v[76:77], 0, v[64:65]
	s_waitcnt lgkmcnt(0)
	global_store_dwordx4 v[76:77], v[72:75], off
	ds_read_b128 v[72:75], v128 offset:4608
	v_mad_i64_i32 v[76:77], s[0:1], v70, s23, v[68:69]
	v_lshlrev_b64 v[76:77], 10, v[76:77]
	v_lshl_add_u64 v[76:77], s[66:67], 0, v[76:77]
	v_lshl_add_u64 v[76:77], v[76:77], 0, v[176:177]
	v_lshl_add_u64 v[78:79], v[76:77], 0, v[66:67]
	v_mul_f32_e32 v69, 0xbfb8aa3b, v48
	s_waitcnt lgkmcnt(0)
	global_store_dwordx4 v[78:79], v[72:75], off
	ds_read_b128 v[72:75], v128 offset:6912
	v_exp_f32_e32 v69, v69
	v_lshl_add_u64 v[76:77], v[76:77], 0, v[64:65]
	v_add_f32_e32 v69, 1.0, v69
	s_waitcnt lgkmcnt(0)
	global_store_dwordx4 v[76:77], v[72:75], off
	s_waitcnt lgkmcnt(0)
	s_nop 1
	v_rcp_f32_e32 v73, v69
	s_nop 0
	v_mul_f32_e32 v48, v48, v73
	v_mul_f32_e32 v32, v32, v48
	v_cvt_pk_bf16_f32 v32, v32, s0
	ds_write_b16 v96, v32
	v_mul_f32_e32 v32, 0xbfb8aa3b, v49
	v_exp_f32_e32 v32, v32
	s_nop 0
	v_add_f32_e32 v32, 1.0, v32
	v_rcp_f32_e32 v69, v32
	s_nop 0
	v_mul_f32_e32 v32, v49, v69
	v_mul_f32_e32 v32, v33, v32
	v_cvt_pk_bf16_f32 v32, v32, s0
	ds_write_b16 v96, v32 offset:144
	v_mul_f32_e32 v32, 0xbfb8aa3b, v50
	v_exp_f32_e32 v32, v32
	s_nop 0
	v_add_f32_e32 v32, 1.0, v32
	v_rcp_f32_e32 v48, v32
	s_nop 0
	v_mul_f32_e32 v32, v50, v48
	v_mul_f32_e32 v32, v34, v32
	v_cvt_pk_bf16_f32 v32, v32, s0
	ds_write_b16 v96, v32 offset:288
	v_mul_f32_e32 v32, 0xbfb8aa3b, v51
	v_exp_f32_e32 v32, v32
	s_nop 0
	v_add_f32_e32 v32, 1.0, v32
	v_rcp_f32_e32 v34, v32
	s_nop 0
	v_mul_f32_e32 v32, v51, v34
	v_mul_f32_e32 v32, v35, v32
	v_cvt_pk_bf16_f32 v32, v32, s0
	ds_write_b16 v96, v32 offset:432
	v_mul_f32_e32 v32, 0xbfb8aa3b, v52
	v_exp_f32_e32 v32, v32
	s_nop 0
	v_add_f32_e32 v32, 1.0, v32
	v_rcp_f32_e32 v34, v32
	s_nop 0
	v_mul_f32_e32 v32, v52, v34
	v_mul_f32_e32 v32, v36, v32
	v_cvt_pk_bf16_f32 v32, v32, s0
	ds_write_b16 v96, v32 offset:1152
	v_mul_f32_e32 v32, 0xbfb8aa3b, v53
	v_exp_f32_e32 v32, v32
	s_nop 0
	v_add_f32_e32 v32, 1.0, v32
	v_rcp_f32_e32 v34, v32
	s_nop 0
	v_mul_f32_e32 v32, v53, v34
	v_mul_f32_e32 v32, v37, v32
	v_cvt_pk_bf16_f32 v32, v32, s0
	ds_write_b16 v96, v32 offset:1296
	v_mul_f32_e32 v32, 0xbfb8aa3b, v54
	v_exp_f32_e32 v32, v32
	s_nop 0
	v_add_f32_e32 v32, 1.0, v32
	v_rcp_f32_e32 v34, v32
	s_nop 0
	v_mul_f32_e32 v32, v54, v34
	v_mul_f32_e32 v32, v38, v32
	v_cvt_pk_bf16_f32 v32, v32, s0
	ds_write_b16 v96, v32 offset:1440
	v_mul_f32_e32 v32, 0xbfb8aa3b, v55
	v_exp_f32_e32 v32, v32
	s_nop 0
	v_add_f32_e32 v32, 1.0, v32
	v_rcp_f32_e32 v34, v32
	s_nop 0
	v_mul_f32_e32 v32, v55, v34
	v_mul_f32_e32 v32, v39, v32
	v_cvt_pk_bf16_f32 v32, v32, s0
	ds_write_b16 v96, v32 offset:1584
	v_mul_f32_e32 v32, 0xbfb8aa3b, v56
	v_exp_f32_e32 v32, v32
	s_nop 0
	v_add_f32_e32 v32, 1.0, v32
	v_rcp_f32_e32 v34, v32
	s_nop 0
	v_mul_f32_e32 v32, v56, v34
	v_mul_f32_e32 v32, v40, v32
	v_cvt_pk_bf16_f32 v32, v32, s0
	ds_write_b16 v96, v32 offset:2304
	v_mul_f32_e32 v32, 0xbfb8aa3b, v57
	v_exp_f32_e32 v32, v32
	s_nop 0
	v_add_f32_e32 v32, 1.0, v32
	v_rcp_f32_e32 v34, v32
	s_nop 0
	v_mul_f32_e32 v32, v57, v34
	v_mul_f32_e32 v32, v41, v32
	v_cvt_pk_bf16_f32 v32, v32, s0
	ds_write_b16 v96, v32 offset:2448
	v_mul_f32_e32 v32, 0xbfb8aa3b, v58
	v_exp_f32_e32 v32, v32
	s_nop 0
	v_add_f32_e32 v32, 1.0, v32
	v_rcp_f32_e32 v34, v32
	s_nop 0
	v_mul_f32_e32 v32, v58, v34
	v_mul_f32_e32 v32, v42, v32
	v_cvt_pk_bf16_f32 v32, v32, s0
	ds_write_b16 v96, v32 offset:2592
	v_mul_f32_e32 v32, 0xbfb8aa3b, v59
	v_exp_f32_e32 v32, v32
	s_nop 0
	v_add_f32_e32 v32, 1.0, v32
	v_rcp_f32_e32 v34, v32
	s_nop 0
	v_mul_f32_e32 v32, v59, v34
	v_mul_f32_e32 v32, v43, v32
	v_cvt_pk_bf16_f32 v32, v32, s0
	ds_write_b16 v96, v32 offset:2736
	v_mul_f32_e32 v32, 0xbfb8aa3b, v60
	v_exp_f32_e32 v32, v32
	s_nop 0
	v_add_f32_e32 v32, 1.0, v32
	v_rcp_f32_e32 v34, v32
	s_nop 0
	v_mul_f32_e32 v32, v60, v34
	v_mul_f32_e32 v32, v44, v32
	v_cvt_pk_bf16_f32 v32, v32, s0
	ds_write_b16 v96, v32 offset:3456
	v_mul_f32_e32 v32, 0xbfb8aa3b, v61
	v_exp_f32_e32 v32, v32
	s_nop 0
	v_add_f32_e32 v32, 1.0, v32
	v_rcp_f32_e32 v34, v32
	s_nop 0
	v_mul_f32_e32 v32, v61, v34
	v_mul_f32_e32 v32, v45, v32
	v_cvt_pk_bf16_f32 v32, v32, s0
	ds_write_b16 v96, v32 offset:3600
	v_mul_f32_e32 v32, 0xbfb8aa3b, v62
	v_exp_f32_e32 v32, v32
	s_nop 0
	v_add_f32_e32 v32, 1.0, v32
	v_rcp_f32_e32 v34, v32
	s_nop 0
	v_mul_f32_e32 v32, v62, v34
	v_mul_f32_e32 v32, v46, v32
	v_cvt_pk_bf16_f32 v32, v32, s0
	ds_write_b16 v96, v32 offset:3744
	v_mul_f32_e32 v32, 0xbfb8aa3b, v63
	v_exp_f32_e32 v32, v32
	s_nop 0
	v_add_f32_e32 v32, 1.0, v32
	v_rcp_f32_e32 v34, v32
	s_nop 0
	v_mul_f32_e32 v32, v63, v34
	v_mul_f32_e32 v32, v47, v32
	v_cvt_pk_bf16_f32 v32, v32, s0
	ds_write_b16 v96, v32 offset:3888
	v_mul_f32_e32 v32, 0xbfb8aa3b, v16
	v_exp_f32_e32 v32, v32
	s_nop 0
	v_add_f32_e32 v32, 1.0, v32
	v_rcp_f32_e32 v34, v32
	s_nop 0
	v_mul_f32_e32 v16, v16, v34
	v_mul_f32_e32 v0, v0, v16
	v_cvt_pk_bf16_f32 v0, v0, s0
	ds_write_b16 v96, v0 offset:4608
	v_mul_f32_e32 v0, 0xbfb8aa3b, v17
	v_exp_f32_e32 v0, v0
	s_nop 0
	v_add_f32_e32 v0, 1.0, v0
	v_rcp_f32_e32 v32, v0
	s_nop 0
	v_mul_f32_e32 v0, v17, v32
	v_mul_f32_e32 v0, v1, v0
	v_cvt_pk_bf16_f32 v0, v0, s0
	ds_write_b16 v96, v0 offset:4752
	v_mul_f32_e32 v0, 0xbfb8aa3b, v18
	v_exp_f32_e32 v0, v0
	s_nop 0
	v_add_f32_e32 v0, 1.0, v0
	v_rcp_f32_e32 v16, v0
	s_nop 0
	v_mul_f32_e32 v0, v18, v16
	v_mul_f32_e32 v0, v2, v0
	v_cvt_pk_bf16_f32 v0, v0, s0
	ds_write_b16 v96, v0 offset:4896
	v_mul_f32_e32 v0, 0xbfb8aa3b, v19
	v_exp_f32_e32 v0, v0
	s_nop 0
	v_add_f32_e32 v0, 1.0, v0
	v_rcp_f32_e32 v2, v0
	s_nop 0
	v_mul_f32_e32 v0, v19, v2
	v_mul_f32_e32 v0, v3, v0
	v_cvt_pk_bf16_f32 v0, v0, s0
	ds_write_b16 v96, v0 offset:5040
	v_mul_f32_e32 v0, 0xbfb8aa3b, v20
	v_exp_f32_e32 v0, v0
	s_nop 0
	v_add_f32_e32 v0, 1.0, v0
	v_rcp_f32_e32 v2, v0
	s_nop 0
	v_mul_f32_e32 v0, v20, v2
	v_mul_f32_e32 v0, v4, v0
	v_cvt_pk_bf16_f32 v0, v0, s0
	ds_write_b16 v96, v0 offset:5760
	v_mul_f32_e32 v0, 0xbfb8aa3b, v21
	v_exp_f32_e32 v0, v0
	s_nop 0
	v_add_f32_e32 v0, 1.0, v0
	v_rcp_f32_e32 v2, v0
	s_nop 0
	v_mul_f32_e32 v0, v21, v2
	v_mul_f32_e32 v0, v5, v0
	v_cvt_pk_bf16_f32 v0, v0, s0
	ds_write_b16 v96, v0 offset:5904
	v_mul_f32_e32 v0, 0xbfb8aa3b, v22
	v_exp_f32_e32 v0, v0
	s_nop 0
	v_add_f32_e32 v0, 1.0, v0
	v_rcp_f32_e32 v2, v0
	s_nop 0
	v_mul_f32_e32 v0, v22, v2
	v_mul_f32_e32 v0, v6, v0
	v_cvt_pk_bf16_f32 v0, v0, s0
	ds_write_b16 v96, v0 offset:6048
	v_mul_f32_e32 v0, 0xbfb8aa3b, v23
	v_exp_f32_e32 v0, v0
	s_nop 0
	v_add_f32_e32 v0, 1.0, v0
	v_rcp_f32_e32 v2, v0
	s_nop 0
	v_mul_f32_e32 v0, v23, v2
	v_mul_f32_e32 v0, v7, v0
	v_cvt_pk_bf16_f32 v0, v0, s0
	ds_write_b16 v96, v0 offset:6192
	v_mul_f32_e32 v0, 0xbfb8aa3b, v24
	v_exp_f32_e32 v0, v0
	s_nop 0
	v_add_f32_e32 v0, 1.0, v0
	v_rcp_f32_e32 v2, v0
	s_nop 0
	v_mul_f32_e32 v0, v24, v2
	v_mul_f32_e32 v0, v8, v0
	v_cvt_pk_bf16_f32 v0, v0, s0
	ds_write_b16 v96, v0 offset:6912
	v_mul_f32_e32 v0, 0xbfb8aa3b, v25
	v_exp_f32_e32 v0, v0
	s_nop 0
	v_add_f32_e32 v0, 1.0, v0
	v_rcp_f32_e32 v2, v0
	s_nop 0
	v_mul_f32_e32 v0, v25, v2
	v_mul_f32_e32 v0, v9, v0
	v_cvt_pk_bf16_f32 v0, v0, s0
	ds_write_b16 v96, v0 offset:7056
	v_mul_f32_e32 v0, 0xbfb8aa3b, v26
	v_exp_f32_e32 v0, v0
	s_nop 0
	v_add_f32_e32 v0, 1.0, v0
	v_rcp_f32_e32 v2, v0
	s_nop 0
	v_mul_f32_e32 v0, v26, v2
	v_mul_f32_e32 v0, v10, v0
	v_cvt_pk_bf16_f32 v0, v0, s0
	ds_write_b16 v96, v0 offset:7200
	v_mul_f32_e32 v0, 0xbfb8aa3b, v27
	v_exp_f32_e32 v0, v0
	s_nop 0
	v_add_f32_e32 v0, 1.0, v0
	v_rcp_f32_e32 v2, v0
	s_nop 0
	v_mul_f32_e32 v0, v27, v2
	v_mul_f32_e32 v0, v11, v0
	v_cvt_pk_bf16_f32 v0, v0, s0
	ds_write_b16 v96, v0 offset:7344
	v_mul_f32_e32 v0, 0xbfb8aa3b, v28
	v_exp_f32_e32 v0, v0
	s_nop 0
	v_add_f32_e32 v0, 1.0, v0
	v_rcp_f32_e32 v2, v0
	s_nop 0
	v_mul_f32_e32 v0, v28, v2
	v_mul_f32_e32 v0, v12, v0
	v_cvt_pk_bf16_f32 v0, v0, s0
	ds_write_b16 v96, v0 offset:8064
	v_mul_f32_e32 v0, 0xbfb8aa3b, v29
	v_exp_f32_e32 v0, v0
	s_nop 0
	v_add_f32_e32 v0, 1.0, v0
	v_rcp_f32_e32 v2, v0
	s_nop 0
	v_mul_f32_e32 v0, v29, v2
	v_mul_f32_e32 v0, v13, v0
	v_cvt_pk_bf16_f32 v0, v0, s0
	ds_write_b16 v96, v0 offset:8208
	v_mul_f32_e32 v0, 0xbfb8aa3b, v30
	v_exp_f32_e32 v0, v0
	s_nop 0
	v_add_f32_e32 v0, 1.0, v0
	v_rcp_f32_e32 v2, v0
	s_nop 0
	v_mul_f32_e32 v0, v30, v2
	v_mul_f32_e32 v0, v14, v0
	v_cvt_pk_bf16_f32 v0, v0, s0
	ds_write_b16 v96, v0 offset:8352
	v_mul_f32_e32 v0, 0xbfb8aa3b, v31
	v_exp_f32_e32 v0, v0
	s_nop 0
	v_add_f32_e32 v0, 1.0, v0
	v_rcp_f32_e32 v2, v0
	s_nop 0
	v_mul_f32_e32 v0, v31, v2
	v_mul_f32_e32 v0, v15, v0
	v_cvt_pk_bf16_f32 v0, v0, s0
	ds_write_b16 v96, v0 offset:8496
	v_or_b32_e32 v4, 2, v68
	s_waitcnt lgkmcnt(0)
	v_ashrrev_i32_e32 v5, 31, v4
	ds_read_b128 v[0:3], v128
	v_mad_i64_i32 v[6:7], s[0:1], v71, s23, v[4:5]
	v_lshlrev_b64 v[6:7], 10, v[6:7]
	v_lshl_add_u64 v[6:7], s[66:67], 0, v[6:7]
	v_lshl_add_u64 v[6:7], v[6:7], 0, v[176:177]
	v_lshl_add_u64 v[8:9], v[6:7], 0, v[66:67]
	s_waitcnt lgkmcnt(0)
	global_store_dwordx4 v[8:9], v[0:3], off
	ds_read_b128 v[0:3], v128 offset:2304
	v_lshl_add_u64 v[6:7], v[6:7], 0, v[64:65]
	v_mad_i64_i32 v[4:5], s[0:1], v70, s23, v[4:5]
	v_lshlrev_b64 v[4:5], 10, v[4:5]
	s_waitcnt lgkmcnt(0)
	global_store_dwordx4 v[6:7], v[0:3], off
	ds_read_b128 v[0:3], v128 offset:4608
	v_lshl_add_u64 v[4:5], s[66:67], 0, v[4:5]
	v_lshl_add_u64 v[4:5], v[4:5], 0, v[176:177]
	v_lshl_add_u64 v[6:7], v[4:5], 0, v[66:67]
	v_lshl_add_u64 v[4:5], v[4:5], 0, v[64:65]
	s_waitcnt lgkmcnt(0)
	global_store_dwordx4 v[6:7], v[0:3], off
	ds_read_b128 v[0:3], v128 offset:6912
	v_readlane_b32 s0, v254, 11
	s_add_i32 s2, s2, s0
	s_cmp_lt_i32 s2, s3
	s_waitcnt lgkmcnt(0)
	global_store_dwordx4 v[4:5], v[0:3], off
	s_waitcnt lgkmcnt(0)
	s_barrier
	s_cbranch_scc1 .LBB0_1031

.LBB0_1086:
	s_ashr_i32 s6, s2, 31
	s_lshr_b32 s6, s6, 26
	s_add_i32 s6, s2, s6
	s_ashr_i32 s7, s6, 6
	s_lshl_b32 s7, s7, 3
	s_sub_i32 s8, s25, s7
	s_min_i32 s8, s8, 8
	s_abs_i32 s9, s8
	v_cvt_f32_u32_e32 v0, s9
	s_sub_i32 s12, 0, s9
	s_andn2_b32 s6, s6, 63
	s_sub_i32 s10, s2, s6
	v_rcp_iflag_f32_e32 v0, v0
	s_abs_i32 s6, s10
	s_xor_b32 s11, s10, s8
	s_ashr_i32 s11, s11, 31
	v_mul_f32_e32 v0, 0x4f7ffffe, v0
	v_cvt_u32_f32_e32 v0, v0
	v_mov_b32_e32 v181, v179
	v_readfirstlane_b32 s13, v0
	s_mul_i32 s12, s12, s13
	s_mul_hi_u32 s12, s13, s12
	s_add_i32 s13, s13, s12
	s_mul_hi_u32 s12, s6, s13
	s_mul_i32 s13, s12, s9
	s_sub_i32 s6, s6, s13
	s_add_i32 s14, s12, 1
	s_sub_i32 s13, s6, s9
	s_cmp_ge_u32 s6, s9
	s_cselect_b32 s12, s14, s12
	s_cselect_b32 s6, s13, s6
	s_add_i32 s13, s12, 1
	s_cmp_ge_u32 s6, s9
	s_cselect_b32 s6, s13, s12
	s_xor_b32 s6, s6, s11
	s_sub_i32 s6, s6, s11
	s_mul_i32 s8, s8, s6
	s_add_i32 s7, s7, s5
	s_sub_i32 s8, s10, s8
	v_ashrrev_i32_e32 v237, 6, v181
	s_add_i32 s7, s7, s8
	v_lshlrev_b32_e32 v0, 1, v237
	v_bfe_u32 v183, v181, 5, 1
	v_lshl_add_u32 v2, s7, 3, v0
	v_mov_b64_e32 v[0:1], s[66:67]
	v_and_b32_e32 v238, 31, v181
	v_mad_i64_i32 v[0:1], s[8:9], v2, s24, v[0:1]
	v_lshlrev_b32_e32 v176, 9, v183
	v_lshl_add_u64 v[0:1], v[0:1], 0, v[176:177]
	v_lshlrev_b32_e32 v176, 4, v238
	v_ashrrev_i32_e32 v38, 2, v181
	s_mul_i32 s8, s6, 0xb0000
	v_lshl_add_u64 v[184:185], v[0:1], 0, v[176:177]
	s_mul_hi_i32 s9, s6, 0xb0000
	s_add_u32 s8, s3, s8
	v_lshlrev_b32_e32 v0, 5, v38
	s_addc_u32 s9, s4, s9
	v_ashrrev_i32_e32 v1, 31, v0
	v_lshlrev_b32_e32 v2, 4, v181
	v_lshl_add_u64 v[0:1], v[0:1], 1, s[8:9]
	v_and_b32_e32 v176, 48, v2
	v_lshl_add_u64 v[186:187], v[0:1], 0, v[176:177]
	s_movk_i32 s8, 0x2000
	v_add_co_u32_e32 v34, vcc, s8, v186
	v_mul_u32_u24_e32 v36, 40, v238
	s_nop 0
	v_addc_co_u32_e32 v35, vcc, 0, v187, vcc
	v_lshlrev_b32_e32 v37, 4, v183
	v_lshl_add_u32 v240, v36, 1, v37
	v_add_co_u32_e32 v36, vcc, s24, v184
	s_movk_i32 s9, 0x50
	s_nop 0
	v_addc_co_u32_e32 v37, vcc, 0, v185, vcc
	v_and_b32_e32 v239, 63, v181
	v_mov_b32_e32 v176, 0x800
	v_lshl_add_u64 v[188:189], v[186:187], 0, v[176:177]
	v_bfe_u32 v247, v181, 4, 1
	v_lshlrev_b32_e32 v176, 9, v183
	v_lshl_add_u32 v176, v247, 8, v176
	v_lshl_add_u64 v[184:185], v[184:185], 0, v[176:177]
	v_mov_b32_e32 v176, s24
	v_lshl_add_u64 v[186:187], v[184:185], 0, v[176:177]
	v_lshrrev_b32_e32 v241, 2, v181
	v_bfe_u32 v247, v181, 4, 2
	v_lshlrev_b32_e32 v247, 1, v247
	v_mov_b32_e32 v176, 0x78
	v_lshrrev_b32_e32 v247, v247, v176
	v_and_b32_e32 v247, 3, v247
	v_and_b32_e32 v246, 3, v181
	v_xor_b32_e32 v247, v247, v246
	v_lshlrev_b32_e32 v247, 4, v247
	v_lshl_add_u32 v241, v241, 6, v247
	v_bfe_u32 v247, v181, 2, 2
	v_lshlrev_b32_e32 v247, 1, v247
	v_lshrrev_b32_e32 v247, v247, v176
	v_and_b32_e32 v247, 3, v247
	v_bfe_u32 v246, v181, 4, 2
	v_xor_b32_e32 v247, v247, v246
	v_lshlrev_b32_e32 v247, 4, v247
	v_and_b32_e32 v246, 15, v181
	v_lshl_add_u32 v246, v246, 6, v247
	s_mov_b32 s96, 0
	v_lshl_add_u64 v[166:167], v[188:189], 0, s[96:97]
	global_load_dwordx4 v[160:163], v[166:167], off offset:-2048
	global_load_dwordx4 v[164:167], v[166:167], off offset:2048
	s_movk_i32 s96, 0x2000
	v_lshl_add_u64 v[174:175], v[188:189], 0, s[96:97]
	global_load_dwordx4 v[168:171], v[174:175], off offset:-2048
	global_load_dwordx4 v[172:175], v[174:175], off offset:2048
	s_mov_b32 s96, 0
	v_lshl_add_u64 v[248:249], v[184:185], 0, s[96:97]
	v_lshl_add_u64 v[250:251], v[186:187], 0, s[96:97]
	global_load_dwordx4 v[128:131], v[248:249], off
	global_load_dwordx4 v[132:135], v[248:249], off offset:256
	global_load_dwordx4 v[136:139], v[250:251], off
	global_load_dwordx4 v[140:143], v[250:251], off offset:256
	s_movk_i32 s96, 0x800
	v_lshl_add_u64 v[248:249], v[184:185], 0, s[96:97]
	v_lshl_add_u64 v[250:251], v[186:187], 0, s[96:97]
	global_load_dwordx4 v[144:147], v[248:249], off
	global_load_dwordx4 v[148:151], v[248:249], off offset:256
	global_load_dwordx4 v[152:155], v[250:251], off
	global_load_dwordx4 v[156:159], v[250:251], off offset:256
	v_mov_b32_e32 v0, 0
	v_mov_b32_e32 v1, 0
	v_mov_b32_e32 v2, 0
	v_mov_b32_e32 v3, 0
	v_mov_b32_e32 v4, 0
	v_mov_b32_e32 v5, 0
	v_mov_b32_e32 v6, 0
	v_mov_b32_e32 v7, 0
	v_mov_b32_e32 v8, 0
	v_mov_b32_e32 v9, 0
	v_mov_b32_e32 v10, 0
	v_mov_b32_e32 v11, 0
	v_mov_b32_e32 v12, 0
	v_mov_b32_e32 v13, 0
	v_mov_b32_e32 v14, 0
	v_mov_b32_e32 v15, 0
	v_mov_b32_e32 v16, 0
	v_mov_b32_e32 v17, 0
	v_mov_b32_e32 v18, 0
	v_mov_b32_e32 v19, 0
	v_mov_b32_e32 v20, 0
	v_mov_b32_e32 v21, 0
	v_mov_b32_e32 v22, 0
	v_mov_b32_e32 v23, 0
	v_mov_b32_e32 v24, 0
	v_mov_b32_e32 v25, 0
	v_mov_b32_e32 v26, 0
	v_mov_b32_e32 v27, 0
	v_mov_b32_e32 v28, 0
	v_mov_b32_e32 v29, 0
	v_mov_b32_e32 v30, 0
	v_mov_b32_e32 v31, 0
	v_mov_b32_e32 v32, 0
	v_mov_b32_e32 v33, 0
	v_mov_b32_e32 v34, 0
	v_mov_b32_e32 v35, 0
	v_mov_b32_e32 v36, 0
	v_mov_b32_e32 v37, 0
	v_mov_b32_e32 v38, 0
	v_mov_b32_e32 v39, 0
	v_mov_b32_e32 v40, 0
	v_mov_b32_e32 v41, 0
	v_mov_b32_e32 v42, 0
	v_mov_b32_e32 v43, 0
	v_mov_b32_e32 v44, 0
	v_mov_b32_e32 v45, 0
	v_mov_b32_e32 v46, 0
	v_mov_b32_e32 v47, 0
	v_mov_b32_e32 v48, 0
	v_mov_b32_e32 v49, 0
	v_mov_b32_e32 v50, 0
	v_mov_b32_e32 v51, 0
	v_mov_b32_e32 v52, 0
	v_mov_b32_e32 v53, 0
	v_mov_b32_e32 v54, 0
	v_mov_b32_e32 v55, 0
	v_mov_b32_e32 v56, 0
	v_mov_b32_e32 v57, 0
	v_mov_b32_e32 v58, 0
	v_mov_b32_e32 v59, 0
	v_mov_b32_e32 v60, 0
	v_mov_b32_e32 v61, 0
	v_mov_b32_e32 v62, 0
	v_mov_b32_e32 v63, 0
	v_mov_b32_e32 v64, 0
	v_mov_b32_e32 v65, 0
	v_mov_b32_e32 v66, 0
	v_mov_b32_e32 v67, 0
	v_mov_b32_e32 v68, 0
	v_mov_b32_e32 v69, 0
	v_mov_b32_e32 v70, 0
	v_mov_b32_e32 v71, 0
	v_mov_b32_e32 v72, 0
	v_mov_b32_e32 v73, 0
	v_mov_b32_e32 v74, 0
	v_mov_b32_e32 v75, 0
	v_mov_b32_e32 v76, 0
	v_mov_b32_e32 v77, 0
	v_mov_b32_e32 v78, 0
	v_mov_b32_e32 v79, 0
	v_mov_b32_e32 v80, 0
	v_mov_b32_e32 v81, 0
	v_mov_b32_e32 v82, 0
	v_mov_b32_e32 v83, 0
	v_mov_b32_e32 v84, 0
	v_mov_b32_e32 v85, 0
	v_mov_b32_e32 v86, 0
	v_mov_b32_e32 v87, 0
	v_mov_b32_e32 v88, 0
	v_mov_b32_e32 v89, 0
	v_mov_b32_e32 v90, 0
	v_mov_b32_e32 v91, 0
	v_mov_b32_e32 v92, 0
	v_mov_b32_e32 v93, 0
	v_mov_b32_e32 v94, 0
	v_mov_b32_e32 v95, 0
	v_mov_b32_e32 v96, 0
	v_mov_b32_e32 v97, 0
	v_mov_b32_e32 v98, 0
	v_mov_b32_e32 v99, 0
	v_mov_b32_e32 v100, 0
	v_mov_b32_e32 v101, 0
	v_mov_b32_e32 v102, 0
	v_mov_b32_e32 v103, 0
	v_mov_b32_e32 v104, 0
	v_mov_b32_e32 v105, 0
	v_mov_b32_e32 v106, 0
	v_mov_b32_e32 v107, 0
	v_mov_b32_e32 v108, 0
	v_mov_b32_e32 v109, 0
	v_mov_b32_e32 v110, 0
	v_mov_b32_e32 v111, 0
	v_mov_b32_e32 v112, 0
	v_mov_b32_e32 v113, 0
	v_mov_b32_e32 v114, 0
	v_mov_b32_e32 v115, 0
	v_mov_b32_e32 v116, 0
	v_mov_b32_e32 v117, 0
	v_mov_b32_e32 v118, 0
	v_mov_b32_e32 v119, 0
	v_mov_b32_e32 v120, 0
	v_mov_b32_e32 v121, 0
	v_mov_b32_e32 v122, 0
	v_mov_b32_e32 v123, 0
	v_mov_b32_e32 v124, 0
	v_mov_b32_e32 v125, 0
	v_mov_b32_e32 v126, 0
	v_mov_b32_e32 v127, 0
	s_mov_b32 s8, 0
	s_waitcnt vmcnt(10)
	ds_write_b128 v241, v[160:163]
	ds_write_b128 v241, v[164:167] offset:4096
	s_waitcnt lgkmcnt(0)
	s_movk_i32 s96, 0x4000
	v_lshl_add_u64 v[166:167], v[188:189], 0, s[96:97]
	global_load_dwordx4 v[160:163], v[166:167], off offset:-2048
	global_load_dwordx4 v[164:167], v[166:167], off offset:2048
	s_barrier
.Lg16_down_k:
	ds_read_b128 v[196:199], v246 offset:0
	ds_read_b128 v[200:203], v246 offset:1024
	ds_read_b128 v[204:207], v246 offset:2048
	ds_read_b128 v[242:245], v246 offset:3072
	s_add_i32 s9, s8, 2
	s_min_u32 s10, s9, 86
	s_lshl_b32 s96, s10, 11
	v_lshl_add_u64 v[248:249], v[184:185], 0, s[96:97]
	v_lshl_add_u64 v[250:251], v[186:187], 0, s[96:97]
	s_waitcnt vmcnt(6) lgkmcnt(3)
	v_mfma_f32_16x16x32_bf16 v[112:115], v[128:131], v[196:199], v[112:115]
	v_mfma_f32_16x16x32_bf16 v[120:123], v[132:135], v[196:199], v[120:123]
	v_mfma_f32_16x16x32_bf16 v[48:51], v[136:139], v[196:199], v[48:51]
	v_mfma_f32_16x16x32_bf16 v[56:59], v[140:143], v[196:199], v[56:59]
	ds_read_b128 v[196:199], v246 offset:4096
	s_waitcnt lgkmcnt(3)
	v_mfma_f32_16x16x32_bf16 v[116:119], v[128:131], v[200:203], v[116:119]
	v_mfma_f32_16x16x32_bf16 v[124:127], v[132:135], v[200:203], v[124:127]
	v_mfma_f32_16x16x32_bf16 v[52:55], v[136:139], v[200:203], v[52:55]
	v_mfma_f32_16x16x32_bf16 v[60:63], v[140:143], v[200:203], v[60:63]
	ds_read_b128 v[200:203], v246 offset:5120
	s_waitcnt lgkmcnt(3)
	v_mfma_f32_16x16x32_bf16 v[96:99], v[128:131], v[204:207], v[96:99]
	v_mfma_f32_16x16x32_bf16 v[104:107], v[132:135], v[204:207], v[104:107]
	v_mfma_f32_16x16x32_bf16 v[32:35], v[136:139], v[204:207], v[32:35]
	v_mfma_f32_16x16x32_bf16 v[40:43], v[140:143], v[204:207], v[40:43]
	ds_read_b128 v[204:207], v246 offset:6144
	s_waitcnt lgkmcnt(3)
	v_mfma_f32_16x16x32_bf16 v[100:103], v[128:131], v[242:245], v[100:103]
	v_mfma_f32_16x16x32_bf16 v[108:111], v[132:135], v[242:245], v[108:111]
	v_mfma_f32_16x16x32_bf16 v[36:39], v[136:139], v[242:245], v[36:39]
	v_mfma_f32_16x16x32_bf16 v[44:47], v[140:143], v[242:245], v[44:47]
	ds_read_b128 v[242:245], v246 offset:7168
	ds_write_b128 v241, v[168:171] offset:8192
	ds_write_b128 v241, v[172:175] offset:12288
	s_add_i32 s9, s8, 3
	s_min_u32 s10, s9, 87
	s_lshl_b32 s96, s10, 13
	v_lshl_add_u64 v[174:175], v[188:189], 0, s[96:97]
	global_load_dwordx4 v[168:171], v[174:175], off offset:-2048
	global_load_dwordx4 v[172:175], v[174:175], off offset:2048
	s_waitcnt lgkmcnt(5)
	v_mfma_f32_16x16x32_bf16 v[80:83], v[128:131], v[196:199], v[80:83]
	v_mfma_f32_16x16x32_bf16 v[88:91], v[132:135], v[196:199], v[88:91]
	v_mfma_f32_16x16x32_bf16 v[16:19], v[136:139], v[196:199], v[16:19]
	v_mfma_f32_16x16x32_bf16 v[24:27], v[140:143], v[196:199], v[24:27]
	s_waitcnt lgkmcnt(4)
	v_mfma_f32_16x16x32_bf16 v[84:87], v[128:131], v[200:203], v[84:87]
	v_mfma_f32_16x16x32_bf16 v[92:95], v[132:135], v[200:203], v[92:95]
	v_mfma_f32_16x16x32_bf16 v[20:23], v[136:139], v[200:203], v[20:23]
	v_mfma_f32_16x16x32_bf16 v[28:31], v[140:143], v[200:203], v[28:31]
	s_waitcnt lgkmcnt(3)
	v_mfma_f32_16x16x32_bf16 v[64:67], v[128:131], v[204:207], v[64:67]
	v_mfma_f32_16x16x32_bf16 v[72:75], v[132:135], v[204:207], v[72:75]
	v_mfma_f32_16x16x32_bf16 v[0:3], v[136:139], v[204:207], v[0:3]
	v_mfma_f32_16x16x32_bf16 v[8:11], v[140:143], v[204:207], v[8:11]
	s_waitcnt lgkmcnt(2)
	v_mfma_f32_16x16x32_bf16 v[68:71], v[128:131], v[242:245], v[68:71]
	v_mfma_f32_16x16x32_bf16 v[76:79], v[132:135], v[242:245], v[76:79]
	v_mfma_f32_16x16x32_bf16 v[4:7], v[136:139], v[242:245], v[4:7]
	v_mfma_f32_16x16x32_bf16 v[12:15], v[140:143], v[242:245], v[12:15]
	global_load_dwordx4 v[128:131], v[248:249], off
	global_load_dwordx4 v[132:135], v[248:249], off offset:256
	global_load_dwordx4 v[136:139], v[250:251], off
	global_load_dwordx4 v[140:143], v[250:251], off offset:256
	s_waitcnt lgkmcnt(0)
	s_barrier
	ds_read_b128 v[196:199], v246 offset:8192
	ds_read_b128 v[200:203], v246 offset:9216
	ds_read_b128 v[204:207], v246 offset:10240
	ds_read_b128 v[242:245], v246 offset:11264
	s_add_i32 s9, s8, 3
	s_min_u32 s10, s9, 87
	s_lshl_b32 s96, s10, 11
	v_lshl_add_u64 v[248:249], v[184:185], 0, s[96:97]
	v_lshl_add_u64 v[250:251], v[186:187], 0, s[96:97]
	s_waitcnt vmcnt(6) lgkmcnt(3)
	v_mfma_f32_16x16x32_bf16 v[112:115], v[144:147], v[196:199], v[112:115]
	v_mfma_f32_16x16x32_bf16 v[120:123], v[148:151], v[196:199], v[120:123]
	v_mfma_f32_16x16x32_bf16 v[48:51], v[152:155], v[196:199], v[48:51]
	v_mfma_f32_16x16x32_bf16 v[56:59], v[156:159], v[196:199], v[56:59]
	ds_read_b128 v[196:199], v246 offset:12288
	s_waitcnt lgkmcnt(3)
	v_mfma_f32_16x16x32_bf16 v[116:119], v[144:147], v[200:203], v[116:119]
	v_mfma_f32_16x16x32_bf16 v[124:127], v[148:151], v[200:203], v[124:127]
	v_mfma_f32_16x16x32_bf16 v[52:55], v[152:155], v[200:203], v[52:55]
	v_mfma_f32_16x16x32_bf16 v[60:63], v[156:159], v[200:203], v[60:63]
	ds_read_b128 v[200:203], v246 offset:13312
	s_waitcnt lgkmcnt(3)
	v_mfma_f32_16x16x32_bf16 v[96:99], v[144:147], v[204:207], v[96:99]
	v_mfma_f32_16x16x32_bf16 v[104:107], v[148:151], v[204:207], v[104:107]
	v_mfma_f32_16x16x32_bf16 v[32:35], v[152:155], v[204:207], v[32:35]
	v_mfma_f32_16x16x32_bf16 v[40:43], v[156:159], v[204:207], v[40:43]
	ds_read_b128 v[204:207], v246 offset:14336
	s_waitcnt lgkmcnt(3)
	v_mfma_f32_16x16x32_bf16 v[100:103], v[144:147], v[242:245], v[100:103]
	v_mfma_f32_16x16x32_bf16 v[108:111], v[148:151], v[242:245], v[108:111]
	v_mfma_f32_16x16x32_bf16 v[36:39], v[152:155], v[242:245], v[36:39]
	v_mfma_f32_16x16x32_bf16 v[44:47], v[156:159], v[242:245], v[44:47]
	ds_read_b128 v[242:245], v246 offset:15360
	ds_write_b128 v241, v[160:163] offset:0
	ds_write_b128 v241, v[164:167] offset:4096
	s_add_i32 s9, s8, 4
	s_min_u32 s10, s9, 86
	s_lshl_b32 s96, s10, 13
	v_lshl_add_u64 v[166:167], v[188:189], 0, s[96:97]
	global_load_dwordx4 v[160:163], v[166:167], off offset:-2048
	global_load_dwordx4 v[164:167], v[166:167], off offset:2048
	s_waitcnt lgkmcnt(5)
	v_mfma_f32_16x16x32_bf16 v[80:83], v[144:147], v[196:199], v[80:83]
	v_mfma_f32_16x16x32_bf16 v[88:91], v[148:151], v[196:199], v[88:91]
	v_mfma_f32_16x16x32_bf16 v[16:19], v[152:155], v[196:199], v[16:19]
	v_mfma_f32_16x16x32_bf16 v[24:27], v[156:159], v[196:199], v[24:27]
	s_waitcnt lgkmcnt(4)
	v_mfma_f32_16x16x32_bf16 v[84:87], v[144:147], v[200:203], v[84:87]
	v_mfma_f32_16x16x32_bf16 v[92:95], v[148:151], v[200:203], v[92:95]
	v_mfma_f32_16x16x32_bf16 v[20:23], v[152:155], v[200:203], v[20:23]
	v_mfma_f32_16x16x32_bf16 v[28:31], v[156:159], v[200:203], v[28:31]
	s_waitcnt lgkmcnt(3)
	v_mfma_f32_16x16x32_bf16 v[64:67], v[144:147], v[204:207], v[64:67]
	v_mfma_f32_16x16x32_bf16 v[72:75], v[148:151], v[204:207], v[72:75]
	v_mfma_f32_16x16x32_bf16 v[0:3], v[152:155], v[204:207], v[0:3]
	v_mfma_f32_16x16x32_bf16 v[8:11], v[156:159], v[204:207], v[8:11]
	s_waitcnt lgkmcnt(2)
	v_mfma_f32_16x16x32_bf16 v[68:71], v[144:147], v[242:245], v[68:71]
	v_mfma_f32_16x16x32_bf16 v[76:79], v[148:151], v[242:245], v[76:79]
	v_mfma_f32_16x16x32_bf16 v[4:7], v[152:155], v[242:245], v[4:7]
	v_mfma_f32_16x16x32_bf16 v[12:15], v[156:159], v[242:245], v[12:15]
	global_load_dwordx4 v[144:147], v[248:249], off
	global_load_dwordx4 v[148:151], v[248:249], off offset:256
	global_load_dwordx4 v[152:155], v[250:251], off
	global_load_dwordx4 v[156:159], v[250:251], off offset:256
	s_add_i32 s8, s8, 2
	s_cmp_lt_u32 s8, 88
	s_waitcnt lgkmcnt(0)
	s_barrier
	s_cbranch_scc1 .Lg16_down_k
	s_nop 7
	v_permlane16_swap_b32_e32 v112, v116
	v_permlane16_swap_b32_e32 v113, v117
	v_permlane16_swap_b32_e32 v114, v118
	v_permlane16_swap_b32_e32 v115, v119
	v_permlane16_swap_b32_e32 v120, v124
	v_permlane16_swap_b32_e32 v121, v125
	v_permlane16_swap_b32_e32 v122, v126
	v_permlane16_swap_b32_e32 v123, v127
	v_permlane16_swap_b32_e32 v96, v100
	v_permlane16_swap_b32_e32 v97, v101
	v_permlane16_swap_b32_e32 v98, v102
	v_permlane16_swap_b32_e32 v99, v103
	v_permlane16_swap_b32_e32 v104, v108
	v_permlane16_swap_b32_e32 v105, v109
	v_permlane16_swap_b32_e32 v106, v110
	v_permlane16_swap_b32_e32 v107, v111
	v_permlane16_swap_b32_e32 v80, v84
	v_permlane16_swap_b32_e32 v81, v85
	v_permlane16_swap_b32_e32 v82, v86
	v_permlane16_swap_b32_e32 v83, v87
	v_permlane16_swap_b32_e32 v88, v92
	v_permlane16_swap_b32_e32 v89, v93
	v_permlane16_swap_b32_e32 v90, v94
	v_permlane16_swap_b32_e32 v91, v95
	v_permlane16_swap_b32_e32 v64, v68
	v_permlane16_swap_b32_e32 v65, v69
	v_permlane16_swap_b32_e32 v66, v70
	v_permlane16_swap_b32_e32 v67, v71
	v_permlane16_swap_b32_e32 v72, v76
	v_permlane16_swap_b32_e32 v73, v77
	v_permlane16_swap_b32_e32 v74, v78
	v_permlane16_swap_b32_e32 v75, v79
	v_permlane16_swap_b32_e32 v48, v52
	v_permlane16_swap_b32_e32 v49, v53
	v_permlane16_swap_b32_e32 v50, v54
	v_permlane16_swap_b32_e32 v51, v55
	v_permlane16_swap_b32_e32 v56, v60
	v_permlane16_swap_b32_e32 v57, v61
	v_permlane16_swap_b32_e32 v58, v62
	v_permlane16_swap_b32_e32 v59, v63
	v_permlane16_swap_b32_e32 v32, v36
	v_permlane16_swap_b32_e32 v33, v37
	v_permlane16_swap_b32_e32 v34, v38
	v_permlane16_swap_b32_e32 v35, v39
	v_permlane16_swap_b32_e32 v40, v44
	v_permlane16_swap_b32_e32 v41, v45
	v_permlane16_swap_b32_e32 v42, v46
	v_permlane16_swap_b32_e32 v43, v47
	v_permlane16_swap_b32_e32 v16, v20
	v_permlane16_swap_b32_e32 v17, v21
	v_permlane16_swap_b32_e32 v18, v22
	v_permlane16_swap_b32_e32 v19, v23
	v_permlane16_swap_b32_e32 v24, v28
	v_permlane16_swap_b32_e32 v25, v29
	v_permlane16_swap_b32_e32 v26, v30
	v_permlane16_swap_b32_e32 v27, v31
	v_permlane16_swap_b32_e32 v0, v4
	v_permlane16_swap_b32_e32 v1, v5
	v_permlane16_swap_b32_e32 v2, v6
	v_permlane16_swap_b32_e32 v3, v7
	v_permlane16_swap_b32_e32 v8, v12
	v_permlane16_swap_b32_e32 v9, v13
	v_permlane16_swap_b32_e32 v10, v14
	v_permlane16_swap_b32_e32 v11, v15
	v_permlane32_swap_b32_e32 v112, v116
	v_permlane32_swap_b32_e32 v113, v117
	v_permlane32_swap_b32_e32 v114, v118
	v_permlane32_swap_b32_e32 v115, v119
	v_permlane32_swap_b32_e32 v120, v124
	v_permlane32_swap_b32_e32 v121, v125
	v_permlane32_swap_b32_e32 v122, v126
	v_permlane32_swap_b32_e32 v123, v127
	v_permlane32_swap_b32_e32 v96, v100
	v_permlane32_swap_b32_e32 v97, v101
	v_permlane32_swap_b32_e32 v98, v102
	v_permlane32_swap_b32_e32 v99, v103
	v_permlane32_swap_b32_e32 v104, v108
	v_permlane32_swap_b32_e32 v105, v109
	v_permlane32_swap_b32_e32 v106, v110
	v_permlane32_swap_b32_e32 v107, v111
	v_permlane32_swap_b32_e32 v80, v84
	v_permlane32_swap_b32_e32 v81, v85
	v_permlane32_swap_b32_e32 v82, v86
	v_permlane32_swap_b32_e32 v83, v87
	v_permlane32_swap_b32_e32 v88, v92
	v_permlane32_swap_b32_e32 v89, v93
	v_permlane32_swap_b32_e32 v90, v94
	v_permlane32_swap_b32_e32 v91, v95
	v_permlane32_swap_b32_e32 v64, v68
	v_permlane32_swap_b32_e32 v65, v69
	v_permlane32_swap_b32_e32 v66, v70
	v_permlane32_swap_b32_e32 v67, v71
	v_permlane32_swap_b32_e32 v72, v76
	v_permlane32_swap_b32_e32 v73, v77
	v_permlane32_swap_b32_e32 v74, v78
	v_permlane32_swap_b32_e32 v75, v79
	v_permlane32_swap_b32_e32 v48, v52
	v_permlane32_swap_b32_e32 v49, v53
	v_permlane32_swap_b32_e32 v50, v54
	v_permlane32_swap_b32_e32 v51, v55
	v_permlane32_swap_b32_e32 v56, v60
	v_permlane32_swap_b32_e32 v57, v61
	v_permlane32_swap_b32_e32 v58, v62
	v_permlane32_swap_b32_e32 v59, v63
	v_permlane32_swap_b32_e32 v32, v36
	v_permlane32_swap_b32_e32 v33, v37
	v_permlane32_swap_b32_e32 v34, v38
	v_permlane32_swap_b32_e32 v35, v39
	v_permlane32_swap_b32_e32 v40, v44
	v_permlane32_swap_b32_e32 v41, v45
	v_permlane32_swap_b32_e32 v42, v46
	v_permlane32_swap_b32_e32 v43, v47
	v_permlane32_swap_b32_e32 v16, v20
	v_permlane32_swap_b32_e32 v17, v21
	v_permlane32_swap_b32_e32 v18, v22
	v_permlane32_swap_b32_e32 v19, v23
	v_permlane32_swap_b32_e32 v24, v28
	v_permlane32_swap_b32_e32 v25, v29
	v_permlane32_swap_b32_e32 v26, v30
	v_permlane32_swap_b32_e32 v27, v31
	v_permlane32_swap_b32_e32 v0, v4
	v_permlane32_swap_b32_e32 v1, v5
	v_permlane32_swap_b32_e32 v2, v6
	v_permlane32_swap_b32_e32 v3, v7
	v_permlane32_swap_b32_e32 v8, v12
	v_permlane32_swap_b32_e32 v9, v13
	v_permlane32_swap_b32_e32 v10, v14
	v_permlane32_swap_b32_e32 v11, v15
	s_waitcnt vmcnt(0)
	s_movk_i32 s8, 0x2400
	s_waitcnt vmcnt(0)
	v_and_b32_e32 v132, 0xffffffc0, v181
	v_mul_lo_u32 v129, v237, s8
	v_lshlrev_b32_e32 v130, 2, v238
	v_lshl_add_u32 v156, s7, 8, v132
	v_mul_u32_u24_e32 v132, 0x110, v183
	v_or_b32_e32 v131, v129, v130
	v_lshlrev_b32_e32 v132, 2, v132
	v_add_u32_e32 v131, v131, v132
	v_add3_u32 v132, v129, v132, v130
	v_readlane_b32 s8, v253, 36
	v_lshlrev_b32_e32 v128, 2, v181
	v_add_u32_e32 v133, 0x800, v131
	v_add_u32_e32 v134, 0x800, v132
	v_lshrrev_b32_e32 v155, 4, v239
	v_readlane_b32 s12, v253, 40
	v_readlane_b32 s13, v253, 41
	v_readlane_b32 s14, v253, 42
	v_readlane_b32 s15, v253, 43
	v_readlane_b32 s16, v253, 44
	v_readlane_b32 s17, v253, 45
	v_readlane_b32 s18, v253, 46
	v_readlane_b32 s19, v253, 47
	v_and_b32_e32 v128, 60, v128
	ds_write2_b32 v131, v112, v113 offset1:68
	ds_write2_b32 v132, v96, v97 offset0:32 offset1:100
	ds_write2_b32 v131, v114, v115 offset0:136 offset1:204
	ds_write2_b32 v132, v98, v99 offset0:168 offset1:236
	ds_write2_b32 v133, v116, v117 offset0:32 offset1:100
	ds_write2_b32 v134, v100, v101 offset0:64 offset1:132
	ds_write2_b32 v133, v118, v119 offset0:168 offset1:236
	v_or_b32_e32 v100, v156, v155
	v_readlane_b32 s20, v253, 48
	v_readlane_b32 s21, v253, 49
	v_readlane_b32 s22, v253, 50
	v_readlane_b32 s23, v253, 51
	s_mov_b64 s[12:13], s[16:17]
	v_lshl_or_b32 v144, v128, 2, v129
	v_lshl_or_b32 v128, s6, 7, v128
	s_movk_i32 s6, 0x110
	v_cmp_gt_i32_e32 vcc, s39, v100
	v_add_u32_e32 v96, 0xffff8000, v100
	v_ashrrev_i32_e32 v97, 31, v100
	s_mov_b64 s[14:15], s[18:19]
	v_mad_u32_u24 v130, v155, s6, v144
	v_cndmask_b32_e32 v97, 0, v97, vcc
	v_cndmask_b32_e32 v96, v96, v100, vcc
	v_mov_b32_e32 v144, s63
	v_mov_b32_e32 v145, s15
	v_mov_b32_e32 v146, s62
	v_mov_b32_e32 v147, s14
	v_min_i32_e32 v100, 0x8000, v100
	v_add_u32_e32 v135, 0xa00, v132
	v_add_u32_e32 v136, 0x1000, v131
	v_add_u32_e32 v137, 0x1000, v132
	v_add_u32_e32 v138, 0x1200, v131
	v_add_u32_e32 v139, 0x1200, v132
	v_add_u32_e32 v140, 0x1800, v131
	v_add_u32_e32 v141, 0x1800, v132
	v_add_u32_e32 v142, 0x1a00, v131
	v_add_u32_e32 v143, 0x1c00, v132
	v_ashrrev_i32_e32 v129, 31, v128
	v_cndmask_b32_e32 v99, v144, v145, vcc
	v_cndmask_b32_e32 v98, v146, v147, vcc
	v_lshlrev_b64 v[96:97], 12, v[96:97]
	v_ashrrev_i32_e32 v100, 12, v100
	ds_write2_b32 v135, v102, v103 offset0:72 offset1:140
	ds_write2_b32 v136, v120, v121 offset0:64 offset1:132
	ds_write2_b32 v137, v104, v105 offset0:96 offset1:164
	ds_write2_b32 v138, v122, v123 offset0:72 offset1:140
	ds_write2_b32 v139, v106, v107 offset0:104 offset1:172
	ds_write2_b32 v140, v124, v125 offset0:96 offset1:164
	ds_write2_b32 v141, v108, v109 offset0:128 offset1:196
	ds_write2_b32 v142, v126, v127 offset0:104 offset1:172
	ds_write2_b32 v143, v110, v111 offset0:8 offset1:76
	v_lshl_add_u64 v[98:99], v[98:99], 0, v[96:97]
	v_lshlrev_b64 v[96:97], 2, v[128:129]
	v_mul_hi_i32_i24_e32 v101, 0x6000, v100
	v_mul_i32_i24_e32 v100, 0x6000, v100
	s_waitcnt lgkmcnt(0)
	v_lshl_add_u64 v[98:99], v[98:99], 0, v[96:97]
	v_lshl_add_u64 v[100:101], s[0:1], 0, v[100:101]
	v_lshl_add_u64 v[100:101], v[100:101], 0, v[96:97]
	ds_read_b128 v[102:105], v130
	global_load_dwordx4 v[106:109], v[98:99], off
	global_load_dwordx4 v[110:113], v[100:101], off
	v_or_b32_e32 v148, 4, v155
	v_or_b32_e32 v149, 8, v155
	v_or_b32_e32 v150, 12, v155
	v_or_b32_e32 v151, 16, v155
	v_or_b32_e32 v152, 20, v155
	v_or_b32_e32 v153, 24, v155
	v_or_b32_e32 v154, 28, v155
	v_or_b32_e32 v157, v156, v154
	v_readlane_b32 s6, v254, 11
	s_add_i32 s2, s2, s6
	s_cmp_lt_i32 s2, s26
	v_readlane_b32 s9, v253, 37
	v_readlane_b32 s10, v253, 38
	v_readlane_b32 s11, v253, 39
	s_mov_b64 s[16:17], s[20:21]
	s_mov_b64 s[18:19], s[22:23]
	s_waitcnt vmcnt(0) lgkmcnt(0)
	v_pk_fma_f32 v[102:103], v[102:103], v[110:111], v[106:107]
	v_pk_fma_f32 v[104:105], v[104:105], v[112:113], v[108:109]
	v_or_b32_e32 v106, v156, v148
	global_store_dwordx4 v[98:99], v[102:105], off
	v_cmp_gt_i32_e32 vcc, s39, v106
	s_nop 0
	v_ashrrev_i32_e32 v102, 31, v106
	v_add_u32_e32 v104, 0xffff8000, v106
	v_cndmask_b32_e32 v103, 0, v102, vcc
	v_cndmask_b32_e32 v102, v104, v106, vcc
	v_cndmask_b32_e32 v105, v144, v145, vcc
	v_cndmask_b32_e32 v104, v146, v147, vcc
	v_lshlrev_b64 v[102:103], 12, v[102:103]
	v_lshl_add_u64 v[102:103], v[104:105], 0, v[102:103]
	v_min_i32_e32 v104, 0x8000, v106
	v_ashrrev_i32_e32 v104, 12, v104
	v_mul_hi_i32_i24_e32 v105, 0x6000, v104
	v_mul_i32_i24_e32 v104, 0x6000, v104
	v_lshl_add_u64 v[102:103], v[102:103], 0, v[96:97]
	v_lshl_add_u64 v[104:105], s[0:1], 0, v[104:105]
	v_lshl_add_u64 v[104:105], v[104:105], 0, v[96:97]
	ds_read_b128 v[106:109], v130 offset:1088
	global_load_dwordx4 v[110:113], v[102:103], off
	global_load_dwordx4 v[114:117], v[104:105], off
	s_waitcnt vmcnt(0) lgkmcnt(0)
	v_pk_fma_f32 v[106:107], v[106:107], v[114:115], v[110:111]
	v_pk_fma_f32 v[108:109], v[108:109], v[116:117], v[112:113]
	v_or_b32_e32 v110, v156, v149
	global_store_dwordx4 v[102:103], v[106:109], off
	v_cmp_gt_i32_e32 vcc, s39, v110
	s_nop 0
	v_ashrrev_i32_e32 v106, 31, v110
	v_add_u32_e32 v108, 0xffff8000, v110
	v_cndmask_b32_e32 v107, 0, v106, vcc
	v_cndmask_b32_e32 v106, v108, v110, vcc
	v_cndmask_b32_e32 v109, v144, v145, vcc
	v_cndmask_b32_e32 v108, v146, v147, vcc
	v_lshlrev_b64 v[106:107], 12, v[106:107]
	v_lshl_add_u64 v[106:107], v[108:109], 0, v[106:107]
	v_min_i32_e32 v108, 0x8000, v110
	v_ashrrev_i32_e32 v108, 12, v108
	v_mul_hi_i32_i24_e32 v109, 0x6000, v108
	v_mul_i32_i24_e32 v108, 0x6000, v108
	v_lshl_add_u64 v[106:107], v[106:107], 0, v[96:97]
	v_lshl_add_u64 v[108:109], s[0:1], 0, v[108:109]
	v_lshl_add_u64 v[108:109], v[108:109], 0, v[96:97]
	ds_read_b128 v[110:113], v130 offset:2176
	global_load_dwordx4 v[114:117], v[106:107], off
	global_load_dwordx4 v[118:121], v[108:109], off
	s_waitcnt vmcnt(0) lgkmcnt(0)
	v_pk_fma_f32 v[110:111], v[110:111], v[118:119], v[114:115]
	v_pk_fma_f32 v[112:113], v[112:113], v[120:121], v[116:117]
	v_or_b32_e32 v114, v156, v150
	global_store_dwordx4 v[106:107], v[110:113], off
	v_cmp_gt_i32_e32 vcc, s39, v114
	s_nop 0
	v_ashrrev_i32_e32 v110, 31, v114
	v_add_u32_e32 v112, 0xffff8000, v114
	v_cndmask_b32_e32 v111, 0, v110, vcc
	v_cndmask_b32_e32 v110, v112, v114, vcc
	v_cndmask_b32_e32 v113, v144, v145, vcc
	v_cndmask_b32_e32 v112, v146, v147, vcc
	v_lshlrev_b64 v[110:111], 12, v[110:111]
	v_lshl_add_u64 v[110:111], v[112:113], 0, v[110:111]
	v_min_i32_e32 v112, 0x8000, v114
	v_ashrrev_i32_e32 v112, 12, v112
	v_mul_hi_i32_i24_e32 v113, 0x6000, v112
	v_mul_i32_i24_e32 v112, 0x6000, v112
	v_lshl_add_u64 v[110:111], v[110:111], 0, v[96:97]
	v_lshl_add_u64 v[112:113], s[0:1], 0, v[112:113]
	v_lshl_add_u64 v[112:113], v[112:113], 0, v[96:97]
	ds_read_b128 v[114:117], v130 offset:3264
	global_load_dwordx4 v[118:121], v[110:111], off
	global_load_dwordx4 v[122:125], v[112:113], off
	s_waitcnt vmcnt(0) lgkmcnt(0)
	v_pk_fma_f32 v[114:115], v[114:115], v[122:123], v[118:119]
	v_pk_fma_f32 v[116:117], v[116:117], v[124:125], v[120:121]
	v_or_b32_e32 v118, v156, v151
	global_store_dwordx4 v[110:111], v[114:117], off
	v_cmp_gt_i32_e32 vcc, s39, v118
	s_nop 0
	v_ashrrev_i32_e32 v114, 31, v118
	v_add_u32_e32 v116, 0xffff8000, v118
	v_cndmask_b32_e32 v115, 0, v114, vcc
	v_cndmask_b32_e32 v114, v116, v118, vcc
	v_cndmask_b32_e32 v117, v144, v145, vcc
	v_cndmask_b32_e32 v116, v146, v147, vcc
	v_lshlrev_b64 v[114:115], 12, v[114:115]
	v_lshl_add_u64 v[114:115], v[116:117], 0, v[114:115]
	v_min_i32_e32 v116, 0x8000, v118
	v_ashrrev_i32_e32 v116, 12, v116
	v_mul_hi_i32_i24_e32 v117, 0x6000, v116
	v_mul_i32_i24_e32 v116, 0x6000, v116
	v_lshl_add_u64 v[114:115], v[114:115], 0, v[96:97]
	v_lshl_add_u64 v[116:117], s[0:1], 0, v[116:117]
	v_lshl_add_u64 v[116:117], v[116:117], 0, v[96:97]
	ds_read_b128 v[118:121], v130 offset:4352
	global_load_dwordx4 v[122:125], v[114:115], off
	global_load_dwordx4 v[126:129], v[116:117], off
	s_waitcnt vmcnt(0) lgkmcnt(0)
	v_pk_fma_f32 v[118:119], v[118:119], v[126:127], v[122:123]
	v_pk_fma_f32 v[120:121], v[120:121], v[128:129], v[124:125]
	v_or_b32_e32 v122, v156, v152
	global_store_dwordx4 v[114:115], v[118:121], off
	v_cmp_gt_i32_e32 vcc, s39, v122
	s_nop 0
	v_ashrrev_i32_e32 v118, 31, v122
	v_add_u32_e32 v120, 0xffff8000, v122
	v_cndmask_b32_e32 v119, 0, v118, vcc
	v_cndmask_b32_e32 v118, v120, v122, vcc
	v_cndmask_b32_e32 v121, v144, v145, vcc
	v_cndmask_b32_e32 v120, v146, v147, vcc
	v_lshlrev_b64 v[118:119], 12, v[118:119]
	v_lshl_add_u64 v[118:119], v[120:121], 0, v[118:119]
	v_min_i32_e32 v120, 0x8000, v122
	v_ashrrev_i32_e32 v120, 12, v120
	v_mul_hi_i32_i24_e32 v121, 0x6000, v120
	v_mul_i32_i24_e32 v120, 0x6000, v120
	v_lshl_add_u64 v[118:119], v[118:119], 0, v[96:97]
	v_lshl_add_u64 v[120:121], s[0:1], 0, v[120:121]
	v_lshl_add_u64 v[120:121], v[120:121], 0, v[96:97]
	ds_read_b128 v[122:125], v130 offset:5440
	global_load_dwordx4 v[126:129], v[118:119], off
	global_load_dwordx4 v[158:161], v[120:121], off
	s_waitcnt vmcnt(0) lgkmcnt(0)
	v_pk_fma_f32 v[122:123], v[122:123], v[158:159], v[126:127]
	v_pk_fma_f32 v[124:125], v[124:125], v[160:161], v[128:129]
	v_or_b32_e32 v126, v156, v153
	global_store_dwordx4 v[118:119], v[122:125], off
	v_cmp_gt_i32_e32 vcc, s39, v126
	s_nop 0
	v_ashrrev_i32_e32 v122, 31, v126
	v_add_u32_e32 v124, 0xffff8000, v126
	v_cndmask_b32_e32 v123, 0, v122, vcc
	v_cndmask_b32_e32 v122, v124, v126, vcc
	v_cndmask_b32_e32 v125, v144, v145, vcc
	v_cndmask_b32_e32 v124, v146, v147, vcc
	v_lshlrev_b64 v[122:123], 12, v[122:123]
	v_lshl_add_u64 v[122:123], v[124:125], 0, v[122:123]
	v_min_i32_e32 v124, 0x8000, v126
	v_ashrrev_i32_e32 v124, 12, v124
	v_mul_hi_i32_i24_e32 v125, 0x6000, v124
	v_mul_i32_i24_e32 v124, 0x6000, v124
	v_lshl_add_u64 v[122:123], v[122:123], 0, v[96:97]
	v_lshl_add_u64 v[124:125], s[0:1], 0, v[124:125]
	v_lshl_add_u64 v[124:125], v[124:125], 0, v[96:97]
	ds_read_b128 v[126:129], v130 offset:6528
	global_load_dwordx4 v[158:161], v[122:123], off
	global_load_dwordx4 v[162:165], v[124:125], off
	v_cmp_gt_i32_e32 vcc, s39, v157
	s_waitcnt vmcnt(0) lgkmcnt(0)
	v_pk_fma_f32 v[126:127], v[126:127], v[162:163], v[158:159]
	v_pk_fma_f32 v[128:129], v[128:129], v[164:165], v[160:161]
	global_store_dwordx4 v[122:123], v[126:129], off
	ds_read_b128 v[158:161], v130 offset:7616
	s_nop 0
	v_ashrrev_i32_e32 v126, 31, v157
	v_add_u32_e32 v128, 0xffff8000, v157
	v_cndmask_b32_e32 v127, 0, v126, vcc
	v_cndmask_b32_e32 v126, v128, v157, vcc
	v_cndmask_b32_e32 v129, v144, v145, vcc
	v_cndmask_b32_e32 v128, v146, v147, vcc
	v_lshlrev_b64 v[126:127], 12, v[126:127]
	v_lshl_add_u64 v[126:127], v[128:129], 0, v[126:127]
	v_min_i32_e32 v128, 0x8000, v157
	v_ashrrev_i32_e32 v128, 12, v128
	v_mul_hi_i32_i24_e32 v129, 0x6000, v128
	v_mul_i32_i24_e32 v128, 0x6000, v128
	v_lshl_add_u64 v[126:127], v[126:127], 0, v[96:97]
	v_lshl_add_u64 v[128:129], s[0:1], 0, v[128:129]
	v_lshl_add_u64 v[128:129], v[128:129], 0, v[96:97]
	global_load_dwordx4 v[162:165], v[126:127], off
	global_load_dwordx4 v[166:169], v[128:129], off
	s_waitcnt vmcnt(0) lgkmcnt(0)
	v_pk_fma_f32 v[158:159], v[158:159], v[166:167], v[162:163]
	v_pk_fma_f32 v[160:161], v[160:161], v[168:169], v[164:165]
	global_store_dwordx4 v[126:127], v[158:161], off
	s_waitcnt lgkmcnt(0)
	ds_write2_b32 v131, v80, v81 offset1:68
	ds_write2_b32 v132, v64, v65 offset0:32 offset1:100
	ds_write2_b32 v131, v82, v83 offset0:136 offset1:204
	ds_write2_b32 v132, v66, v67 offset0:168 offset1:236
	ds_write2_b32 v133, v84, v85 offset0:32 offset1:100
	ds_write2_b32 v134, v68, v69 offset0:64 offset1:132
	ds_write2_b32 v133, v86, v87 offset0:168 offset1:236
	ds_write2_b32 v135, v70, v71 offset0:72 offset1:140
	ds_write2_b32 v136, v88, v89 offset0:64 offset1:132
	ds_write2_b32 v137, v72, v73 offset0:96 offset1:164
	ds_write2_b32 v138, v90, v91 offset0:72 offset1:140
	ds_write2_b32 v139, v74, v75 offset0:104 offset1:172
	ds_write2_b32 v140, v92, v93 offset0:96 offset1:164
	ds_write2_b32 v141, v76, v77 offset0:128 offset1:196
	ds_write2_b32 v142, v94, v95 offset0:104 offset1:172
	ds_write2_b32 v143, v78, v79 offset0:8 offset1:76
	s_waitcnt lgkmcnt(0)
	ds_read_b128 v[64:67], v130
	global_load_dwordx4 v[68:71], v[98:99], off offset:256
	global_load_dwordx4 v[72:75], v[100:101], off offset:256
	s_waitcnt vmcnt(0) lgkmcnt(0)
	v_pk_fma_f32 v[64:65], v[64:65], v[72:73], v[68:69]
	v_pk_fma_f32 v[66:67], v[66:67], v[74:75], v[70:71]
	global_store_dwordx4 v[98:99], v[64:67], off offset:256
	ds_read_b128 v[64:67], v130 offset:1088
	global_load_dwordx4 v[68:71], v[102:103], off offset:256
	global_load_dwordx4 v[72:75], v[104:105], off offset:256
	s_waitcnt vmcnt(0) lgkmcnt(0)
	v_pk_fma_f32 v[64:65], v[64:65], v[72:73], v[68:69]
	v_pk_fma_f32 v[66:67], v[66:67], v[74:75], v[70:71]
	global_store_dwordx4 v[102:103], v[64:67], off offset:256
	ds_read_b128 v[64:67], v130 offset:2176
	global_load_dwordx4 v[68:71], v[106:107], off offset:256
	global_load_dwordx4 v[72:75], v[108:109], off offset:256
	s_waitcnt vmcnt(0) lgkmcnt(0)
	v_pk_fma_f32 v[64:65], v[64:65], v[72:73], v[68:69]
	v_pk_fma_f32 v[66:67], v[66:67], v[74:75], v[70:71]
	global_store_dwordx4 v[106:107], v[64:67], off offset:256
	ds_read_b128 v[64:67], v130 offset:3264
	global_load_dwordx4 v[68:71], v[110:111], off offset:256
	global_load_dwordx4 v[72:75], v[112:113], off offset:256
	s_waitcnt vmcnt(0) lgkmcnt(0)
	v_pk_fma_f32 v[64:65], v[64:65], v[72:73], v[68:69]
	v_pk_fma_f32 v[66:67], v[66:67], v[74:75], v[70:71]
	global_store_dwordx4 v[110:111], v[64:67], off offset:256
	ds_read_b128 v[64:67], v130 offset:4352
	global_load_dwordx4 v[68:71], v[114:115], off offset:256
	global_load_dwordx4 v[72:75], v[116:117], off offset:256
	s_waitcnt vmcnt(0) lgkmcnt(0)
	v_pk_fma_f32 v[64:65], v[64:65], v[72:73], v[68:69]
	v_pk_fma_f32 v[66:67], v[66:67], v[74:75], v[70:71]
	global_store_dwordx4 v[114:115], v[64:67], off offset:256
	ds_read_b128 v[64:67], v130 offset:5440
	global_load_dwordx4 v[68:71], v[118:119], off offset:256
	global_load_dwordx4 v[72:75], v[120:121], off offset:256
	s_waitcnt vmcnt(0) lgkmcnt(0)
	v_pk_fma_f32 v[64:65], v[64:65], v[72:73], v[68:69]
	v_pk_fma_f32 v[66:67], v[66:67], v[74:75], v[70:71]
	global_store_dwordx4 v[118:119], v[64:67], off offset:256
	ds_read_b128 v[64:67], v130 offset:6528
	global_load_dwordx4 v[68:71], v[122:123], off offset:256
	global_load_dwordx4 v[72:75], v[124:125], off offset:256
	s_waitcnt vmcnt(0) lgkmcnt(0)
	v_pk_fma_f32 v[64:65], v[64:65], v[72:73], v[68:69]
	v_pk_fma_f32 v[66:67], v[66:67], v[74:75], v[70:71]
	global_store_dwordx4 v[122:123], v[64:67], off offset:256
	ds_read_b128 v[64:67], v130 offset:7616
	global_load_dwordx4 v[68:71], v[126:127], off offset:256
	global_load_dwordx4 v[72:75], v[128:129], off offset:256
	s_waitcnt vmcnt(0) lgkmcnt(0)
	v_pk_fma_f32 v[64:65], v[64:65], v[72:73], v[68:69]
	v_pk_fma_f32 v[66:67], v[66:67], v[74:75], v[70:71]
	global_store_dwordx4 v[126:127], v[64:67], off offset:256
	s_waitcnt lgkmcnt(0)
	ds_write2_b32 v131, v48, v49 offset1:68
	ds_write2_b32 v132, v32, v33 offset0:32 offset1:100
	ds_write2_b32 v131, v50, v51 offset0:136 offset1:204
	ds_write2_b32 v132, v34, v35 offset0:168 offset1:236
	ds_write2_b32 v133, v52, v53 offset0:32 offset1:100
	ds_write2_b32 v134, v36, v37 offset0:64 offset1:132
	ds_write2_b32 v133, v54, v55 offset0:168 offset1:236
	ds_write2_b32 v135, v38, v39 offset0:72 offset1:140
	ds_write2_b32 v136, v56, v57 offset0:64 offset1:132
	ds_write2_b32 v137, v40, v41 offset0:96 offset1:164
	ds_write2_b32 v138, v58, v59 offset0:72 offset1:140
	ds_write2_b32 v139, v42, v43 offset0:104 offset1:172
	ds_write2_b32 v140, v60, v61 offset0:96 offset1:164
	ds_write2_b32 v141, v44, v45 offset0:128 offset1:196
	ds_write2_b32 v142, v62, v63 offset0:104 offset1:172
	ds_write2_b32 v143, v46, v47 offset0:8 offset1:76
	v_or_b32_e32 v64, 32, v156
	v_or_b32_e32 v36, v64, v155
	v_cmp_gt_i32_e32 vcc, s39, v36
	v_ashrrev_i32_e32 v32, 31, v36
	v_add_u32_e32 v34, 0xffff8000, v36
	v_cndmask_b32_e32 v33, 0, v32, vcc
	v_cndmask_b32_e32 v32, v34, v36, vcc
	v_cndmask_b32_e32 v35, v144, v145, vcc
	v_cndmask_b32_e32 v34, v146, v147, vcc
	v_lshlrev_b64 v[32:33], 12, v[32:33]
	v_lshl_add_u64 v[32:33], v[34:35], 0, v[32:33]
	v_min_i32_e32 v34, 0x8000, v36
	v_ashrrev_i32_e32 v34, 12, v34
	v_mul_hi_i32_i24_e32 v35, 0x6000, v34
	v_mul_i32_i24_e32 v34, 0x6000, v34
	s_waitcnt lgkmcnt(0)
	v_lshl_add_u64 v[32:33], v[32:33], 0, v[96:97]
	v_lshl_add_u64 v[34:35], s[0:1], 0, v[34:35]
	v_lshl_add_u64 v[34:35], v[34:35], 0, v[96:97]
	ds_read_b128 v[36:39], v130
	global_load_dwordx4 v[40:43], v[32:33], off
	global_load_dwordx4 v[44:47], v[34:35], off
	s_waitcnt vmcnt(0) lgkmcnt(0)
	v_pk_fma_f32 v[36:37], v[36:37], v[44:45], v[40:41]
	v_pk_fma_f32 v[38:39], v[38:39], v[46:47], v[42:43]
	v_or_b32_e32 v40, v64, v148
	global_store_dwordx4 v[32:33], v[36:39], off
	v_cmp_gt_i32_e32 vcc, s39, v40
	s_nop 0
	v_ashrrev_i32_e32 v36, 31, v40
	v_add_u32_e32 v38, 0xffff8000, v40
	v_cndmask_b32_e32 v37, 0, v36, vcc
	v_cndmask_b32_e32 v36, v38, v40, vcc
	v_cndmask_b32_e32 v39, v144, v145, vcc
	v_cndmask_b32_e32 v38, v146, v147, vcc
	v_lshlrev_b64 v[36:37], 12, v[36:37]
	v_lshl_add_u64 v[36:37], v[38:39], 0, v[36:37]
	v_min_i32_e32 v38, 0x8000, v40
	v_ashrrev_i32_e32 v38, 12, v38
	v_mul_hi_i32_i24_e32 v39, 0x6000, v38
	v_mul_i32_i24_e32 v38, 0x6000, v38
	v_lshl_add_u64 v[36:37], v[36:37], 0, v[96:97]
	v_lshl_add_u64 v[38:39], s[0:1], 0, v[38:39]
	v_lshl_add_u64 v[38:39], v[38:39], 0, v[96:97]
	ds_read_b128 v[40:43], v130 offset:1088
	global_load_dwordx4 v[44:47], v[36:37], off
	global_load_dwordx4 v[48:51], v[38:39], off
	s_waitcnt vmcnt(0) lgkmcnt(0)
	v_pk_fma_f32 v[40:41], v[40:41], v[48:49], v[44:45]
	v_pk_fma_f32 v[42:43], v[42:43], v[50:51], v[46:47]
	v_or_b32_e32 v44, v64, v149
	global_store_dwordx4 v[36:37], v[40:43], off
	v_cmp_gt_i32_e32 vcc, s39, v44
	s_nop 0
	v_ashrrev_i32_e32 v40, 31, v44
	v_add_u32_e32 v42, 0xffff8000, v44
	v_cndmask_b32_e32 v41, 0, v40, vcc
	v_cndmask_b32_e32 v40, v42, v44, vcc
	v_cndmask_b32_e32 v43, v144, v145, vcc
	v_cndmask_b32_e32 v42, v146, v147, vcc
	v_lshlrev_b64 v[40:41], 12, v[40:41]
	v_lshl_add_u64 v[40:41], v[42:43], 0, v[40:41]
	v_min_i32_e32 v42, 0x8000, v44
	v_ashrrev_i32_e32 v42, 12, v42
	v_mul_hi_i32_i24_e32 v43, 0x6000, v42
	v_mul_i32_i24_e32 v42, 0x6000, v42
	v_lshl_add_u64 v[40:41], v[40:41], 0, v[96:97]
	v_lshl_add_u64 v[42:43], s[0:1], 0, v[42:43]
	v_lshl_add_u64 v[42:43], v[42:43], 0, v[96:97]
	ds_read_b128 v[44:47], v130 offset:2176
	global_load_dwordx4 v[48:51], v[40:41], off
	global_load_dwordx4 v[52:55], v[42:43], off
	s_waitcnt vmcnt(0) lgkmcnt(0)
	v_pk_fma_f32 v[44:45], v[44:45], v[52:53], v[48:49]
	v_pk_fma_f32 v[46:47], v[46:47], v[54:55], v[50:51]
	v_or_b32_e32 v48, v64, v150
	global_store_dwordx4 v[40:41], v[44:47], off
	v_cmp_gt_i32_e32 vcc, s39, v48
	s_nop 0
	v_ashrrev_i32_e32 v44, 31, v48
	v_add_u32_e32 v46, 0xffff8000, v48
	v_cndmask_b32_e32 v45, 0, v44, vcc
	v_cndmask_b32_e32 v44, v46, v48, vcc
	v_cndmask_b32_e32 v47, v144, v145, vcc
	v_cndmask_b32_e32 v46, v146, v147, vcc
	v_lshlrev_b64 v[44:45], 12, v[44:45]
	v_lshl_add_u64 v[44:45], v[46:47], 0, v[44:45]
	v_min_i32_e32 v46, 0x8000, v48
	v_ashrrev_i32_e32 v46, 12, v46
	v_mul_hi_i32_i24_e32 v47, 0x6000, v46
	v_mul_i32_i24_e32 v46, 0x6000, v46
	v_lshl_add_u64 v[44:45], v[44:45], 0, v[96:97]
	v_lshl_add_u64 v[46:47], s[0:1], 0, v[46:47]
	v_lshl_add_u64 v[46:47], v[46:47], 0, v[96:97]
	ds_read_b128 v[48:51], v130 offset:3264
	global_load_dwordx4 v[52:55], v[44:45], off
	global_load_dwordx4 v[56:59], v[46:47], off
	s_waitcnt vmcnt(0) lgkmcnt(0)
	v_pk_fma_f32 v[48:49], v[48:49], v[56:57], v[52:53]
	v_pk_fma_f32 v[50:51], v[50:51], v[58:59], v[54:55]
	v_or_b32_e32 v52, v64, v151
	global_store_dwordx4 v[44:45], v[48:51], off
	v_cmp_gt_i32_e32 vcc, s39, v52
	s_nop 0
	v_ashrrev_i32_e32 v48, 31, v52
	v_add_u32_e32 v50, 0xffff8000, v52
	v_cndmask_b32_e32 v49, 0, v48, vcc
	v_cndmask_b32_e32 v48, v50, v52, vcc
	v_cndmask_b32_e32 v51, v144, v145, vcc
	v_cndmask_b32_e32 v50, v146, v147, vcc
	v_lshlrev_b64 v[48:49], 12, v[48:49]
	v_lshl_add_u64 v[48:49], v[50:51], 0, v[48:49]
	v_min_i32_e32 v50, 0x8000, v52
	v_ashrrev_i32_e32 v50, 12, v50
	v_mul_hi_i32_i24_e32 v51, 0x6000, v50
	v_mul_i32_i24_e32 v50, 0x6000, v50
	v_lshl_add_u64 v[48:49], v[48:49], 0, v[96:97]
	v_lshl_add_u64 v[50:51], s[0:1], 0, v[50:51]
	v_lshl_add_u64 v[50:51], v[50:51], 0, v[96:97]
	ds_read_b128 v[52:55], v130 offset:4352
	global_load_dwordx4 v[56:59], v[48:49], off
	global_load_dwordx4 v[60:63], v[50:51], off
	s_waitcnt vmcnt(0) lgkmcnt(0)
	v_pk_fma_f32 v[52:53], v[52:53], v[60:61], v[56:57]
	v_pk_fma_f32 v[54:55], v[54:55], v[62:63], v[58:59]
	v_or_b32_e32 v56, v64, v152
	global_store_dwordx4 v[48:49], v[52:55], off
	v_cmp_gt_i32_e32 vcc, s39, v56
	s_nop 0
	v_ashrrev_i32_e32 v52, 31, v56
	v_add_u32_e32 v54, 0xffff8000, v56
	v_cndmask_b32_e32 v53, 0, v52, vcc
	v_cndmask_b32_e32 v52, v54, v56, vcc
	v_cndmask_b32_e32 v55, v144, v145, vcc
	v_cndmask_b32_e32 v54, v146, v147, vcc
	v_lshlrev_b64 v[52:53], 12, v[52:53]
	v_lshl_add_u64 v[52:53], v[54:55], 0, v[52:53]
	v_min_i32_e32 v54, 0x8000, v56
	v_ashrrev_i32_e32 v54, 12, v54
	v_mul_hi_i32_i24_e32 v55, 0x6000, v54
	v_mul_i32_i24_e32 v54, 0x6000, v54
	v_lshl_add_u64 v[52:53], v[52:53], 0, v[96:97]
	v_lshl_add_u64 v[54:55], s[0:1], 0, v[54:55]
	v_lshl_add_u64 v[54:55], v[54:55], 0, v[96:97]
	ds_read_b128 v[56:59], v130 offset:5440
	global_load_dwordx4 v[60:63], v[52:53], off
	global_load_dwordx4 v[66:69], v[54:55], off
	s_waitcnt vmcnt(0) lgkmcnt(0)
	v_pk_fma_f32 v[56:57], v[56:57], v[66:67], v[60:61]
	v_pk_fma_f32 v[58:59], v[58:59], v[68:69], v[62:63]
	v_or_b32_e32 v60, v64, v153
	global_store_dwordx4 v[52:53], v[56:59], off
	v_cmp_gt_i32_e32 vcc, s39, v60
	v_or_b32_e32 v64, v64, v154
	v_ashrrev_i32_e32 v56, 31, v60
	v_add_u32_e32 v58, 0xffff8000, v60
	v_cndmask_b32_e32 v57, 0, v56, vcc
	v_cndmask_b32_e32 v56, v58, v60, vcc
	v_cndmask_b32_e32 v59, v144, v145, vcc
	v_cndmask_b32_e32 v58, v146, v147, vcc
	v_lshlrev_b64 v[56:57], 12, v[56:57]
	v_lshl_add_u64 v[56:57], v[58:59], 0, v[56:57]
	v_min_i32_e32 v58, 0x8000, v60
	v_ashrrev_i32_e32 v58, 12, v58
	v_mul_hi_i32_i24_e32 v59, 0x6000, v58
	v_mul_i32_i24_e32 v58, 0x6000, v58
	v_lshl_add_u64 v[56:57], v[56:57], 0, v[96:97]
	v_lshl_add_u64 v[58:59], s[0:1], 0, v[58:59]
	v_lshl_add_u64 v[58:59], v[58:59], 0, v[96:97]
	ds_read_b128 v[60:63], v130 offset:6528
	global_load_dwordx4 v[66:69], v[56:57], off
	global_load_dwordx4 v[70:73], v[58:59], off
	v_cmp_gt_i32_e32 vcc, s39, v64
	s_waitcnt vmcnt(0) lgkmcnt(0)
	v_pk_fma_f32 v[60:61], v[60:61], v[70:71], v[66:67]
	v_pk_fma_f32 v[62:63], v[62:63], v[72:73], v[68:69]
	global_store_dwordx4 v[56:57], v[60:63], off
	s_nop 1
	v_ashrrev_i32_e32 v60, 31, v64
	v_add_u32_e32 v62, 0xffff8000, v64
	v_cndmask_b32_e32 v61, 0, v60, vcc
	v_cndmask_b32_e32 v60, v62, v64, vcc
	v_cndmask_b32_e32 v63, v144, v145, vcc
	v_cndmask_b32_e32 v62, v146, v147, vcc
	v_lshlrev_b64 v[60:61], 12, v[60:61]
	v_lshl_add_u64 v[60:61], v[62:63], 0, v[60:61]
	v_min_i32_e32 v62, 0x8000, v64
	v_ashrrev_i32_e32 v62, 12, v62
	v_mul_hi_i32_i24_e32 v63, 0x6000, v62
	v_mul_i32_i24_e32 v62, 0x6000, v62
	v_lshl_add_u64 v[60:61], v[60:61], 0, v[96:97]
	v_lshl_add_u64 v[62:63], s[0:1], 0, v[62:63]
	v_lshl_add_u64 v[62:63], v[62:63], 0, v[96:97]
	ds_read_b128 v[64:67], v130 offset:7616
	global_load_dwordx4 v[68:71], v[60:61], off
	global_load_dwordx4 v[72:75], v[62:63], off
	s_waitcnt vmcnt(0) lgkmcnt(0)
	v_pk_fma_f32 v[64:65], v[64:65], v[72:73], v[68:69]
	v_pk_fma_f32 v[66:67], v[66:67], v[74:75], v[70:71]
	global_store_dwordx4 v[60:61], v[64:67], off
	s_waitcnt lgkmcnt(0)
	ds_write2_b32 v131, v16, v17 offset1:68
	ds_write2_b32 v132, v0, v1 offset0:32 offset1:100
	ds_write2_b32 v131, v18, v19 offset0:136 offset1:204
	ds_write2_b32 v132, v2, v3 offset0:168 offset1:236
	ds_write2_b32 v133, v20, v21 offset0:32 offset1:100
	ds_write2_b32 v134, v4, v5 offset0:64 offset1:132
	ds_write2_b32 v133, v22, v23 offset0:168 offset1:236
	ds_write2_b32 v135, v6, v7 offset0:72 offset1:140
	ds_write2_b32 v136, v24, v25 offset0:64 offset1:132
	ds_write2_b32 v137, v8, v9 offset0:96 offset1:164
	ds_write2_b32 v138, v26, v27 offset0:72 offset1:140
	ds_write2_b32 v139, v10, v11 offset0:104 offset1:172
	ds_write2_b32 v140, v28, v29 offset0:96 offset1:164
	ds_write2_b32 v141, v12, v13 offset0:128 offset1:196
	ds_write2_b32 v142, v30, v31 offset0:104 offset1:172
	ds_write2_b32 v143, v14, v15 offset0:8 offset1:76
	s_waitcnt lgkmcnt(0)
	ds_read_b128 v[0:3], v130
	global_load_dwordx4 v[4:7], v[32:33], off offset:256
	global_load_dwordx4 v[8:11], v[34:35], off offset:256
	s_waitcnt vmcnt(0) lgkmcnt(0)
	v_pk_fma_f32 v[0:1], v[0:1], v[8:9], v[4:5]
	v_pk_fma_f32 v[2:3], v[2:3], v[10:11], v[6:7]
	global_store_dwordx4 v[32:33], v[0:3], off offset:256
	ds_read_b128 v[0:3], v130 offset:1088
	global_load_dwordx4 v[4:7], v[36:37], off offset:256
	global_load_dwordx4 v[8:11], v[38:39], off offset:256
	s_waitcnt vmcnt(0) lgkmcnt(0)
	v_pk_fma_f32 v[0:1], v[0:1], v[8:9], v[4:5]
	v_pk_fma_f32 v[2:3], v[2:3], v[10:11], v[6:7]
	global_store_dwordx4 v[36:37], v[0:3], off offset:256
	ds_read_b128 v[0:3], v130 offset:2176
	global_load_dwordx4 v[4:7], v[40:41], off offset:256
	global_load_dwordx4 v[8:11], v[42:43], off offset:256
	s_waitcnt vmcnt(0) lgkmcnt(0)
	v_pk_fma_f32 v[0:1], v[0:1], v[8:9], v[4:5]
	v_pk_fma_f32 v[2:3], v[2:3], v[10:11], v[6:7]
	global_store_dwordx4 v[40:41], v[0:3], off offset:256
	ds_read_b128 v[0:3], v130 offset:3264
	global_load_dwordx4 v[4:7], v[44:45], off offset:256
	global_load_dwordx4 v[8:11], v[46:47], off offset:256
	s_waitcnt vmcnt(0) lgkmcnt(0)
	v_pk_fma_f32 v[0:1], v[0:1], v[8:9], v[4:5]
	v_pk_fma_f32 v[2:3], v[2:3], v[10:11], v[6:7]
	global_store_dwordx4 v[44:45], v[0:3], off offset:256
	ds_read_b128 v[0:3], v130 offset:4352
	global_load_dwordx4 v[4:7], v[48:49], off offset:256
	global_load_dwordx4 v[8:11], v[50:51], off offset:256
	s_waitcnt vmcnt(0) lgkmcnt(0)
	v_pk_fma_f32 v[0:1], v[0:1], v[8:9], v[4:5]
	v_pk_fma_f32 v[2:3], v[2:3], v[10:11], v[6:7]
	global_store_dwordx4 v[48:49], v[0:3], off offset:256
	ds_read_b128 v[0:3], v130 offset:5440
	global_load_dwordx4 v[4:7], v[52:53], off offset:256
	global_load_dwordx4 v[8:11], v[54:55], off offset:256
	s_waitcnt vmcnt(0) lgkmcnt(0)
	v_pk_fma_f32 v[0:1], v[0:1], v[8:9], v[4:5]
	v_pk_fma_f32 v[2:3], v[2:3], v[10:11], v[6:7]
	global_store_dwordx4 v[52:53], v[0:3], off offset:256
	ds_read_b128 v[0:3], v130 offset:6528
	global_load_dwordx4 v[4:7], v[56:57], off offset:256
	global_load_dwordx4 v[8:11], v[58:59], off offset:256
	s_waitcnt vmcnt(0) lgkmcnt(0)
	v_pk_fma_f32 v[0:1], v[0:1], v[8:9], v[4:5]
	v_pk_fma_f32 v[2:3], v[2:3], v[10:11], v[6:7]
	global_store_dwordx4 v[56:57], v[0:3], off offset:256
	ds_read_b128 v[0:3], v130 offset:7616
	global_load_dwordx4 v[4:7], v[60:61], off offset:256
	global_load_dwordx4 v[8:11], v[62:63], off offset:256
	s_waitcnt vmcnt(0) lgkmcnt(0)
	v_pk_fma_f32 v[0:1], v[0:1], v[8:9], v[4:5]
	v_pk_fma_f32 v[2:3], v[2:3], v[10:11], v[6:7]
	global_store_dwordx4 v[60:61], v[0:3], off offset:256
	s_waitcnt lgkmcnt(0)
	s_barrier
	s_cbranch_scc1 .LBB0_1086
